# GEMM EpiStoreN epilogue (6 instances): the 8 per-row rss loads issued together with counted waits instead of load/vmcnt(0)/rsqrt one at a time
# speedup vs baseline: 1.0057x; 1.0057x over previous
; DI unsigned cvtpk(float lo, float hi) { f32x2 v = {lo, hi}; bf16x2_t b = __builtin_convertvector(v, bf16x2_t); return __builtin_bit_cast(unsigned, b); }
;     DI void operator()(const f32x4 (&acc)[2][2][4][2], const pg8::Unit& u, int wr, int wc, int fr, int fq) const {
;         const int lrow0 = u.pm * 256 + wr * 64 + fr, grow0 = row_base + u.pm * 256, col0 = u.pn * 256 + wc * 32 + 8 * fq;
;         bf16* Ou = O + (size_t)(u.pm * 256) * ldc + u.pn * 256;
;         const int mrow = grow0 < NCTX ? 8 : (grow0 - NCTX) >> 12;
;         float rstd[2][4];
; #pragma unroll
;         for (int ai = 0; ai < 2; ++ai)
; #pragma unroll
;             for (int m = 0; m < 4; ++m) rstd[ai][m] = rsqrtf(rss[row_base + lrow0 + ai * 128 + m * 16] * (1.f / DM) + EPS);
;         const float* bp = bias + mrow * 4096 + col0;
;         f32x4 bb[2][2];
; #pragma unroll
;         for (int bj = 0; bj < 2; ++bj) { bb[bj][0] = *(const f32x4*)(bp + bj * 128); bb[bj][1] = *(const f32x4*)(bp + bj * 128 + 4); }
;         asm volatile("" ::: "memory");
; #pragma unroll
;         for (int bj = 0; bj < 2; ++bj) { const f32x4 b0 = bb[bj][0], b1 = bb[bj][1];
; #pragma unroll
;             for (int ai = 0; ai < 2; ++ai)
; #pragma unroll
;                 for (int m = 0; m < 4; ++m) {
;                     f32x4 v0 = acc[ai][bj][m][0] * rstd[ai][m] + b0, v1 = acc[ai][bj][m][1] * rstd[ai][m] + b1;
;                     if (ACT == 1) {
; #pragma unroll
;                         for (int e = 0; e < 4; ++e) { float a = fmaxf(v0[e], 0.f), b = fmaxf(v1[e], 0.f); v0[e] = a * a; v1[e] = b * b; } }
;                     u32x4 w; w.x = cvtpk(v0[0], v0[1]); w.y = cvtpk(v0[2], v0[3]); w.z = cvtpk(v1[0], v1[1]); w.w = cvtpk(v1[2], v1[3]);
;                     *(u32x4*)(Ou + (wr * 64 + fr + ai * 128 + m * 16) * ldc + wc * 32 + 8 * fq + bj * 128) = w; } }
.LBB0_1030:
	s_lshl_b32 s6, s56, 8
	v_add_u32_e32 v128, s6, v183
	v_ashrrev_i32_e32 v129, 31, v128
	v_lshl_add_u64 v[128:129], v[128:129], 2, s[86:87]
	global_load_dword v200, v[128:129], off
	global_load_dword v201, v[128:129], off offset:64
	global_load_dword v202, v[128:129], off offset:128
	global_load_dword v203, v[128:129], off offset:192
	global_load_dword v204, v[128:129], off offset:512
	global_load_dword v205, v[128:129], off offset:576
	global_load_dword v206, v[128:129], off offset:640
	global_load_dword v207, v[128:129], off offset:704
	s_lshl_b32 s4, s31, 8
	s_ashr_i32 s7, s6, 31
	s_ashr_i32 s5, s4, 31
	s_lshl_b64 s[8:9], s[6:7], 13
	s_add_u32 s8, s33, s8
	s_addc_u32 s9, s59, s9
	s_and_b32 s7, s6, 0xfffff000
	s_cmp_lt_u32 s6, 0x7ffff800
	s_cselect_b32 s6, s7, 0x8000
	s_ashr_i32 s7, s6, 31
	s_lshl_b64 s[6:7], s[6:7], 2
	v_readlane_b32 s22, v253, 61
	v_readlane_b32 s23, v253, 62
	s_add_u32 s6, s22, s6
	s_addc_u32 s7, s23, s7
	s_waitcnt vmcnt(7)
	v_fmamk_f32 v200, v200, 0x3a800000, v187
	v_cmp_gt_f32_e32 vcc, s52, v200
	v_mul_f32_e32 v131, 0x4b800000, v200
	s_nop 0
	v_cndmask_b32_e32 v200, v200, v131, vcc
	v_rsq_f32_e32 v200, v200
	s_nop 0
	v_mul_f32_e32 v131, 0x45800000, v200
	v_cndmask_b32_e32 v192, v200, v131, vcc
	s_waitcnt vmcnt(6)
	v_fmamk_f32 v201, v201, 0x3a800000, v187
	v_cmp_gt_f32_e32 vcc, s52, v201
	v_mul_f32_e32 v131, 0x4b800000, v201
	s_nop 0
	v_cndmask_b32_e32 v201, v201, v131, vcc
	v_rsq_f32_e32 v201, v201
	s_nop 0
	v_mul_f32_e32 v131, 0x45800000, v201
	v_cndmask_b32_e32 v190, v201, v131, vcc
	s_waitcnt vmcnt(5)
	v_fmamk_f32 v202, v202, 0x3a800000, v187
	v_cmp_gt_f32_e32 vcc, s52, v202
	v_mul_f32_e32 v131, 0x4b800000, v202
	s_nop 0
	v_cndmask_b32_e32 v202, v202, v131, vcc
	v_rsq_f32_e32 v202, v202
	s_nop 0
	v_mul_f32_e32 v131, 0x45800000, v202
	v_cndmask_b32_e32 v188, v202, v131, vcc
	s_waitcnt vmcnt(4)
	v_fmamk_f32 v203, v203, 0x3a800000, v187
	v_cmp_gt_f32_e32 vcc, s52, v203
	v_mul_f32_e32 v131, 0x4b800000, v203
	s_nop 0
	v_cndmask_b32_e32 v203, v203, v131, vcc
	v_rsq_f32_e32 v203, v203
	s_nop 0
	v_mul_f32_e32 v131, 0x45800000, v203
	v_cndmask_b32_e32 v186, v203, v131, vcc
	s_waitcnt vmcnt(3)
	v_fmamk_f32 v204, v204, 0x3a800000, v187
	v_cmp_gt_f32_e32 vcc, s52, v204
	v_mul_f32_e32 v131, 0x4b800000, v204
	s_nop 0
	v_cndmask_b32_e32 v204, v204, v131, vcc
	v_rsq_f32_e32 v204, v204
	s_nop 0
	v_mul_f32_e32 v131, 0x45800000, v204
	v_cndmask_b32_e32 v184, v204, v131, vcc
	s_waitcnt vmcnt(2)
	v_fmamk_f32 v205, v205, 0x3a800000, v187
	v_cmp_gt_f32_e32 vcc, s52, v205
	v_mul_f32_e32 v131, 0x4b800000, v205
	s_nop 0
	v_cndmask_b32_e32 v205, v205, v131, vcc
	v_rsq_f32_e32 v205, v205
	s_nop 0
	v_mul_f32_e32 v131, 0x45800000, v205
	v_cndmask_b32_e32 v182, v205, v131, vcc
	s_waitcnt vmcnt(1)
	v_fmamk_f32 v206, v206, 0x3a800000, v187
	v_cmp_gt_f32_e32 vcc, s52, v206
	v_mul_f32_e32 v131, 0x4b800000, v206
	s_waitcnt vmcnt(0)
	v_fmamk_f32 v207, v207, 0x3a800000, v187
	v_cndmask_b32_e32 v206, v206, v131, vcc
	v_rsq_f32_e32 v206, v206
	v_mul_f32_e32 v129, 0x4b800000, v207
	v_mul_f32_e32 v131, 0x45800000, v206
	v_cndmask_b32_e32 v180, v206, v131, vcc
	v_cmp_gt_f32_e32 vcc, s52, v207
	s_nop 1
	v_cndmask_b32_e32 v207, v207, v129, vcc
	v_rsq_f32_e32 v207, v207
	s_nop 0
	v_mul_f32_e32 v129, 0x45800000, v207
	v_cndmask_b32_e32 v178, v207, v129, vcc
	v_or_b32_e32 v128, s4, v181
	v_ashrrev_i32_e32 v129, 31, v128
	v_lshl_add_u64 v[132:133], v[128:129], 2, s[6:7]
	global_load_dwordx4 v[136:139], v[132:133], off offset:16
	global_load_dwordx4 v[140:143], v[132:133], off
	global_load_dwordx4 v[128:131], v[132:133], off offset:528
	s_nop 0
	global_load_dwordx4 v[132:135], v[132:133], off offset:512
	s_lshl_b64 s[4:5], s[4:5], 1
	s_add_u32 s4, s8, s4
	s_addc_u32 s5, s9, s5
	s_add_u32 s4, s4, s53
	s_addc_u32 s5, s5, 0
	v_lshl_add_u64 v[194:195], s[4:5], 0, v[152:153]
	s_mov_b64 s[4:5], 0x100
	s_andn2_b64 vcc, exec, s[36:37]
	s_waitcnt vmcnt(3)
	v_pk_fma_f32 v[122:123], v[122:123], v[192:193], v[138:139] op_sel_hi:[1,0,1]
	s_waitcnt vmcnt(2)
	v_pk_fma_f32 v[126:127], v[126:127], v[192:193], v[142:143] op_sel_hi:[1,0,1]
	v_pk_fma_f32 v[124:125], v[124:125], v[192:193], v[140:141] op_sel_hi:[1,0,1]
	v_pk_fma_f32 v[120:121], v[120:121], v[192:193], v[136:137] op_sel_hi:[1,0,1]
	v_max_f32_e32 v124, 0, v124
	v_max_f32_e32 v120, 0, v120
	v_max_f32_e32 v125, 0, v125
	v_max_f32_e32 v121, 0, v121
	v_max_f32_e32 v126, 0, v126
	v_max_f32_e32 v122, 0, v122
	v_max_f32_e32 v127, 0, v127
	v_max_f32_e32 v123, 0, v123
	v_pk_mul_f32 v[124:125], v[124:125], v[124:125]
	v_pk_mul_f32 v[120:121], v[120:121], v[120:121]
	v_pk_mul_f32 v[126:127], v[126:127], v[126:127]
	v_pk_mul_f32 v[196:197], v[122:123], v[122:123]
	v_pk_fma_f32 v[112:113], v[112:113], v[190:191], v[136:137] op_sel_hi:[1,0,1]
	v_cvt_pk_bf16_f32 v122, v124, v125
	v_cvt_pk_bf16_f32 v123, v126, v127
	v_cvt_pk_bf16_f32 v124, v120, v121
	v_cvt_pk_bf16_f32 v125, v196, v197
	v_lshl_add_u64 v[120:121], v[154:155], 1, v[194:195]
	v_pk_fma_f32 v[118:119], v[118:119], v[190:191], v[142:143] op_sel_hi:[1,0,1]
	v_pk_fma_f32 v[116:117], v[116:117], v[190:191], v[140:141] op_sel_hi:[1,0,1]
	v_pk_fma_f32 v[114:115], v[114:115], v[190:191], v[138:139] op_sel_hi:[1,0,1]
	v_max_f32_e32 v112, 0, v112
	v_max_f32_e32 v113, 0, v113
	global_store_dwordx4 v[120:121], v[122:125], off
	v_max_f32_e32 v116, 0, v116
	v_max_f32_e32 v117, 0, v117
	v_pk_mul_f32 v[122:123], v[112:113], v[112:113]
	v_max_f32_e32 v112, 0, v118
	v_max_f32_e32 v114, 0, v114
	v_max_f32_e32 v113, 0, v119
	v_max_f32_e32 v115, 0, v115
	v_pk_mul_f32 v[116:117], v[116:117], v[116:117]
	v_pk_mul_f32 v[118:119], v[112:113], v[112:113]
	v_pk_mul_f32 v[124:125], v[114:115], v[114:115]
; DI unsigned cvtpk(float lo, float hi) { f32x2 v = {lo, hi}; bf16x2_t b = __builtin_convertvector(v, bf16x2_t); return __builtin_bit_cast(unsigned, b); }
;     DI void operator()(const f32x4 (&acc)[2][2][4][2], const pg8::Unit& u, int wr, int wc, int fr, int fq) const {
;     ...
;         for (int bj = 0; bj < 2; ++bj) { const f32x4 b0 = bb[bj][0], b1 = bb[bj][1];
; #pragma unroll
;             for (int ai = 0; ai < 2; ++ai)
; #pragma unroll
;                 for (int m = 0; m < 4; ++m) {
;                     f32x4 v0 = acc[ai][bj][m][0] * rstd[ai][m] + b0, v1 = acc[ai][bj][m][1] * rstd[ai][m] + b1;
;                     if (ACT == 1) {
; #pragma unroll
;                         for (int e = 0; e < 4; ++e) { float a = fmaxf(v0[e], 0.f), b = fmaxf(v1[e], 0.f); v0[e] = a * a; v1[e] = b * b; } }
;                     u32x4 w; w.x = cvtpk(v0[0], v0[1]); w.y = cvtpk(v0[2], v0[3]); w.z = cvtpk(v1[0], v1[1]); w.w = cvtpk(v1[2], v1[3]);
;                     *(u32x4*)(Ou + (wr * 64 + fr + ai * 128 + m * 16) * ldc + wc * 32 + 8 * fq + bj * 128) = w; } }
	v_pk_fma_f32 v[104:105], v[104:105], v[188:189], v[136:137] op_sel_hi:[1,0,1]
	v_cvt_pk_bf16_f32 v112, v116, v117
	v_cvt_pk_bf16_f32 v113, v118, v119
	v_cvt_pk_bf16_f32 v114, v122, v123
	v_cvt_pk_bf16_f32 v115, v124, v125
	v_lshl_add_u64 v[116:117], v[194:195], 0, v[170:171]
	v_pk_fma_f32 v[110:111], v[110:111], v[188:189], v[142:143] op_sel_hi:[1,0,1]
	v_pk_fma_f32 v[108:109], v[108:109], v[188:189], v[140:141] op_sel_hi:[1,0,1]
	v_pk_fma_f32 v[106:107], v[106:107], v[188:189], v[138:139] op_sel_hi:[1,0,1]
	v_max_f32_e32 v104, 0, v104
	v_max_f32_e32 v105, 0, v105
	global_store_dwordx4 v[116:117], v[112:115], off
	v_max_f32_e32 v108, 0, v108
	v_max_f32_e32 v109, 0, v109
	v_pk_mul_f32 v[112:113], v[104:105], v[104:105]
	v_max_f32_e32 v104, 0, v110
	v_max_f32_e32 v106, 0, v106
	v_max_f32_e32 v105, 0, v111
	v_max_f32_e32 v107, 0, v107
	v_pk_mul_f32 v[108:109], v[108:109], v[108:109]
	v_pk_mul_f32 v[110:111], v[104:105], v[104:105]
	v_pk_mul_f32 v[114:115], v[106:107], v[106:107]
	v_pk_fma_f32 v[96:97], v[96:97], v[186:187], v[136:137] op_sel_hi:[1,0,1]
	v_cvt_pk_bf16_f32 v104, v108, v109
	v_cvt_pk_bf16_f32 v105, v110, v111
	v_cvt_pk_bf16_f32 v106, v112, v113
	v_cvt_pk_bf16_f32 v107, v114, v115
	v_lshl_add_u64 v[108:109], v[194:195], 0, v[172:173]
	v_pk_fma_f32 v[102:103], v[102:103], v[186:187], v[142:143] op_sel_hi:[1,0,1]
	v_pk_fma_f32 v[100:101], v[100:101], v[186:187], v[140:141] op_sel_hi:[1,0,1]
	v_pk_fma_f32 v[98:99], v[98:99], v[186:187], v[138:139] op_sel_hi:[1,0,1]
	v_max_f32_e32 v96, 0, v96
	v_max_f32_e32 v97, 0, v97
	global_store_dwordx4 v[108:109], v[104:107], off
	v_max_f32_e32 v100, 0, v100
	v_max_f32_e32 v101, 0, v101
	v_pk_mul_f32 v[104:105], v[96:97], v[96:97]
	v_max_f32_e32 v96, 0, v102
	v_max_f32_e32 v98, 0, v98
	v_max_f32_e32 v97, 0, v103
	v_max_f32_e32 v99, 0, v99
	v_pk_mul_f32 v[100:101], v[100:101], v[100:101]
	v_pk_mul_f32 v[102:103], v[96:97], v[96:97]
	v_pk_mul_f32 v[106:107], v[98:99], v[98:99]
	v_pk_fma_f32 v[94:95], v[94:95], v[184:185], v[142:143] op_sel_hi:[1,0,1]
	v_pk_fma_f32 v[92:93], v[92:93], v[184:185], v[140:141] op_sel_hi:[1,0,1]
	v_pk_fma_f32 v[90:91], v[90:91], v[184:185], v[138:139] op_sel_hi:[1,0,1]
	v_pk_fma_f32 v[88:89], v[88:89], v[184:185], v[136:137] op_sel_hi:[1,0,1]
	v_cvt_pk_bf16_f32 v96, v100, v101
	v_cvt_pk_bf16_f32 v97, v102, v103
	v_cvt_pk_bf16_f32 v98, v104, v105
	v_cvt_pk_bf16_f32 v99, v106, v107
	v_lshl_add_u64 v[100:101], v[194:195], 0, v[174:175]
	v_max_f32_e32 v92, 0, v92
	v_max_f32_e32 v88, 0, v88
	v_max_f32_e32 v93, 0, v93
	v_max_f32_e32 v89, 0, v89
	v_max_f32_e32 v94, 0, v94
	v_max_f32_e32 v90, 0, v90
	v_max_f32_e32 v95, 0, v95
	v_max_f32_e32 v91, 0, v91
	global_store_dwordx4 v[100:101], v[96:99], off
	v_pk_mul_f32 v[92:93], v[92:93], v[92:93]
	v_pk_mul_f32 v[88:89], v[88:89], v[88:89]
	v_pk_mul_f32 v[94:95], v[94:95], v[94:95]
	v_pk_mul_f32 v[96:97], v[90:91], v[90:91]
	v_pk_fma_f32 v[86:87], v[86:87], v[182:183], v[142:143] op_sel_hi:[1,0,1]
	v_pk_fma_f32 v[84:85], v[84:85], v[182:183], v[140:141] op_sel_hi:[1,0,1]
	v_pk_fma_f32 v[82:83], v[82:83], v[182:183], v[138:139] op_sel_hi:[1,0,1]
	v_pk_fma_f32 v[80:81], v[80:81], v[182:183], v[136:137] op_sel_hi:[1,0,1]
	v_cvt_pk_bf16_f32 v90, v92, v93
	v_cvt_pk_bf16_f32 v91, v94, v95
	v_cvt_pk_bf16_f32 v92, v88, v89
	v_cvt_pk_bf16_f32 v93, v96, v97
	v_lshl_add_u64 v[88:89], v[156:157], 1, v[194:195]
	v_max_f32_e32 v84, 0, v84
	v_max_f32_e32 v80, 0, v80
	v_max_f32_e32 v85, 0, v85
	v_max_f32_e32 v81, 0, v81
	v_max_f32_e32 v86, 0, v86
	v_max_f32_e32 v82, 0, v82
	v_max_f32_e32 v87, 0, v87
	v_max_f32_e32 v83, 0, v83
	global_store_dwordx4 v[88:89], v[90:93], off
	v_pk_mul_f32 v[84:85], v[84:85], v[84:85]
	v_pk_mul_f32 v[80:81], v[80:81], v[80:81]
	v_pk_mul_f32 v[86:87], v[86:87], v[86:87]
	v_pk_mul_f32 v[90:91], v[82:83], v[82:83]
	v_pk_fma_f32 v[78:79], v[78:79], v[180:181], v[142:143] op_sel_hi:[1,0,1]
	v_pk_fma_f32 v[76:77], v[76:77], v[180:181], v[140:141] op_sel_hi:[1,0,1]
	v_pk_fma_f32 v[74:75], v[74:75], v[180:181], v[138:139] op_sel_hi:[1,0,1]
	v_pk_fma_f32 v[72:73], v[72:73], v[180:181], v[136:137] op_sel_hi:[1,0,1]
	v_cvt_pk_bf16_f32 v82, v84, v85
	v_cvt_pk_bf16_f32 v83, v86, v87
	v_cvt_pk_bf16_f32 v84, v80, v81
	v_cvt_pk_bf16_f32 v85, v90, v91
	v_lshl_add_u64 v[80:81], v[158:159], 1, v[194:195]
	v_max_f32_e32 v76, 0, v76
	v_max_f32_e32 v72, 0, v72
	v_max_f32_e32 v77, 0, v77
	v_max_f32_e32 v73, 0, v73
	v_max_f32_e32 v78, 0, v78
	v_max_f32_e32 v74, 0, v74
	v_max_f32_e32 v79, 0, v79
	v_max_f32_e32 v75, 0, v75
	global_store_dwordx4 v[80:81], v[82:85], off
	v_pk_mul_f32 v[76:77], v[76:77], v[76:77]
	v_pk_mul_f32 v[72:73], v[72:73], v[72:73]
	v_pk_mul_f32 v[78:79], v[78:79], v[78:79]
	v_pk_mul_f32 v[82:83], v[74:75], v[74:75]
	v_pk_fma_f32 v[62:63], v[62:63], v[178:179], v[142:143] op_sel_hi:[1,0,1]
	v_pk_fma_f32 v[60:61], v[60:61], v[178:179], v[140:141] op_sel_hi:[1,0,1]
	v_pk_fma_f32 v[58:59], v[58:59], v[178:179], v[138:139] op_sel_hi:[1,0,1]
	v_pk_fma_f32 v[56:57], v[56:57], v[178:179], v[136:137] op_sel_hi:[1,0,1]
	v_cvt_pk_bf16_f32 v74, v76, v77
	v_cvt_pk_bf16_f32 v75, v78, v79
	v_cvt_pk_bf16_f32 v76, v72, v73
	v_cvt_pk_bf16_f32 v77, v82, v83
	v_lshl_add_u64 v[72:73], v[160:161], 1, v[194:195]
	v_max_f32_e32 v60, 0, v60
	v_max_f32_e32 v56, 0, v56
	v_max_f32_e32 v61, 0, v61
	v_max_f32_e32 v57, 0, v57
	v_max_f32_e32 v62, 0, v62
	v_max_f32_e32 v58, 0, v58
	v_max_f32_e32 v63, 0, v63
	v_max_f32_e32 v59, 0, v59
	global_store_dwordx4 v[72:73], v[74:77], off
	v_pk_mul_f32 v[60:61], v[60:61], v[60:61]
	v_pk_mul_f32 v[56:57], v[56:57], v[56:57]
	v_pk_mul_f32 v[62:63], v[62:63], v[62:63]
	v_pk_mul_f32 v[74:75], v[58:59], v[58:59]
	v_cvt_pk_bf16_f32 v58, v60, v61
	v_cvt_pk_bf16_f32 v59, v62, v63
	v_cvt_pk_bf16_f32 v60, v56, v57
	v_cvt_pk_bf16_f32 v61, v74, v75
	v_lshl_add_u64 v[56:57], v[162:163], 1, v[194:195]
	global_store_dwordx4 v[56:57], v[58:61], off
	s_waitcnt vmcnt(9)
; DI unsigned cvtpk(float lo, float hi) { f32x2 v = {lo, hi}; bf16x2_t b = __builtin_convertvector(v, bf16x2_t); return __builtin_bit_cast(unsigned, b); }
;     DI void operator()(const f32x4 (&acc)[2][2][4][2], const pg8::Unit& u, int wr, int wc, int fr, int fq) const {
;     ...
;         for (int bj = 0; bj < 2; ++bj) { const f32x4 b0 = bb[bj][0], b1 = bb[bj][1];
; #pragma unroll
;             for (int ai = 0; ai < 2; ++ai)
; #pragma unroll
;                 for (int m = 0; m < 4; ++m) {
;                     f32x4 v0 = acc[ai][bj][m][0] * rstd[ai][m] + b0, v1 = acc[ai][bj][m][1] * rstd[ai][m] + b1;
;                     if (ACT == 1) {
; #pragma unroll
;                         for (int e = 0; e < 4; ++e) { float a = fmaxf(v0[e], 0.f), b = fmaxf(v1[e], 0.f); v0[e] = a * a; v1[e] = b * b; } }
;                     u32x4 w; w.x = cvtpk(v0[0], v0[1]); w.y = cvtpk(v0[2], v0[3]); w.z = cvtpk(v1[0], v1[1]); w.w = cvtpk(v1[2], v1[3]);
;                     *(u32x4*)(Ou + (wr * 64 + fr + ai * 128 + m * 16) * ldc + wc * 32 + 8 * fq + bj * 128) = w; } }
	v_pk_fma_f32 v[66:67], v[66:67], v[192:193], v[130:131] op_sel_hi:[1,0,1]
	v_pk_fma_f32 v[64:65], v[64:65], v[192:193], v[128:129] op_sel_hi:[1,0,1]
	s_waitcnt vmcnt(8)
	v_pk_fma_f32 v[58:59], v[70:71], v[192:193], v[134:135] op_sel_hi:[1,0,1]
	v_pk_fma_f32 v[60:61], v[68:69], v[192:193], v[132:133] op_sel_hi:[1,0,1]
	v_max_f32_e32 v64, 0, v64
	v_max_f32_e32 v60, 0, v60
	v_max_f32_e32 v61, 0, v61
	v_max_f32_e32 v65, 0, v65
	v_max_f32_e32 v58, 0, v58
	v_max_f32_e32 v66, 0, v66
	v_max_f32_e32 v59, 0, v59
	v_max_f32_e32 v67, 0, v67
	v_pk_mul_f32 v[60:61], v[60:61], v[60:61]
	v_pk_mul_f32 v[64:65], v[64:65], v[64:65]
	v_pk_mul_f32 v[68:69], v[58:59], v[58:59]
	v_pk_mul_f32 v[66:67], v[66:67], v[66:67]
	v_pk_fma_f32 v[48:49], v[48:49], v[190:191], v[128:129] op_sel_hi:[1,0,1]
	v_cvt_pk_bf16_f32 v58, v60, v61
	v_cvt_pk_bf16_f32 v59, v68, v69
	v_cvt_pk_bf16_f32 v60, v64, v65
	v_cvt_pk_bf16_f32 v61, v66, v67
	v_pk_fma_f32 v[54:55], v[54:55], v[190:191], v[134:135] op_sel_hi:[1,0,1]
	v_pk_fma_f32 v[52:53], v[52:53], v[190:191], v[132:133] op_sel_hi:[1,0,1]
	v_pk_fma_f32 v[50:51], v[50:51], v[190:191], v[130:131] op_sel_hi:[1,0,1]
	v_max_f32_e32 v48, 0, v48
	v_max_f32_e32 v49, 0, v49
	global_store_dwordx4 v[120:121], v[58:61], off offset:256
	v_max_f32_e32 v52, 0, v52
	v_max_f32_e32 v53, 0, v53
	v_pk_mul_f32 v[58:59], v[48:49], v[48:49]
	v_max_f32_e32 v48, 0, v54
	v_max_f32_e32 v50, 0, v50
	v_max_f32_e32 v49, 0, v55
	v_max_f32_e32 v51, 0, v51
	v_lshl_add_u64 v[62:63], v[194:195], 0, s[4:5]
	v_pk_mul_f32 v[52:53], v[52:53], v[52:53]
	v_pk_mul_f32 v[54:55], v[48:49], v[48:49]
	v_pk_mul_f32 v[60:61], v[50:51], v[50:51]
	v_pk_fma_f32 v[40:41], v[40:41], v[188:189], v[128:129] op_sel_hi:[1,0,1]
	v_cvt_pk_bf16_f32 v48, v52, v53
	v_cvt_pk_bf16_f32 v49, v54, v55
	v_cvt_pk_bf16_f32 v50, v58, v59
	v_cvt_pk_bf16_f32 v51, v60, v61
	v_lshl_add_u64 v[52:53], v[62:63], 0, v[170:171]
	v_pk_fma_f32 v[46:47], v[46:47], v[188:189], v[134:135] op_sel_hi:[1,0,1]
	v_pk_fma_f32 v[44:45], v[44:45], v[188:189], v[132:133] op_sel_hi:[1,0,1]
	v_pk_fma_f32 v[42:43], v[42:43], v[188:189], v[130:131] op_sel_hi:[1,0,1]
	v_max_f32_e32 v40, 0, v40
	v_max_f32_e32 v41, 0, v41
	global_store_dwordx4 v[52:53], v[48:51], off
	v_max_f32_e32 v44, 0, v44
	v_max_f32_e32 v45, 0, v45
	v_pk_mul_f32 v[48:49], v[40:41], v[40:41]
	v_max_f32_e32 v40, 0, v46
	v_max_f32_e32 v42, 0, v42
	v_max_f32_e32 v41, 0, v47
	v_max_f32_e32 v43, 0, v43
	v_pk_mul_f32 v[44:45], v[44:45], v[44:45]
	v_pk_mul_f32 v[46:47], v[40:41], v[40:41]
	v_pk_mul_f32 v[50:51], v[42:43], v[42:43]
	v_pk_fma_f32 v[32:33], v[32:33], v[186:187], v[128:129] op_sel_hi:[1,0,1]
	v_cvt_pk_bf16_f32 v40, v44, v45
	v_cvt_pk_bf16_f32 v41, v46, v47
	v_cvt_pk_bf16_f32 v42, v48, v49
	v_cvt_pk_bf16_f32 v43, v50, v51
	v_lshl_add_u64 v[44:45], v[62:63], 0, v[172:173]
	v_pk_fma_f32 v[38:39], v[38:39], v[186:187], v[134:135] op_sel_hi:[1,0,1]
	v_pk_fma_f32 v[36:37], v[36:37], v[186:187], v[132:133] op_sel_hi:[1,0,1]
	v_pk_fma_f32 v[34:35], v[34:35], v[186:187], v[130:131] op_sel_hi:[1,0,1]
	v_max_f32_e32 v32, 0, v32
	v_max_f32_e32 v33, 0, v33
	global_store_dwordx4 v[44:45], v[40:43], off
	v_max_f32_e32 v36, 0, v36
	v_max_f32_e32 v37, 0, v37
	v_pk_mul_f32 v[40:41], v[32:33], v[32:33]
	v_max_f32_e32 v32, 0, v38
	v_max_f32_e32 v34, 0, v34
	v_max_f32_e32 v33, 0, v39
	v_max_f32_e32 v35, 0, v35
	v_pk_mul_f32 v[36:37], v[36:37], v[36:37]
	v_pk_mul_f32 v[38:39], v[32:33], v[32:33]
	v_pk_mul_f32 v[42:43], v[34:35], v[34:35]
	v_pk_fma_f32 v[24:25], v[24:25], v[184:185], v[128:129] op_sel_hi:[1,0,1]
	v_cvt_pk_bf16_f32 v32, v36, v37
	v_cvt_pk_bf16_f32 v33, v38, v39
	v_cvt_pk_bf16_f32 v34, v40, v41
; DI unsigned cvtpk(float lo, float hi) { f32x2 v = {lo, hi}; bf16x2_t b = __builtin_convertvector(v, bf16x2_t); return __builtin_bit_cast(unsigned, b); }
;     DI void operator()(const f32x4 (&acc)[2][2][4][2], const pg8::Unit& u, int wr, int wc, int fr, int fq) const {
;     ...
;         for (int bj = 0; bj < 2; ++bj) { const f32x4 b0 = bb[bj][0], b1 = bb[bj][1];
; #pragma unroll
;             for (int ai = 0; ai < 2; ++ai)
; #pragma unroll
;                 for (int m = 0; m < 4; ++m) {
;                     f32x4 v0 = acc[ai][bj][m][0] * rstd[ai][m] + b0, v1 = acc[ai][bj][m][1] * rstd[ai][m] + b1;
;                     if (ACT == 1) {
; #pragma unroll
;                         for (int e = 0; e < 4; ++e) { float a = fmaxf(v0[e], 0.f), b = fmaxf(v1[e], 0.f); v0[e] = a * a; v1[e] = b * b; } }
;                     u32x4 w; w.x = cvtpk(v0[0], v0[1]); w.y = cvtpk(v0[2], v0[3]); w.z = cvtpk(v1[0], v1[1]); w.w = cvtpk(v1[2], v1[3]);
;                     *(u32x4*)(Ou + (wr * 64 + fr + ai * 128 + m * 16) * ldc + wc * 32 + 8 * fq + bj * 128) = w; } }
	v_cvt_pk_bf16_f32 v35, v42, v43
	v_lshl_add_u64 v[36:37], v[62:63], 0, v[174:175]
	v_pk_fma_f32 v[30:31], v[30:31], v[184:185], v[134:135] op_sel_hi:[1,0,1]
	v_pk_fma_f32 v[28:29], v[28:29], v[184:185], v[132:133] op_sel_hi:[1,0,1]
	v_pk_fma_f32 v[26:27], v[26:27], v[184:185], v[130:131] op_sel_hi:[1,0,1]
	v_max_f32_e32 v24, 0, v24
	v_max_f32_e32 v25, 0, v25
	global_store_dwordx4 v[36:37], v[32:35], off
	v_max_f32_e32 v28, 0, v28
	v_max_f32_e32 v29, 0, v29
	v_pk_mul_f32 v[32:33], v[24:25], v[24:25]
	v_max_f32_e32 v24, 0, v30
	v_max_f32_e32 v26, 0, v26
	v_max_f32_e32 v25, 0, v31
	v_max_f32_e32 v27, 0, v27
	v_pk_mul_f32 v[28:29], v[28:29], v[28:29]
	v_pk_mul_f32 v[30:31], v[24:25], v[24:25]
	v_pk_mul_f32 v[34:35], v[26:27], v[26:27]
	v_pk_fma_f32 v[16:17], v[16:17], v[182:183], v[128:129] op_sel_hi:[1,0,1]
	v_cvt_pk_bf16_f32 v24, v28, v29
	v_cvt_pk_bf16_f32 v25, v30, v31
	v_cvt_pk_bf16_f32 v26, v32, v33
	v_cvt_pk_bf16_f32 v27, v34, v35
	v_pk_fma_f32 v[22:23], v[22:23], v[182:183], v[134:135] op_sel_hi:[1,0,1]
	v_pk_fma_f32 v[20:21], v[20:21], v[182:183], v[132:133] op_sel_hi:[1,0,1]
	v_pk_fma_f32 v[18:19], v[18:19], v[182:183], v[130:131] op_sel_hi:[1,0,1]
	v_max_f32_e32 v16, 0, v16
	v_max_f32_e32 v17, 0, v17
	global_store_dwordx4 v[88:89], v[24:27], off offset:256
	v_max_f32_e32 v20, 0, v20
	v_max_f32_e32 v21, 0, v21
	v_pk_mul_f32 v[24:25], v[16:17], v[16:17]
	v_max_f32_e32 v16, 0, v22
	v_max_f32_e32 v18, 0, v18
	v_max_f32_e32 v17, 0, v23
	v_max_f32_e32 v19, 0, v19
	v_pk_mul_f32 v[20:21], v[20:21], v[20:21]
	v_pk_mul_f32 v[22:23], v[16:17], v[16:17]
	v_pk_mul_f32 v[26:27], v[18:19], v[18:19]
	v_pk_fma_f32 v[8:9], v[8:9], v[180:181], v[128:129] op_sel_hi:[1,0,1]
	v_cvt_pk_bf16_f32 v16, v20, v21
	v_cvt_pk_bf16_f32 v17, v22, v23
	v_cvt_pk_bf16_f32 v18, v24, v25
	v_cvt_pk_bf16_f32 v19, v26, v27
	v_pk_fma_f32 v[14:15], v[14:15], v[180:181], v[134:135] op_sel_hi:[1,0,1]
	v_pk_fma_f32 v[12:13], v[12:13], v[180:181], v[132:133] op_sel_hi:[1,0,1]
	v_pk_fma_f32 v[10:11], v[10:11], v[180:181], v[130:131] op_sel_hi:[1,0,1]
	v_max_f32_e32 v8, 0, v8
	v_max_f32_e32 v9, 0, v9
	global_store_dwordx4 v[80:81], v[16:19], off offset:256
	v_max_f32_e32 v12, 0, v12
	v_max_f32_e32 v13, 0, v13
	v_pk_mul_f32 v[16:17], v[8:9], v[8:9]
	v_max_f32_e32 v8, 0, v14
	v_max_f32_e32 v10, 0, v10
	v_max_f32_e32 v9, 0, v15
	v_max_f32_e32 v11, 0, v11
	v_pk_mul_f32 v[12:13], v[12:13], v[12:13]
	v_pk_mul_f32 v[14:15], v[8:9], v[8:9]
	v_pk_mul_f32 v[18:19], v[10:11], v[10:11]
	v_pk_fma_f32 v[0:1], v[0:1], v[178:179], v[128:129] op_sel_hi:[1,0,1]
	v_cvt_pk_bf16_f32 v8, v12, v13
	v_cvt_pk_bf16_f32 v9, v14, v15
	v_cvt_pk_bf16_f32 v10, v16, v17
	v_cvt_pk_bf16_f32 v11, v18, v19
	v_pk_fma_f32 v[6:7], v[6:7], v[178:179], v[134:135] op_sel_hi:[1,0,1]
	v_pk_fma_f32 v[4:5], v[4:5], v[178:179], v[132:133] op_sel_hi:[1,0,1]
	v_pk_fma_f32 v[2:3], v[2:3], v[178:179], v[130:131] op_sel_hi:[1,0,1]
	v_max_f32_e32 v0, 0, v0
	v_max_f32_e32 v1, 0, v1
	global_store_dwordx4 v[72:73], v[8:11], off offset:256
	v_max_f32_e32 v4, 0, v4
	v_max_f32_e32 v5, 0, v5
	v_pk_mul_f32 v[8:9], v[0:1], v[0:1]
	v_max_f32_e32 v0, 0, v6
	v_max_f32_e32 v2, 0, v2
	v_max_f32_e32 v1, 0, v7
	v_max_f32_e32 v3, 0, v3
	v_pk_mul_f32 v[4:5], v[4:5], v[4:5]
	v_pk_mul_f32 v[6:7], v[0:1], v[0:1]
	v_pk_mul_f32 v[10:11], v[2:3], v[2:3]
	v_cvt_pk_bf16_f32 v0, v4, v5
	v_cvt_pk_bf16_f32 v1, v6, v7
	v_cvt_pk_bf16_f32 v2, v8, v9
	v_cvt_pk_bf16_f32 v3, v10, v11
	s_mov_b64 s[4:5], -1
	global_store_dwordx4 v[56:57], v[0:3], off offset:256
	s_cbranch_vccnz .LBB0_1023
	s_andn2_b64 vcc, exec, s[0:1]
	s_cbranch_vccnz .LBB0_1022
	s_barrier
	s_branch .LBB0_1022

; DI unsigned cvtpk(float lo, float hi) { f32x2 v = {lo, hi}; bf16x2_t b = __builtin_convertvector(v, bf16x2_t); return __builtin_bit_cast(unsigned, b); }
;     DI void operator()(const f32x4 (&acc)[2][2][4][2], const pg8::Unit& u, int wr, int wc, int fr, int fq) const {
;         const int lrow0 = u.pm * 256 + wr * 64 + fr, grow0 = row_base + u.pm * 256, col0 = u.pn * 256 + wc * 32 + 8 * fq;
;         bf16* Ou = O + (size_t)(u.pm * 256) * ldc + u.pn * 256;
;         const int mrow = grow0 < NCTX ? 8 : (grow0 - NCTX) >> 12;
;         float rstd[2][4];
; #pragma unroll
;         for (int ai = 0; ai < 2; ++ai)
; #pragma unroll
;             for (int m = 0; m < 4; ++m) rstd[ai][m] = rsqrtf(rss[row_base + lrow0 + ai * 128 + m * 16] * (1.f / DM) + EPS);
;         const float* bp = bias + mrow * 4096 + col0;
;         f32x4 bb[2][2];
; #pragma unroll
;         for (int bj = 0; bj < 2; ++bj) { bb[bj][0] = *(const f32x4*)(bp + bj * 128); bb[bj][1] = *(const f32x4*)(bp + bj * 128 + 4); }
;         asm volatile("" ::: "memory");
; #pragma unroll
;         for (int bj = 0; bj < 2; ++bj) { const f32x4 b0 = bb[bj][0], b1 = bb[bj][1];
; #pragma unroll
;             for (int ai = 0; ai < 2; ++ai)
; #pragma unroll
;                 for (int m = 0; m < 4; ++m) {
;                     f32x4 v0 = acc[ai][bj][m][0] * rstd[ai][m] + b0, v1 = acc[ai][bj][m][1] * rstd[ai][m] + b1;
;                     if (ACT == 1) {
; #pragma unroll
;                         for (int e = 0; e < 4; ++e) { float a = fmaxf(v0[e], 0.f), b = fmaxf(v1[e], 0.f); v0[e] = a * a; v1[e] = b * b; } }
;                     u32x4 w; w.x = cvtpk(v0[0], v0[1]); w.y = cvtpk(v0[2], v0[3]); w.z = cvtpk(v1[0], v1[1]); w.w = cvtpk(v1[2], v1[3]);
;                     *(u32x4*)(Ou + (wr * 64 + fr + ai * 128 + m * 16) * ldc + wc * 32 + 8 * fq + bj * 128) = w; } }
.LBB0_1097:
	s_lshl_b32 s6, s48, 8
	v_add_u32_e32 v128, s6, v179
	v_ashrrev_i32_e32 v129, 31, v128
	v_lshl_add_u64 v[128:129], v[128:129], 2, s[86:87]
	global_load_dword v200, v[128:129], off
	global_load_dword v201, v[128:129], off offset:64
	global_load_dword v202, v[128:129], off offset:128
	global_load_dword v203, v[128:129], off offset:192
	global_load_dword v204, v[128:129], off offset:512
	global_load_dword v205, v[128:129], off offset:576
	global_load_dword v206, v[128:129], off offset:640
	global_load_dword v207, v[128:129], off offset:704
	s_lshl_b32 s4, s31, 8
	s_ashr_i32 s7, s6, 31
	s_ashr_i32 s5, s4, 31
	s_lshl_b64 s[8:9], s[6:7], 13
	s_add_u32 s8, s88, s8
	s_addc_u32 s9, s89, s9
	s_addk_i32 s6, 0xf800
	s_and_b32 s6, s6, 0xfffff000
	s_cmp_gt_i32 s48, 7
	s_cselect_b32 s6, s6, 0x8000
	s_ashr_i32 s7, s6, 31
	s_lshl_b64 s[6:7], s[6:7], 2
	v_readlane_b32 s22, v253, 61
	v_readlane_b32 s23, v253, 62
	s_add_u32 s6, s22, s6
	s_addc_u32 s7, s23, s7
	s_waitcnt vmcnt(7)
	v_fmamk_f32 v200, v200, 0x3a800000, v189
	v_cmp_gt_f32_e32 vcc, s60, v200
	v_mul_f32_e32 v131, 0x4b800000, v200
	s_nop 0
	v_cndmask_b32_e32 v200, v200, v131, vcc
	v_rsq_f32_e32 v200, v200
	s_nop 0
	v_mul_f32_e32 v131, 0x45800000, v200
	v_cndmask_b32_e32 v192, v200, v131, vcc
	s_waitcnt vmcnt(6)
	v_fmamk_f32 v201, v201, 0x3a800000, v189
	v_cmp_gt_f32_e32 vcc, s60, v201
	v_mul_f32_e32 v131, 0x4b800000, v201
	s_nop 0
	v_cndmask_b32_e32 v201, v201, v131, vcc
	v_rsq_f32_e32 v201, v201
	s_nop 0
	v_mul_f32_e32 v131, 0x45800000, v201
	v_cndmask_b32_e32 v190, v201, v131, vcc
	s_waitcnt vmcnt(5)
	v_fmamk_f32 v202, v202, 0x3a800000, v189
	v_cmp_gt_f32_e32 vcc, s60, v202
	v_mul_f32_e32 v131, 0x4b800000, v202
	s_nop 0
	v_cndmask_b32_e32 v202, v202, v131, vcc
	v_rsq_f32_e32 v202, v202
	s_nop 0
	v_mul_f32_e32 v131, 0x45800000, v202
	v_cndmask_b32_e32 v188, v202, v131, vcc
	s_waitcnt vmcnt(4)
	v_fmamk_f32 v203, v203, 0x3a800000, v189
	v_cmp_gt_f32_e32 vcc, s60, v203
	v_mul_f32_e32 v131, 0x4b800000, v203
	s_nop 0
	v_cndmask_b32_e32 v203, v203, v131, vcc
	v_rsq_f32_e32 v203, v203
	s_nop 0
	v_mul_f32_e32 v131, 0x45800000, v203
	v_cndmask_b32_e32 v186, v203, v131, vcc
	s_waitcnt vmcnt(3)
	v_fmamk_f32 v204, v204, 0x3a800000, v189
	v_cmp_gt_f32_e32 vcc, s60, v204
	v_mul_f32_e32 v131, 0x4b800000, v204
	s_nop 0
	v_cndmask_b32_e32 v204, v204, v131, vcc
	v_rsq_f32_e32 v204, v204
	s_nop 0
	v_mul_f32_e32 v131, 0x45800000, v204
	v_cndmask_b32_e32 v184, v204, v131, vcc
	s_waitcnt vmcnt(2)
	v_fmamk_f32 v205, v205, 0x3a800000, v189
	v_cmp_gt_f32_e32 vcc, s60, v205
	v_mul_f32_e32 v131, 0x4b800000, v205
	s_nop 0
	v_cndmask_b32_e32 v205, v205, v131, vcc
	v_rsq_f32_e32 v205, v205
	s_nop 0
	v_mul_f32_e32 v131, 0x45800000, v205
	v_cndmask_b32_e32 v182, v205, v131, vcc
	s_waitcnt vmcnt(1)
	v_fmamk_f32 v206, v206, 0x3a800000, v189
	v_cmp_gt_f32_e32 vcc, s60, v206
	v_mul_f32_e32 v131, 0x4b800000, v206
	s_waitcnt vmcnt(0)
	v_fmamk_f32 v207, v207, 0x3a800000, v189
	v_cndmask_b32_e32 v206, v206, v131, vcc
	v_rsq_f32_e32 v206, v206
	v_mul_f32_e32 v129, 0x4b800000, v207
	v_mul_f32_e32 v131, 0x45800000, v206
	v_cndmask_b32_e32 v180, v206, v131, vcc
	v_cmp_gt_f32_e32 vcc, s60, v207
	s_nop 1
	v_cndmask_b32_e32 v207, v207, v129, vcc
	v_rsq_f32_e32 v207, v207
	s_nop 0
	v_mul_f32_e32 v129, 0x45800000, v207
	v_cndmask_b32_e32 v178, v207, v129, vcc
	v_or_b32_e32 v128, s4, v183
	v_ashrrev_i32_e32 v129, 31, v128
	v_lshl_add_u64 v[132:133], v[128:129], 2, s[6:7]
	global_load_dwordx4 v[136:139], v[132:133], off offset:16
	global_load_dwordx4 v[140:143], v[132:133], off
	global_load_dwordx4 v[128:131], v[132:133], off offset:528
	s_nop 0
	global_load_dwordx4 v[132:135], v[132:133], off offset:512
	s_lshl_b64 s[4:5], s[4:5], 1
	s_add_u32 s4, s8, s4
	s_addc_u32 s5, s9, s5
	s_add_u32 s4, s4, s61
	s_addc_u32 s5, s5, 0
	v_lshl_add_u64 v[194:195], s[4:5], 0, v[152:153]
	s_mov_b64 s[4:5], 0x100
	s_andn2_b64 vcc, exec, s[36:37]
	s_waitcnt vmcnt(3)
	v_pk_fma_f32 v[122:123], v[122:123], v[192:193], v[138:139] op_sel_hi:[1,0,1]
	s_waitcnt vmcnt(2)
	v_pk_fma_f32 v[126:127], v[126:127], v[192:193], v[142:143] op_sel_hi:[1,0,1]
	v_pk_fma_f32 v[124:125], v[124:125], v[192:193], v[140:141] op_sel_hi:[1,0,1]
	v_pk_fma_f32 v[120:121], v[120:121], v[192:193], v[136:137] op_sel_hi:[1,0,1]
	v_max_f32_e32 v124, 0, v124
	v_max_f32_e32 v120, 0, v120
	v_max_f32_e32 v125, 0, v125
	v_max_f32_e32 v121, 0, v121
	v_max_f32_e32 v126, 0, v126
	v_max_f32_e32 v122, 0, v122
	v_max_f32_e32 v127, 0, v127
	v_max_f32_e32 v123, 0, v123
	v_pk_mul_f32 v[124:125], v[124:125], v[124:125]
	v_pk_mul_f32 v[120:121], v[120:121], v[120:121]
	v_pk_mul_f32 v[126:127], v[126:127], v[126:127]
	v_pk_mul_f32 v[196:197], v[122:123], v[122:123]
	v_pk_fma_f32 v[112:113], v[112:113], v[190:191], v[136:137] op_sel_hi:[1,0,1]
	v_cvt_pk_bf16_f32 v122, v124, v125
	v_cvt_pk_bf16_f32 v123, v126, v127
	v_cvt_pk_bf16_f32 v124, v120, v121
	v_cvt_pk_bf16_f32 v125, v196, v197
	v_lshl_add_u64 v[120:121], v[154:155], 1, v[194:195]
	v_pk_fma_f32 v[118:119], v[118:119], v[190:191], v[142:143] op_sel_hi:[1,0,1]
	v_pk_fma_f32 v[116:117], v[116:117], v[190:191], v[140:141] op_sel_hi:[1,0,1]
	v_pk_fma_f32 v[114:115], v[114:115], v[190:191], v[138:139] op_sel_hi:[1,0,1]
	v_max_f32_e32 v112, 0, v112
	v_max_f32_e32 v113, 0, v113
	global_store_dwordx4 v[120:121], v[122:125], off
	v_max_f32_e32 v116, 0, v116
	v_max_f32_e32 v117, 0, v117
	v_pk_mul_f32 v[122:123], v[112:113], v[112:113]
	v_max_f32_e32 v112, 0, v118
	v_max_f32_e32 v114, 0, v114
	v_max_f32_e32 v113, 0, v119
	v_max_f32_e32 v115, 0, v115
	v_pk_mul_f32 v[116:117], v[116:117], v[116:117]
	v_pk_mul_f32 v[118:119], v[112:113], v[112:113]
; DI unsigned cvtpk(float lo, float hi) { f32x2 v = {lo, hi}; bf16x2_t b = __builtin_convertvector(v, bf16x2_t); return __builtin_bit_cast(unsigned, b); }
;     DI void operator()(const f32x4 (&acc)[2][2][4][2], const pg8::Unit& u, int wr, int wc, int fr, int fq) const {
;     ...
;         for (int bj = 0; bj < 2; ++bj) { const f32x4 b0 = bb[bj][0], b1 = bb[bj][1];
; #pragma unroll
;             for (int ai = 0; ai < 2; ++ai)
; #pragma unroll
;                 for (int m = 0; m < 4; ++m) {
;                     f32x4 v0 = acc[ai][bj][m][0] * rstd[ai][m] + b0, v1 = acc[ai][bj][m][1] * rstd[ai][m] + b1;
;                     if (ACT == 1) {
; #pragma unroll
;                         for (int e = 0; e < 4; ++e) { float a = fmaxf(v0[e], 0.f), b = fmaxf(v1[e], 0.f); v0[e] = a * a; v1[e] = b * b; } }
;                     u32x4 w; w.x = cvtpk(v0[0], v0[1]); w.y = cvtpk(v0[2], v0[3]); w.z = cvtpk(v1[0], v1[1]); w.w = cvtpk(v1[2], v1[3]);
;                     *(u32x4*)(Ou + (wr * 64 + fr + ai * 128 + m * 16) * ldc + wc * 32 + 8 * fq + bj * 128) = w; } }
	v_pk_mul_f32 v[124:125], v[114:115], v[114:115]
	v_pk_fma_f32 v[104:105], v[104:105], v[188:189], v[136:137] op_sel_hi:[1,0,1]
	v_cvt_pk_bf16_f32 v112, v116, v117
	v_cvt_pk_bf16_f32 v113, v118, v119
	v_cvt_pk_bf16_f32 v114, v122, v123
	v_cvt_pk_bf16_f32 v115, v124, v125
	v_lshl_add_u64 v[116:117], v[194:195], 0, v[170:171]
	v_pk_fma_f32 v[110:111], v[110:111], v[188:189], v[142:143] op_sel_hi:[1,0,1]
	v_pk_fma_f32 v[108:109], v[108:109], v[188:189], v[140:141] op_sel_hi:[1,0,1]
	v_pk_fma_f32 v[106:107], v[106:107], v[188:189], v[138:139] op_sel_hi:[1,0,1]
	v_max_f32_e32 v104, 0, v104
	v_max_f32_e32 v105, 0, v105
	global_store_dwordx4 v[116:117], v[112:115], off
	v_max_f32_e32 v108, 0, v108
	v_max_f32_e32 v109, 0, v109
	v_pk_mul_f32 v[112:113], v[104:105], v[104:105]
	v_max_f32_e32 v104, 0, v110
	v_max_f32_e32 v106, 0, v106
	v_max_f32_e32 v105, 0, v111
	v_max_f32_e32 v107, 0, v107
	v_pk_mul_f32 v[108:109], v[108:109], v[108:109]
	v_pk_mul_f32 v[110:111], v[104:105], v[104:105]
	v_pk_mul_f32 v[114:115], v[106:107], v[106:107]
	v_pk_fma_f32 v[96:97], v[96:97], v[186:187], v[136:137] op_sel_hi:[1,0,1]
	v_cvt_pk_bf16_f32 v104, v108, v109
	v_cvt_pk_bf16_f32 v105, v110, v111
	v_cvt_pk_bf16_f32 v106, v112, v113
	v_cvt_pk_bf16_f32 v107, v114, v115
	v_lshl_add_u64 v[108:109], v[194:195], 0, v[172:173]
	v_pk_fma_f32 v[102:103], v[102:103], v[186:187], v[142:143] op_sel_hi:[1,0,1]
	v_pk_fma_f32 v[100:101], v[100:101], v[186:187], v[140:141] op_sel_hi:[1,0,1]
	v_pk_fma_f32 v[98:99], v[98:99], v[186:187], v[138:139] op_sel_hi:[1,0,1]
	v_max_f32_e32 v96, 0, v96
	v_max_f32_e32 v97, 0, v97
	global_store_dwordx4 v[108:109], v[104:107], off
	v_max_f32_e32 v100, 0, v100
	v_max_f32_e32 v101, 0, v101
	v_pk_mul_f32 v[104:105], v[96:97], v[96:97]
	v_max_f32_e32 v96, 0, v102
	v_max_f32_e32 v98, 0, v98
	v_max_f32_e32 v97, 0, v103
	v_max_f32_e32 v99, 0, v99
	v_pk_mul_f32 v[100:101], v[100:101], v[100:101]
	v_pk_mul_f32 v[102:103], v[96:97], v[96:97]
	v_pk_mul_f32 v[106:107], v[98:99], v[98:99]
	v_pk_fma_f32 v[94:95], v[94:95], v[184:185], v[142:143] op_sel_hi:[1,0,1]
	v_pk_fma_f32 v[92:93], v[92:93], v[184:185], v[140:141] op_sel_hi:[1,0,1]
	v_pk_fma_f32 v[90:91], v[90:91], v[184:185], v[138:139] op_sel_hi:[1,0,1]
	v_pk_fma_f32 v[88:89], v[88:89], v[184:185], v[136:137] op_sel_hi:[1,0,1]
	v_cvt_pk_bf16_f32 v96, v100, v101
	v_cvt_pk_bf16_f32 v97, v102, v103
	v_cvt_pk_bf16_f32 v98, v104, v105
	v_cvt_pk_bf16_f32 v99, v106, v107
	v_lshl_add_u64 v[100:101], v[194:195], 0, v[174:175]
	v_max_f32_e32 v92, 0, v92
	v_max_f32_e32 v88, 0, v88
	v_max_f32_e32 v93, 0, v93
	v_max_f32_e32 v89, 0, v89
	v_max_f32_e32 v94, 0, v94
	v_max_f32_e32 v90, 0, v90
	v_max_f32_e32 v95, 0, v95
	v_max_f32_e32 v91, 0, v91
	global_store_dwordx4 v[100:101], v[96:99], off
	v_pk_mul_f32 v[92:93], v[92:93], v[92:93]
	v_pk_mul_f32 v[88:89], v[88:89], v[88:89]
	v_pk_mul_f32 v[94:95], v[94:95], v[94:95]
	v_pk_mul_f32 v[96:97], v[90:91], v[90:91]
	v_pk_fma_f32 v[86:87], v[86:87], v[182:183], v[142:143] op_sel_hi:[1,0,1]
	v_pk_fma_f32 v[84:85], v[84:85], v[182:183], v[140:141] op_sel_hi:[1,0,1]
	v_pk_fma_f32 v[82:83], v[82:83], v[182:183], v[138:139] op_sel_hi:[1,0,1]
	v_pk_fma_f32 v[80:81], v[80:81], v[182:183], v[136:137] op_sel_hi:[1,0,1]
	v_cvt_pk_bf16_f32 v90, v92, v93
	v_cvt_pk_bf16_f32 v91, v94, v95
	v_cvt_pk_bf16_f32 v92, v88, v89
	v_cvt_pk_bf16_f32 v93, v96, v97
	v_lshl_add_u64 v[88:89], v[156:157], 1, v[194:195]
	v_max_f32_e32 v84, 0, v84
	v_max_f32_e32 v80, 0, v80
	v_max_f32_e32 v85, 0, v85
	v_max_f32_e32 v81, 0, v81
	v_max_f32_e32 v86, 0, v86
	v_max_f32_e32 v82, 0, v82
	v_max_f32_e32 v87, 0, v87
	v_max_f32_e32 v83, 0, v83
	global_store_dwordx4 v[88:89], v[90:93], off
	v_pk_mul_f32 v[84:85], v[84:85], v[84:85]
	v_pk_mul_f32 v[80:81], v[80:81], v[80:81]
	v_pk_mul_f32 v[86:87], v[86:87], v[86:87]
	v_pk_mul_f32 v[90:91], v[82:83], v[82:83]
	v_pk_fma_f32 v[78:79], v[78:79], v[180:181], v[142:143] op_sel_hi:[1,0,1]
	v_pk_fma_f32 v[76:77], v[76:77], v[180:181], v[140:141] op_sel_hi:[1,0,1]
	v_pk_fma_f32 v[74:75], v[74:75], v[180:181], v[138:139] op_sel_hi:[1,0,1]
	v_pk_fma_f32 v[72:73], v[72:73], v[180:181], v[136:137] op_sel_hi:[1,0,1]
	v_cvt_pk_bf16_f32 v82, v84, v85
	v_cvt_pk_bf16_f32 v83, v86, v87
	v_cvt_pk_bf16_f32 v84, v80, v81
	v_cvt_pk_bf16_f32 v85, v90, v91
	v_lshl_add_u64 v[80:81], v[158:159], 1, v[194:195]
	v_max_f32_e32 v76, 0, v76
	v_max_f32_e32 v72, 0, v72
	v_max_f32_e32 v77, 0, v77
	v_max_f32_e32 v73, 0, v73
	v_max_f32_e32 v78, 0, v78
	v_max_f32_e32 v74, 0, v74
	v_max_f32_e32 v79, 0, v79
	v_max_f32_e32 v75, 0, v75
	global_store_dwordx4 v[80:81], v[82:85], off
	v_pk_mul_f32 v[76:77], v[76:77], v[76:77]
	v_pk_mul_f32 v[72:73], v[72:73], v[72:73]
	v_pk_mul_f32 v[78:79], v[78:79], v[78:79]
	v_pk_mul_f32 v[82:83], v[74:75], v[74:75]
	v_pk_fma_f32 v[62:63], v[62:63], v[178:179], v[142:143] op_sel_hi:[1,0,1]
	v_pk_fma_f32 v[60:61], v[60:61], v[178:179], v[140:141] op_sel_hi:[1,0,1]
	v_pk_fma_f32 v[58:59], v[58:59], v[178:179], v[138:139] op_sel_hi:[1,0,1]
	v_pk_fma_f32 v[56:57], v[56:57], v[178:179], v[136:137] op_sel_hi:[1,0,1]
	v_cvt_pk_bf16_f32 v74, v76, v77
	v_cvt_pk_bf16_f32 v75, v78, v79
	v_cvt_pk_bf16_f32 v76, v72, v73
	v_cvt_pk_bf16_f32 v77, v82, v83
	v_lshl_add_u64 v[72:73], v[160:161], 1, v[194:195]
	v_max_f32_e32 v60, 0, v60
	v_max_f32_e32 v56, 0, v56
	v_max_f32_e32 v61, 0, v61
	v_max_f32_e32 v57, 0, v57
	v_max_f32_e32 v62, 0, v62
	v_max_f32_e32 v58, 0, v58
	v_max_f32_e32 v63, 0, v63
	v_max_f32_e32 v59, 0, v59
	global_store_dwordx4 v[72:73], v[74:77], off
	v_pk_mul_f32 v[60:61], v[60:61], v[60:61]
	v_pk_mul_f32 v[56:57], v[56:57], v[56:57]
	v_pk_mul_f32 v[62:63], v[62:63], v[62:63]
	v_pk_mul_f32 v[74:75], v[58:59], v[58:59]
	v_cvt_pk_bf16_f32 v58, v60, v61
	v_cvt_pk_bf16_f32 v59, v62, v63
	v_cvt_pk_bf16_f32 v60, v56, v57
	v_cvt_pk_bf16_f32 v61, v74, v75
	v_lshl_add_u64 v[56:57], v[162:163], 1, v[194:195]
	global_store_dwordx4 v[56:57], v[58:61], off
	s_waitcnt vmcnt(9)
; DI unsigned cvtpk(float lo, float hi) { f32x2 v = {lo, hi}; bf16x2_t b = __builtin_convertvector(v, bf16x2_t); return __builtin_bit_cast(unsigned, b); }
;     DI void operator()(const f32x4 (&acc)[2][2][4][2], const pg8::Unit& u, int wr, int wc, int fr, int fq) const {
;     ...
;         for (int bj = 0; bj < 2; ++bj) { const f32x4 b0 = bb[bj][0], b1 = bb[bj][1];
; #pragma unroll
;             for (int ai = 0; ai < 2; ++ai)
; #pragma unroll
;                 for (int m = 0; m < 4; ++m) {
;                     f32x4 v0 = acc[ai][bj][m][0] * rstd[ai][m] + b0, v1 = acc[ai][bj][m][1] * rstd[ai][m] + b1;
;                     if (ACT == 1) {
; #pragma unroll
;                         for (int e = 0; e < 4; ++e) { float a = fmaxf(v0[e], 0.f), b = fmaxf(v1[e], 0.f); v0[e] = a * a; v1[e] = b * b; } }
;                     u32x4 w; w.x = cvtpk(v0[0], v0[1]); w.y = cvtpk(v0[2], v0[3]); w.z = cvtpk(v1[0], v1[1]); w.w = cvtpk(v1[2], v1[3]);
;                     *(u32x4*)(Ou + (wr * 64 + fr + ai * 128 + m * 16) * ldc + wc * 32 + 8 * fq + bj * 128) = w; } }
	v_pk_fma_f32 v[66:67], v[66:67], v[192:193], v[130:131] op_sel_hi:[1,0,1]
	v_pk_fma_f32 v[64:65], v[64:65], v[192:193], v[128:129] op_sel_hi:[1,0,1]
	s_waitcnt vmcnt(8)
	v_pk_fma_f32 v[58:59], v[70:71], v[192:193], v[134:135] op_sel_hi:[1,0,1]
	v_pk_fma_f32 v[60:61], v[68:69], v[192:193], v[132:133] op_sel_hi:[1,0,1]
	v_max_f32_e32 v64, 0, v64
	v_max_f32_e32 v60, 0, v60
	v_max_f32_e32 v61, 0, v61
	v_max_f32_e32 v65, 0, v65
	v_max_f32_e32 v58, 0, v58
	v_max_f32_e32 v66, 0, v66
	v_max_f32_e32 v59, 0, v59
	v_max_f32_e32 v67, 0, v67
	v_pk_mul_f32 v[60:61], v[60:61], v[60:61]
	v_pk_mul_f32 v[64:65], v[64:65], v[64:65]
	v_pk_mul_f32 v[68:69], v[58:59], v[58:59]
	v_pk_mul_f32 v[66:67], v[66:67], v[66:67]
	v_pk_fma_f32 v[48:49], v[48:49], v[190:191], v[128:129] op_sel_hi:[1,0,1]
	v_cvt_pk_bf16_f32 v58, v60, v61
	v_cvt_pk_bf16_f32 v59, v68, v69
	v_cvt_pk_bf16_f32 v60, v64, v65
	v_cvt_pk_bf16_f32 v61, v66, v67
	v_pk_fma_f32 v[54:55], v[54:55], v[190:191], v[134:135] op_sel_hi:[1,0,1]
	v_pk_fma_f32 v[52:53], v[52:53], v[190:191], v[132:133] op_sel_hi:[1,0,1]
	v_pk_fma_f32 v[50:51], v[50:51], v[190:191], v[130:131] op_sel_hi:[1,0,1]
	v_max_f32_e32 v48, 0, v48
	v_max_f32_e32 v49, 0, v49
	global_store_dwordx4 v[120:121], v[58:61], off offset:256
	v_max_f32_e32 v52, 0, v52
	v_max_f32_e32 v53, 0, v53
	v_pk_mul_f32 v[58:59], v[48:49], v[48:49]
	v_max_f32_e32 v48, 0, v54
	v_max_f32_e32 v50, 0, v50
	v_max_f32_e32 v49, 0, v55
	v_max_f32_e32 v51, 0, v51
	v_lshl_add_u64 v[62:63], v[194:195], 0, s[4:5]
	v_pk_mul_f32 v[52:53], v[52:53], v[52:53]
	v_pk_mul_f32 v[54:55], v[48:49], v[48:49]
	v_pk_mul_f32 v[60:61], v[50:51], v[50:51]
	v_pk_fma_f32 v[40:41], v[40:41], v[188:189], v[128:129] op_sel_hi:[1,0,1]
	v_cvt_pk_bf16_f32 v48, v52, v53
	v_cvt_pk_bf16_f32 v49, v54, v55
	v_cvt_pk_bf16_f32 v50, v58, v59
	v_cvt_pk_bf16_f32 v51, v60, v61
	v_lshl_add_u64 v[52:53], v[62:63], 0, v[170:171]
	v_pk_fma_f32 v[46:47], v[46:47], v[188:189], v[134:135] op_sel_hi:[1,0,1]
	v_pk_fma_f32 v[44:45], v[44:45], v[188:189], v[132:133] op_sel_hi:[1,0,1]
	v_pk_fma_f32 v[42:43], v[42:43], v[188:189], v[130:131] op_sel_hi:[1,0,1]
	v_max_f32_e32 v40, 0, v40
	v_max_f32_e32 v41, 0, v41
	global_store_dwordx4 v[52:53], v[48:51], off
	v_max_f32_e32 v44, 0, v44
	v_max_f32_e32 v45, 0, v45
	v_pk_mul_f32 v[48:49], v[40:41], v[40:41]
	v_max_f32_e32 v40, 0, v46
	v_max_f32_e32 v42, 0, v42
	v_max_f32_e32 v41, 0, v47
	v_max_f32_e32 v43, 0, v43
	v_pk_mul_f32 v[44:45], v[44:45], v[44:45]
	v_pk_mul_f32 v[46:47], v[40:41], v[40:41]
	v_pk_mul_f32 v[50:51], v[42:43], v[42:43]
	v_pk_fma_f32 v[32:33], v[32:33], v[186:187], v[128:129] op_sel_hi:[1,0,1]
	v_cvt_pk_bf16_f32 v40, v44, v45
	v_cvt_pk_bf16_f32 v41, v46, v47
	v_cvt_pk_bf16_f32 v42, v48, v49
	v_cvt_pk_bf16_f32 v43, v50, v51
	v_lshl_add_u64 v[44:45], v[62:63], 0, v[172:173]
	v_pk_fma_f32 v[38:39], v[38:39], v[186:187], v[134:135] op_sel_hi:[1,0,1]
	v_pk_fma_f32 v[36:37], v[36:37], v[186:187], v[132:133] op_sel_hi:[1,0,1]
	v_pk_fma_f32 v[34:35], v[34:35], v[186:187], v[130:131] op_sel_hi:[1,0,1]
	v_max_f32_e32 v32, 0, v32
	v_max_f32_e32 v33, 0, v33
	global_store_dwordx4 v[44:45], v[40:43], off
	v_max_f32_e32 v36, 0, v36
	v_max_f32_e32 v37, 0, v37
	v_pk_mul_f32 v[40:41], v[32:33], v[32:33]
	v_max_f32_e32 v32, 0, v38
	v_max_f32_e32 v34, 0, v34
	v_max_f32_e32 v33, 0, v39
	v_max_f32_e32 v35, 0, v35
	v_pk_mul_f32 v[36:37], v[36:37], v[36:37]
	v_pk_mul_f32 v[38:39], v[32:33], v[32:33]
	v_pk_mul_f32 v[42:43], v[34:35], v[34:35]
	v_pk_fma_f32 v[24:25], v[24:25], v[184:185], v[128:129] op_sel_hi:[1,0,1]
	v_cvt_pk_bf16_f32 v32, v36, v37
	v_cvt_pk_bf16_f32 v33, v38, v39
	v_cvt_pk_bf16_f32 v34, v40, v41
; DI unsigned cvtpk(float lo, float hi) { f32x2 v = {lo, hi}; bf16x2_t b = __builtin_convertvector(v, bf16x2_t); return __builtin_bit_cast(unsigned, b); }
;     DI void operator()(const f32x4 (&acc)[2][2][4][2], const pg8::Unit& u, int wr, int wc, int fr, int fq) const {
;     ...
;         for (int bj = 0; bj < 2; ++bj) { const f32x4 b0 = bb[bj][0], b1 = bb[bj][1];
; #pragma unroll
;             for (int ai = 0; ai < 2; ++ai)
; #pragma unroll
;                 for (int m = 0; m < 4; ++m) {
;                     f32x4 v0 = acc[ai][bj][m][0] * rstd[ai][m] + b0, v1 = acc[ai][bj][m][1] * rstd[ai][m] + b1;
;                     if (ACT == 1) {
; #pragma unroll
;                         for (int e = 0; e < 4; ++e) { float a = fmaxf(v0[e], 0.f), b = fmaxf(v1[e], 0.f); v0[e] = a * a; v1[e] = b * b; } }
;                     u32x4 w; w.x = cvtpk(v0[0], v0[1]); w.y = cvtpk(v0[2], v0[3]); w.z = cvtpk(v1[0], v1[1]); w.w = cvtpk(v1[2], v1[3]);
;                     *(u32x4*)(Ou + (wr * 64 + fr + ai * 128 + m * 16) * ldc + wc * 32 + 8 * fq + bj * 128) = w; } }
	v_cvt_pk_bf16_f32 v35, v42, v43
	v_lshl_add_u64 v[36:37], v[62:63], 0, v[174:175]
	v_pk_fma_f32 v[30:31], v[30:31], v[184:185], v[134:135] op_sel_hi:[1,0,1]
	v_pk_fma_f32 v[28:29], v[28:29], v[184:185], v[132:133] op_sel_hi:[1,0,1]
	v_pk_fma_f32 v[26:27], v[26:27], v[184:185], v[130:131] op_sel_hi:[1,0,1]
	v_max_f32_e32 v24, 0, v24
	v_max_f32_e32 v25, 0, v25
	global_store_dwordx4 v[36:37], v[32:35], off
	v_max_f32_e32 v28, 0, v28
	v_max_f32_e32 v29, 0, v29
	v_pk_mul_f32 v[32:33], v[24:25], v[24:25]
	v_max_f32_e32 v24, 0, v30
	v_max_f32_e32 v26, 0, v26
	v_max_f32_e32 v25, 0, v31
	v_max_f32_e32 v27, 0, v27
	v_pk_mul_f32 v[28:29], v[28:29], v[28:29]
	v_pk_mul_f32 v[30:31], v[24:25], v[24:25]
	v_pk_mul_f32 v[34:35], v[26:27], v[26:27]
	v_pk_fma_f32 v[16:17], v[16:17], v[182:183], v[128:129] op_sel_hi:[1,0,1]
	v_cvt_pk_bf16_f32 v24, v28, v29
	v_cvt_pk_bf16_f32 v25, v30, v31
	v_cvt_pk_bf16_f32 v26, v32, v33
	v_cvt_pk_bf16_f32 v27, v34, v35
	v_pk_fma_f32 v[22:23], v[22:23], v[182:183], v[134:135] op_sel_hi:[1,0,1]
	v_pk_fma_f32 v[20:21], v[20:21], v[182:183], v[132:133] op_sel_hi:[1,0,1]
	v_pk_fma_f32 v[18:19], v[18:19], v[182:183], v[130:131] op_sel_hi:[1,0,1]
	v_max_f32_e32 v16, 0, v16
	v_max_f32_e32 v17, 0, v17
	global_store_dwordx4 v[88:89], v[24:27], off offset:256
	v_max_f32_e32 v20, 0, v20
	v_max_f32_e32 v21, 0, v21
	v_pk_mul_f32 v[24:25], v[16:17], v[16:17]
	v_max_f32_e32 v16, 0, v22
	v_max_f32_e32 v18, 0, v18
	v_max_f32_e32 v17, 0, v23
	v_max_f32_e32 v19, 0, v19
	v_pk_mul_f32 v[20:21], v[20:21], v[20:21]
	v_pk_mul_f32 v[22:23], v[16:17], v[16:17]
	v_pk_mul_f32 v[26:27], v[18:19], v[18:19]
	v_pk_fma_f32 v[8:9], v[8:9], v[180:181], v[128:129] op_sel_hi:[1,0,1]
	v_cvt_pk_bf16_f32 v16, v20, v21
	v_cvt_pk_bf16_f32 v17, v22, v23
	v_cvt_pk_bf16_f32 v18, v24, v25
	v_cvt_pk_bf16_f32 v19, v26, v27
	v_pk_fma_f32 v[14:15], v[14:15], v[180:181], v[134:135] op_sel_hi:[1,0,1]
	v_pk_fma_f32 v[12:13], v[12:13], v[180:181], v[132:133] op_sel_hi:[1,0,1]
	v_pk_fma_f32 v[10:11], v[10:11], v[180:181], v[130:131] op_sel_hi:[1,0,1]
	v_max_f32_e32 v8, 0, v8
	v_max_f32_e32 v9, 0, v9
	global_store_dwordx4 v[80:81], v[16:19], off offset:256
	v_max_f32_e32 v12, 0, v12
	v_max_f32_e32 v13, 0, v13
	v_pk_mul_f32 v[16:17], v[8:9], v[8:9]
	v_max_f32_e32 v8, 0, v14
	v_max_f32_e32 v10, 0, v10
	v_max_f32_e32 v9, 0, v15
	v_max_f32_e32 v11, 0, v11
	v_pk_mul_f32 v[12:13], v[12:13], v[12:13]
	v_pk_mul_f32 v[14:15], v[8:9], v[8:9]
	v_pk_mul_f32 v[18:19], v[10:11], v[10:11]
	v_pk_fma_f32 v[0:1], v[0:1], v[178:179], v[128:129] op_sel_hi:[1,0,1]
	v_cvt_pk_bf16_f32 v8, v12, v13
	v_cvt_pk_bf16_f32 v9, v14, v15
	v_cvt_pk_bf16_f32 v10, v16, v17
	v_cvt_pk_bf16_f32 v11, v18, v19
	v_pk_fma_f32 v[6:7], v[6:7], v[178:179], v[134:135] op_sel_hi:[1,0,1]
	v_pk_fma_f32 v[4:5], v[4:5], v[178:179], v[132:133] op_sel_hi:[1,0,1]
	v_pk_fma_f32 v[2:3], v[2:3], v[178:179], v[130:131] op_sel_hi:[1,0,1]
	v_max_f32_e32 v0, 0, v0
	v_max_f32_e32 v1, 0, v1
	global_store_dwordx4 v[72:73], v[8:11], off offset:256
	v_max_f32_e32 v4, 0, v4
	v_max_f32_e32 v5, 0, v5
	v_pk_mul_f32 v[8:9], v[0:1], v[0:1]
	v_max_f32_e32 v0, 0, v6
	v_max_f32_e32 v2, 0, v2
	v_max_f32_e32 v1, 0, v7
	v_max_f32_e32 v3, 0, v3
	v_pk_mul_f32 v[4:5], v[4:5], v[4:5]
	v_pk_mul_f32 v[6:7], v[0:1], v[0:1]
	v_pk_mul_f32 v[10:11], v[2:3], v[2:3]
	v_cvt_pk_bf16_f32 v0, v4, v5
	v_cvt_pk_bf16_f32 v1, v6, v7
	v_cvt_pk_bf16_f32 v2, v8, v9
	v_cvt_pk_bf16_f32 v3, v10, v11
	s_mov_b64 s[4:5], -1
	global_store_dwordx4 v[56:57], v[0:3], off offset:256
	s_cbranch_vccnz .LBB0_1090
	s_andn2_b64 vcc, exec, s[12:13]
	s_cbranch_vccnz .LBB0_1089
	s_barrier
	s_branch .LBB0_1089

; DI unsigned cvtpk(float lo, float hi) { f32x2 v = {lo, hi}; bf16x2_t b = __builtin_convertvector(v, bf16x2_t); return __builtin_bit_cast(unsigned, b); }
;     DI void operator()(const f32x4 (&acc)[2][2][4][2], const pg8::Unit& u, int wr, int wc, int fr, int fq) const {
;         const int lrow0 = u.pm * 256 + wr * 64 + fr, grow0 = row_base + u.pm * 256, col0 = u.pn * 256 + wc * 32 + 8 * fq;
;         bf16* Ou = O + (size_t)(u.pm * 256) * ldc + u.pn * 256;
;         const int mrow = grow0 < NCTX ? 8 : (grow0 - NCTX) >> 12;
;         float rstd[2][4];
; #pragma unroll
;         for (int ai = 0; ai < 2; ++ai)
; #pragma unroll
;             for (int m = 0; m < 4; ++m) rstd[ai][m] = rsqrtf(rss[row_base + lrow0 + ai * 128 + m * 16] * (1.f / DM) + EPS);
;         const float* bp = bias + mrow * 4096 + col0;
;         f32x4 bb[2][2];
; #pragma unroll
;         for (int bj = 0; bj < 2; ++bj) { bb[bj][0] = *(const f32x4*)(bp + bj * 128); bb[bj][1] = *(const f32x4*)(bp + bj * 128 + 4); }
;         asm volatile("" ::: "memory");
; #pragma unroll
;         for (int bj = 0; bj < 2; ++bj) { const f32x4 b0 = bb[bj][0], b1 = bb[bj][1];
; #pragma unroll
;             for (int ai = 0; ai < 2; ++ai)
; #pragma unroll
;                 for (int m = 0; m < 4; ++m) {
;                     f32x4 v0 = acc[ai][bj][m][0] * rstd[ai][m] + b0, v1 = acc[ai][bj][m][1] * rstd[ai][m] + b1;
;                     if (ACT == 1) {
; #pragma unroll
;                         for (int e = 0; e < 4; ++e) { float a = fmaxf(v0[e], 0.f), b = fmaxf(v1[e], 0.f); v0[e] = a * a; v1[e] = b * b; } }
;                     u32x4 w; w.x = cvtpk(v0[0], v0[1]); w.y = cvtpk(v0[2], v0[3]); w.z = cvtpk(v1[0], v1[1]); w.w = cvtpk(v1[2], v1[3]);
;                     *(u32x4*)(Ou + (wr * 64 + fr + ai * 128 + m * 16) * ldc + wc * 32 + 8 * fq + bj * 128) = w; } }
.LBB0_1111:
	s_lshl_b32 s6, s46, 8
	v_add_u32_e32 v128, s6, v183
	v_ashrrev_i32_e32 v129, 31, v128
	v_lshl_add_u64 v[128:129], v[128:129], 2, s[86:87]
	global_load_dword v200, v[128:129], off
	global_load_dword v201, v[128:129], off offset:64
	global_load_dword v202, v[128:129], off offset:128
	global_load_dword v203, v[128:129], off offset:192
	global_load_dword v204, v[128:129], off offset:512
	global_load_dword v205, v[128:129], off offset:576
	global_load_dword v206, v[128:129], off offset:640
	global_load_dword v207, v[128:129], off offset:704
	s_lshl_b32 s4, s31, 8
	s_ashr_i32 s7, s6, 31
	s_ashr_i32 s5, s4, 31
	s_lshl_b64 s[8:9], s[6:7], 13
	s_add_u32 s8, s33, s8
	s_addc_u32 s9, s59, s9
	s_and_b32 s7, s6, 0xfffff000
	s_cmp_lt_u32 s6, 0x7ffff800
	s_cselect_b32 s6, s7, 0x8000
	s_ashr_i32 s7, s6, 31
	s_lshl_b64 s[6:7], s[6:7], 2
	v_readlane_b32 s22, v253, 61
	v_readlane_b32 s23, v253, 62
	s_add_u32 s6, s22, s6
	s_addc_u32 s7, s23, s7
	s_waitcnt vmcnt(7)
	v_fmamk_f32 v200, v200, 0x3a800000, v187
	v_cmp_gt_f32_e32 vcc, s57, v200
	v_mul_f32_e32 v131, 0x4b800000, v200
	s_nop 0
	v_cndmask_b32_e32 v200, v200, v131, vcc
	v_rsq_f32_e32 v200, v200
	s_nop 0
	v_mul_f32_e32 v131, 0x45800000, v200
	v_cndmask_b32_e32 v192, v200, v131, vcc
	s_waitcnt vmcnt(6)
	v_fmamk_f32 v201, v201, 0x3a800000, v187
	v_cmp_gt_f32_e32 vcc, s57, v201
	v_mul_f32_e32 v131, 0x4b800000, v201
	s_nop 0
	v_cndmask_b32_e32 v201, v201, v131, vcc
	v_rsq_f32_e32 v201, v201
	s_nop 0
	v_mul_f32_e32 v131, 0x45800000, v201
	v_cndmask_b32_e32 v190, v201, v131, vcc
	s_waitcnt vmcnt(5)
	v_fmamk_f32 v202, v202, 0x3a800000, v187
	v_cmp_gt_f32_e32 vcc, s57, v202
	v_mul_f32_e32 v131, 0x4b800000, v202
	s_nop 0
	v_cndmask_b32_e32 v202, v202, v131, vcc
	v_rsq_f32_e32 v202, v202
	s_nop 0
	v_mul_f32_e32 v131, 0x45800000, v202
	v_cndmask_b32_e32 v188, v202, v131, vcc
	s_waitcnt vmcnt(4)
	v_fmamk_f32 v203, v203, 0x3a800000, v187
	v_cmp_gt_f32_e32 vcc, s57, v203
	v_mul_f32_e32 v131, 0x4b800000, v203
	s_nop 0
	v_cndmask_b32_e32 v203, v203, v131, vcc
	v_rsq_f32_e32 v203, v203
	s_nop 0
	v_mul_f32_e32 v131, 0x45800000, v203
	v_cndmask_b32_e32 v186, v203, v131, vcc
	s_waitcnt vmcnt(3)
	v_fmamk_f32 v204, v204, 0x3a800000, v187
	v_cmp_gt_f32_e32 vcc, s57, v204
	v_mul_f32_e32 v131, 0x4b800000, v204
	s_nop 0
	v_cndmask_b32_e32 v204, v204, v131, vcc
	v_rsq_f32_e32 v204, v204
	s_nop 0
	v_mul_f32_e32 v131, 0x45800000, v204
	v_cndmask_b32_e32 v184, v204, v131, vcc
	s_waitcnt vmcnt(2)
	v_fmamk_f32 v205, v205, 0x3a800000, v187
	v_cmp_gt_f32_e32 vcc, s57, v205
	v_mul_f32_e32 v131, 0x4b800000, v205
	s_nop 0
	v_cndmask_b32_e32 v205, v205, v131, vcc
	v_rsq_f32_e32 v205, v205
	s_nop 0
	v_mul_f32_e32 v131, 0x45800000, v205
	v_cndmask_b32_e32 v182, v205, v131, vcc
	s_waitcnt vmcnt(1)
	v_fmamk_f32 v206, v206, 0x3a800000, v187
	v_cmp_gt_f32_e32 vcc, s57, v206
	v_mul_f32_e32 v131, 0x4b800000, v206
	s_waitcnt vmcnt(0)
	v_fmamk_f32 v207, v207, 0x3a800000, v187
	v_cndmask_b32_e32 v206, v206, v131, vcc
	v_rsq_f32_e32 v206, v206
	v_mul_f32_e32 v129, 0x4b800000, v207
	v_mul_f32_e32 v131, 0x45800000, v206
	v_cndmask_b32_e32 v180, v206, v131, vcc
	v_cmp_gt_f32_e32 vcc, s57, v207
	s_nop 1
	v_cndmask_b32_e32 v207, v207, v129, vcc
	v_rsq_f32_e32 v207, v207
	s_nop 0
	v_mul_f32_e32 v129, 0x45800000, v207
	v_cndmask_b32_e32 v178, v207, v129, vcc
	v_or_b32_e32 v128, s4, v181
	v_ashrrev_i32_e32 v129, 31, v128
	v_lshl_add_u64 v[132:133], v[128:129], 2, s[6:7]
	global_load_dwordx4 v[136:139], v[132:133], off offset:16
	global_load_dwordx4 v[140:143], v[132:133], off
	global_load_dwordx4 v[128:131], v[132:133], off offset:528
	s_nop 0
	global_load_dwordx4 v[132:135], v[132:133], off offset:512
	s_lshl_b64 s[4:5], s[4:5], 1
	s_add_u32 s4, s8, s4
	s_addc_u32 s5, s9, s5
	s_add_u32 s4, s4, s60
	s_addc_u32 s5, s5, 0
	v_lshl_add_u64 v[194:195], s[4:5], 0, v[152:153]
	s_mov_b64 s[4:5], 0x100
	s_andn2_b64 vcc, exec, s[36:37]
	s_waitcnt vmcnt(3)
	v_pk_fma_f32 v[122:123], v[122:123], v[192:193], v[138:139] op_sel_hi:[1,0,1]
	s_waitcnt vmcnt(2)
	v_pk_fma_f32 v[126:127], v[126:127], v[192:193], v[142:143] op_sel_hi:[1,0,1]
	v_pk_fma_f32 v[124:125], v[124:125], v[192:193], v[140:141] op_sel_hi:[1,0,1]
	v_pk_fma_f32 v[120:121], v[120:121], v[192:193], v[136:137] op_sel_hi:[1,0,1]
	v_max_f32_e32 v124, 0, v124
	v_max_f32_e32 v120, 0, v120
	v_max_f32_e32 v125, 0, v125
	v_max_f32_e32 v121, 0, v121
	v_max_f32_e32 v126, 0, v126
	v_max_f32_e32 v122, 0, v122
	v_max_f32_e32 v127, 0, v127
	v_max_f32_e32 v123, 0, v123
	v_pk_mul_f32 v[124:125], v[124:125], v[124:125]
	v_pk_mul_f32 v[120:121], v[120:121], v[120:121]
	v_pk_mul_f32 v[126:127], v[126:127], v[126:127]
	v_pk_mul_f32 v[196:197], v[122:123], v[122:123]
	v_pk_fma_f32 v[112:113], v[112:113], v[190:191], v[136:137] op_sel_hi:[1,0,1]
	v_cvt_pk_bf16_f32 v122, v124, v125
	v_cvt_pk_bf16_f32 v123, v126, v127
	v_cvt_pk_bf16_f32 v124, v120, v121
	v_cvt_pk_bf16_f32 v125, v196, v197
	v_lshl_add_u64 v[120:121], v[154:155], 1, v[194:195]
	v_pk_fma_f32 v[118:119], v[118:119], v[190:191], v[142:143] op_sel_hi:[1,0,1]
	v_pk_fma_f32 v[116:117], v[116:117], v[190:191], v[140:141] op_sel_hi:[1,0,1]
	v_pk_fma_f32 v[114:115], v[114:115], v[190:191], v[138:139] op_sel_hi:[1,0,1]
	v_max_f32_e32 v112, 0, v112
	v_max_f32_e32 v113, 0, v113
	global_store_dwordx4 v[120:121], v[122:125], off
	v_max_f32_e32 v116, 0, v116
	v_max_f32_e32 v117, 0, v117
	v_pk_mul_f32 v[122:123], v[112:113], v[112:113]
	v_max_f32_e32 v112, 0, v118
	v_max_f32_e32 v114, 0, v114
	v_max_f32_e32 v113, 0, v119
	v_max_f32_e32 v115, 0, v115
	v_pk_mul_f32 v[116:117], v[116:117], v[116:117]
	v_pk_mul_f32 v[118:119], v[112:113], v[112:113]
	v_pk_mul_f32 v[124:125], v[114:115], v[114:115]
; DI unsigned cvtpk(float lo, float hi) { f32x2 v = {lo, hi}; bf16x2_t b = __builtin_convertvector(v, bf16x2_t); return __builtin_bit_cast(unsigned, b); }
;     DI void operator()(const f32x4 (&acc)[2][2][4][2], const pg8::Unit& u, int wr, int wc, int fr, int fq) const {
;     ...
;         for (int bj = 0; bj < 2; ++bj) { const f32x4 b0 = bb[bj][0], b1 = bb[bj][1];
; #pragma unroll
;             for (int ai = 0; ai < 2; ++ai)
; #pragma unroll
;                 for (int m = 0; m < 4; ++m) {
;                     f32x4 v0 = acc[ai][bj][m][0] * rstd[ai][m] + b0, v1 = acc[ai][bj][m][1] * rstd[ai][m] + b1;
;                     if (ACT == 1) {
; #pragma unroll
;                         for (int e = 0; e < 4; ++e) { float a = fmaxf(v0[e], 0.f), b = fmaxf(v1[e], 0.f); v0[e] = a * a; v1[e] = b * b; } }
;                     u32x4 w; w.x = cvtpk(v0[0], v0[1]); w.y = cvtpk(v0[2], v0[3]); w.z = cvtpk(v1[0], v1[1]); w.w = cvtpk(v1[2], v1[3]);
;                     *(u32x4*)(Ou + (wr * 64 + fr + ai * 128 + m * 16) * ldc + wc * 32 + 8 * fq + bj * 128) = w; } }
	v_pk_fma_f32 v[104:105], v[104:105], v[188:189], v[136:137] op_sel_hi:[1,0,1]
	v_cvt_pk_bf16_f32 v112, v116, v117
	v_cvt_pk_bf16_f32 v113, v118, v119
	v_cvt_pk_bf16_f32 v114, v122, v123
	v_cvt_pk_bf16_f32 v115, v124, v125
	v_lshl_add_u64 v[116:117], v[194:195], 0, v[170:171]
	v_pk_fma_f32 v[110:111], v[110:111], v[188:189], v[142:143] op_sel_hi:[1,0,1]
	v_pk_fma_f32 v[108:109], v[108:109], v[188:189], v[140:141] op_sel_hi:[1,0,1]
	v_pk_fma_f32 v[106:107], v[106:107], v[188:189], v[138:139] op_sel_hi:[1,0,1]
	v_max_f32_e32 v104, 0, v104
	v_max_f32_e32 v105, 0, v105
	global_store_dwordx4 v[116:117], v[112:115], off
	v_max_f32_e32 v108, 0, v108
	v_max_f32_e32 v109, 0, v109
	v_pk_mul_f32 v[112:113], v[104:105], v[104:105]
	v_max_f32_e32 v104, 0, v110
	v_max_f32_e32 v106, 0, v106
	v_max_f32_e32 v105, 0, v111
	v_max_f32_e32 v107, 0, v107
	v_pk_mul_f32 v[108:109], v[108:109], v[108:109]
	v_pk_mul_f32 v[110:111], v[104:105], v[104:105]
	v_pk_mul_f32 v[114:115], v[106:107], v[106:107]
	v_pk_fma_f32 v[96:97], v[96:97], v[186:187], v[136:137] op_sel_hi:[1,0,1]
	v_cvt_pk_bf16_f32 v104, v108, v109
	v_cvt_pk_bf16_f32 v105, v110, v111
	v_cvt_pk_bf16_f32 v106, v112, v113
	v_cvt_pk_bf16_f32 v107, v114, v115
	v_lshl_add_u64 v[108:109], v[194:195], 0, v[172:173]
	v_pk_fma_f32 v[102:103], v[102:103], v[186:187], v[142:143] op_sel_hi:[1,0,1]
	v_pk_fma_f32 v[100:101], v[100:101], v[186:187], v[140:141] op_sel_hi:[1,0,1]
	v_pk_fma_f32 v[98:99], v[98:99], v[186:187], v[138:139] op_sel_hi:[1,0,1]
	v_max_f32_e32 v96, 0, v96
	v_max_f32_e32 v97, 0, v97
	global_store_dwordx4 v[108:109], v[104:107], off
	v_max_f32_e32 v100, 0, v100
	v_max_f32_e32 v101, 0, v101
	v_pk_mul_f32 v[104:105], v[96:97], v[96:97]
	v_max_f32_e32 v96, 0, v102
	v_max_f32_e32 v98, 0, v98
	v_max_f32_e32 v97, 0, v103
	v_max_f32_e32 v99, 0, v99
	v_pk_mul_f32 v[100:101], v[100:101], v[100:101]
	v_pk_mul_f32 v[102:103], v[96:97], v[96:97]
	v_pk_mul_f32 v[106:107], v[98:99], v[98:99]
	v_pk_fma_f32 v[94:95], v[94:95], v[184:185], v[142:143] op_sel_hi:[1,0,1]
	v_pk_fma_f32 v[92:93], v[92:93], v[184:185], v[140:141] op_sel_hi:[1,0,1]
	v_pk_fma_f32 v[90:91], v[90:91], v[184:185], v[138:139] op_sel_hi:[1,0,1]
	v_pk_fma_f32 v[88:89], v[88:89], v[184:185], v[136:137] op_sel_hi:[1,0,1]
	v_cvt_pk_bf16_f32 v96, v100, v101
	v_cvt_pk_bf16_f32 v97, v102, v103
	v_cvt_pk_bf16_f32 v98, v104, v105
	v_cvt_pk_bf16_f32 v99, v106, v107
	v_lshl_add_u64 v[100:101], v[194:195], 0, v[174:175]
	v_max_f32_e32 v92, 0, v92
	v_max_f32_e32 v88, 0, v88
	v_max_f32_e32 v93, 0, v93
	v_max_f32_e32 v89, 0, v89
	v_max_f32_e32 v94, 0, v94
	v_max_f32_e32 v90, 0, v90
	v_max_f32_e32 v95, 0, v95
	v_max_f32_e32 v91, 0, v91
	global_store_dwordx4 v[100:101], v[96:99], off
	v_pk_mul_f32 v[92:93], v[92:93], v[92:93]
	v_pk_mul_f32 v[88:89], v[88:89], v[88:89]
	v_pk_mul_f32 v[94:95], v[94:95], v[94:95]
	v_pk_mul_f32 v[96:97], v[90:91], v[90:91]
	v_pk_fma_f32 v[86:87], v[86:87], v[182:183], v[142:143] op_sel_hi:[1,0,1]
	v_pk_fma_f32 v[84:85], v[84:85], v[182:183], v[140:141] op_sel_hi:[1,0,1]
	v_pk_fma_f32 v[82:83], v[82:83], v[182:183], v[138:139] op_sel_hi:[1,0,1]
	v_pk_fma_f32 v[80:81], v[80:81], v[182:183], v[136:137] op_sel_hi:[1,0,1]
	v_cvt_pk_bf16_f32 v90, v92, v93
	v_cvt_pk_bf16_f32 v91, v94, v95
	v_cvt_pk_bf16_f32 v92, v88, v89
	v_cvt_pk_bf16_f32 v93, v96, v97
	v_lshl_add_u64 v[88:89], v[156:157], 1, v[194:195]
	v_max_f32_e32 v84, 0, v84
	v_max_f32_e32 v80, 0, v80
	v_max_f32_e32 v85, 0, v85
	v_max_f32_e32 v81, 0, v81
	v_max_f32_e32 v86, 0, v86
	v_max_f32_e32 v82, 0, v82
	v_max_f32_e32 v87, 0, v87
	v_max_f32_e32 v83, 0, v83
	global_store_dwordx4 v[88:89], v[90:93], off
	v_pk_mul_f32 v[84:85], v[84:85], v[84:85]
	v_pk_mul_f32 v[80:81], v[80:81], v[80:81]
	v_pk_mul_f32 v[86:87], v[86:87], v[86:87]
	v_pk_mul_f32 v[90:91], v[82:83], v[82:83]
	v_pk_fma_f32 v[78:79], v[78:79], v[180:181], v[142:143] op_sel_hi:[1,0,1]
	v_pk_fma_f32 v[76:77], v[76:77], v[180:181], v[140:141] op_sel_hi:[1,0,1]
	v_pk_fma_f32 v[74:75], v[74:75], v[180:181], v[138:139] op_sel_hi:[1,0,1]
	v_pk_fma_f32 v[72:73], v[72:73], v[180:181], v[136:137] op_sel_hi:[1,0,1]
	v_cvt_pk_bf16_f32 v82, v84, v85
	v_cvt_pk_bf16_f32 v83, v86, v87
	v_cvt_pk_bf16_f32 v84, v80, v81
	v_cvt_pk_bf16_f32 v85, v90, v91
	v_lshl_add_u64 v[80:81], v[158:159], 1, v[194:195]
	v_max_f32_e32 v76, 0, v76
	v_max_f32_e32 v72, 0, v72
	v_max_f32_e32 v77, 0, v77
	v_max_f32_e32 v73, 0, v73
	v_max_f32_e32 v78, 0, v78
	v_max_f32_e32 v74, 0, v74
	v_max_f32_e32 v79, 0, v79
	v_max_f32_e32 v75, 0, v75
	global_store_dwordx4 v[80:81], v[82:85], off
	v_pk_mul_f32 v[76:77], v[76:77], v[76:77]
	v_pk_mul_f32 v[72:73], v[72:73], v[72:73]
	v_pk_mul_f32 v[78:79], v[78:79], v[78:79]
	v_pk_mul_f32 v[82:83], v[74:75], v[74:75]
	v_pk_fma_f32 v[62:63], v[62:63], v[178:179], v[142:143] op_sel_hi:[1,0,1]
	v_pk_fma_f32 v[60:61], v[60:61], v[178:179], v[140:141] op_sel_hi:[1,0,1]
	v_pk_fma_f32 v[58:59], v[58:59], v[178:179], v[138:139] op_sel_hi:[1,0,1]
	v_pk_fma_f32 v[56:57], v[56:57], v[178:179], v[136:137] op_sel_hi:[1,0,1]
	v_cvt_pk_bf16_f32 v74, v76, v77
	v_cvt_pk_bf16_f32 v75, v78, v79
	v_cvt_pk_bf16_f32 v76, v72, v73
	v_cvt_pk_bf16_f32 v77, v82, v83
	v_lshl_add_u64 v[72:73], v[160:161], 1, v[194:195]
	v_max_f32_e32 v60, 0, v60
	v_max_f32_e32 v56, 0, v56
	v_max_f32_e32 v61, 0, v61
	v_max_f32_e32 v57, 0, v57
	v_max_f32_e32 v62, 0, v62
	v_max_f32_e32 v58, 0, v58
	v_max_f32_e32 v63, 0, v63
	v_max_f32_e32 v59, 0, v59
	global_store_dwordx4 v[72:73], v[74:77], off
	v_pk_mul_f32 v[60:61], v[60:61], v[60:61]
	v_pk_mul_f32 v[56:57], v[56:57], v[56:57]
	v_pk_mul_f32 v[62:63], v[62:63], v[62:63]
	v_pk_mul_f32 v[74:75], v[58:59], v[58:59]
	v_cvt_pk_bf16_f32 v58, v60, v61
	v_cvt_pk_bf16_f32 v59, v62, v63
	v_cvt_pk_bf16_f32 v60, v56, v57
	v_cvt_pk_bf16_f32 v61, v74, v75
	v_lshl_add_u64 v[56:57], v[162:163], 1, v[194:195]
	global_store_dwordx4 v[56:57], v[58:61], off
	s_waitcnt vmcnt(9)
; DI unsigned cvtpk(float lo, float hi) { f32x2 v = {lo, hi}; bf16x2_t b = __builtin_convertvector(v, bf16x2_t); return __builtin_bit_cast(unsigned, b); }
;     DI void operator()(const f32x4 (&acc)[2][2][4][2], const pg8::Unit& u, int wr, int wc, int fr, int fq) const {
;     ...
;         for (int bj = 0; bj < 2; ++bj) { const f32x4 b0 = bb[bj][0], b1 = bb[bj][1];
; #pragma unroll
;             for (int ai = 0; ai < 2; ++ai)
; #pragma unroll
;                 for (int m = 0; m < 4; ++m) {
;                     f32x4 v0 = acc[ai][bj][m][0] * rstd[ai][m] + b0, v1 = acc[ai][bj][m][1] * rstd[ai][m] + b1;
;                     if (ACT == 1) {
; #pragma unroll
;                         for (int e = 0; e < 4; ++e) { float a = fmaxf(v0[e], 0.f), b = fmaxf(v1[e], 0.f); v0[e] = a * a; v1[e] = b * b; } }
;                     u32x4 w; w.x = cvtpk(v0[0], v0[1]); w.y = cvtpk(v0[2], v0[3]); w.z = cvtpk(v1[0], v1[1]); w.w = cvtpk(v1[2], v1[3]);
;                     *(u32x4*)(Ou + (wr * 64 + fr + ai * 128 + m * 16) * ldc + wc * 32 + 8 * fq + bj * 128) = w; } }
	v_pk_fma_f32 v[66:67], v[66:67], v[192:193], v[130:131] op_sel_hi:[1,0,1]
	v_pk_fma_f32 v[64:65], v[64:65], v[192:193], v[128:129] op_sel_hi:[1,0,1]
	s_waitcnt vmcnt(8)
	v_pk_fma_f32 v[58:59], v[70:71], v[192:193], v[134:135] op_sel_hi:[1,0,1]
	v_pk_fma_f32 v[60:61], v[68:69], v[192:193], v[132:133] op_sel_hi:[1,0,1]
	v_max_f32_e32 v64, 0, v64
	v_max_f32_e32 v60, 0, v60
	v_max_f32_e32 v61, 0, v61
	v_max_f32_e32 v65, 0, v65
	v_max_f32_e32 v58, 0, v58
	v_max_f32_e32 v66, 0, v66
	v_max_f32_e32 v59, 0, v59
	v_max_f32_e32 v67, 0, v67
	v_pk_mul_f32 v[60:61], v[60:61], v[60:61]
	v_pk_mul_f32 v[64:65], v[64:65], v[64:65]
	v_pk_mul_f32 v[68:69], v[58:59], v[58:59]
	v_pk_mul_f32 v[66:67], v[66:67], v[66:67]
	v_pk_fma_f32 v[48:49], v[48:49], v[190:191], v[128:129] op_sel_hi:[1,0,1]
	v_cvt_pk_bf16_f32 v58, v60, v61
	v_cvt_pk_bf16_f32 v59, v68, v69
	v_cvt_pk_bf16_f32 v60, v64, v65
	v_cvt_pk_bf16_f32 v61, v66, v67
	v_pk_fma_f32 v[54:55], v[54:55], v[190:191], v[134:135] op_sel_hi:[1,0,1]
	v_pk_fma_f32 v[52:53], v[52:53], v[190:191], v[132:133] op_sel_hi:[1,0,1]
	v_pk_fma_f32 v[50:51], v[50:51], v[190:191], v[130:131] op_sel_hi:[1,0,1]
	v_max_f32_e32 v48, 0, v48
	v_max_f32_e32 v49, 0, v49
	global_store_dwordx4 v[120:121], v[58:61], off offset:256
	v_max_f32_e32 v52, 0, v52
	v_max_f32_e32 v53, 0, v53
	v_pk_mul_f32 v[58:59], v[48:49], v[48:49]
	v_max_f32_e32 v48, 0, v54
	v_max_f32_e32 v50, 0, v50
	v_max_f32_e32 v49, 0, v55
	v_max_f32_e32 v51, 0, v51
	v_lshl_add_u64 v[62:63], v[194:195], 0, s[4:5]
	v_pk_mul_f32 v[52:53], v[52:53], v[52:53]
	v_pk_mul_f32 v[54:55], v[48:49], v[48:49]
	v_pk_mul_f32 v[60:61], v[50:51], v[50:51]
	v_pk_fma_f32 v[40:41], v[40:41], v[188:189], v[128:129] op_sel_hi:[1,0,1]
	v_cvt_pk_bf16_f32 v48, v52, v53
	v_cvt_pk_bf16_f32 v49, v54, v55
	v_cvt_pk_bf16_f32 v50, v58, v59
	v_cvt_pk_bf16_f32 v51, v60, v61
	v_lshl_add_u64 v[52:53], v[62:63], 0, v[170:171]
	v_pk_fma_f32 v[46:47], v[46:47], v[188:189], v[134:135] op_sel_hi:[1,0,1]
	v_pk_fma_f32 v[44:45], v[44:45], v[188:189], v[132:133] op_sel_hi:[1,0,1]
	v_pk_fma_f32 v[42:43], v[42:43], v[188:189], v[130:131] op_sel_hi:[1,0,1]
	v_max_f32_e32 v40, 0, v40
	v_max_f32_e32 v41, 0, v41
	global_store_dwordx4 v[52:53], v[48:51], off
	v_max_f32_e32 v44, 0, v44
	v_max_f32_e32 v45, 0, v45
	v_pk_mul_f32 v[48:49], v[40:41], v[40:41]
	v_max_f32_e32 v40, 0, v46
	v_max_f32_e32 v42, 0, v42
	v_max_f32_e32 v41, 0, v47
	v_max_f32_e32 v43, 0, v43
	v_pk_mul_f32 v[44:45], v[44:45], v[44:45]
	v_pk_mul_f32 v[46:47], v[40:41], v[40:41]
	v_pk_mul_f32 v[50:51], v[42:43], v[42:43]
	v_pk_fma_f32 v[32:33], v[32:33], v[186:187], v[128:129] op_sel_hi:[1,0,1]
	v_cvt_pk_bf16_f32 v40, v44, v45
	v_cvt_pk_bf16_f32 v41, v46, v47
	v_cvt_pk_bf16_f32 v42, v48, v49
	v_cvt_pk_bf16_f32 v43, v50, v51
	v_lshl_add_u64 v[44:45], v[62:63], 0, v[172:173]
	v_pk_fma_f32 v[38:39], v[38:39], v[186:187], v[134:135] op_sel_hi:[1,0,1]
	v_pk_fma_f32 v[36:37], v[36:37], v[186:187], v[132:133] op_sel_hi:[1,0,1]
	v_pk_fma_f32 v[34:35], v[34:35], v[186:187], v[130:131] op_sel_hi:[1,0,1]
	v_max_f32_e32 v32, 0, v32
	v_max_f32_e32 v33, 0, v33
	global_store_dwordx4 v[44:45], v[40:43], off
	v_max_f32_e32 v36, 0, v36
	v_max_f32_e32 v37, 0, v37
	v_pk_mul_f32 v[40:41], v[32:33], v[32:33]
	v_max_f32_e32 v32, 0, v38
	v_max_f32_e32 v34, 0, v34
	v_max_f32_e32 v33, 0, v39
	v_max_f32_e32 v35, 0, v35
	v_pk_mul_f32 v[36:37], v[36:37], v[36:37]
	v_pk_mul_f32 v[38:39], v[32:33], v[32:33]
	v_pk_mul_f32 v[42:43], v[34:35], v[34:35]
	v_pk_fma_f32 v[24:25], v[24:25], v[184:185], v[128:129] op_sel_hi:[1,0,1]
	v_cvt_pk_bf16_f32 v32, v36, v37
	v_cvt_pk_bf16_f32 v33, v38, v39
	v_cvt_pk_bf16_f32 v34, v40, v41
; DI unsigned cvtpk(float lo, float hi) { f32x2 v = {lo, hi}; bf16x2_t b = __builtin_convertvector(v, bf16x2_t); return __builtin_bit_cast(unsigned, b); }
;     DI void operator()(const f32x4 (&acc)[2][2][4][2], const pg8::Unit& u, int wr, int wc, int fr, int fq) const {
;     ...
;         for (int bj = 0; bj < 2; ++bj) { const f32x4 b0 = bb[bj][0], b1 = bb[bj][1];
; #pragma unroll
;             for (int ai = 0; ai < 2; ++ai)
; #pragma unroll
;                 for (int m = 0; m < 4; ++m) {
;                     f32x4 v0 = acc[ai][bj][m][0] * rstd[ai][m] + b0, v1 = acc[ai][bj][m][1] * rstd[ai][m] + b1;
;                     if (ACT == 1) {
; #pragma unroll
;                         for (int e = 0; e < 4; ++e) { float a = fmaxf(v0[e], 0.f), b = fmaxf(v1[e], 0.f); v0[e] = a * a; v1[e] = b * b; } }
;                     u32x4 w; w.x = cvtpk(v0[0], v0[1]); w.y = cvtpk(v0[2], v0[3]); w.z = cvtpk(v1[0], v1[1]); w.w = cvtpk(v1[2], v1[3]);
;                     *(u32x4*)(Ou + (wr * 64 + fr + ai * 128 + m * 16) * ldc + wc * 32 + 8 * fq + bj * 128) = w; } }
	v_cvt_pk_bf16_f32 v35, v42, v43
	v_lshl_add_u64 v[36:37], v[62:63], 0, v[174:175]
	v_pk_fma_f32 v[30:31], v[30:31], v[184:185], v[134:135] op_sel_hi:[1,0,1]
	v_pk_fma_f32 v[28:29], v[28:29], v[184:185], v[132:133] op_sel_hi:[1,0,1]
	v_pk_fma_f32 v[26:27], v[26:27], v[184:185], v[130:131] op_sel_hi:[1,0,1]
	v_max_f32_e32 v24, 0, v24
	v_max_f32_e32 v25, 0, v25
	global_store_dwordx4 v[36:37], v[32:35], off
	v_max_f32_e32 v28, 0, v28
	v_max_f32_e32 v29, 0, v29
	v_pk_mul_f32 v[32:33], v[24:25], v[24:25]
	v_max_f32_e32 v24, 0, v30
	v_max_f32_e32 v26, 0, v26
	v_max_f32_e32 v25, 0, v31
	v_max_f32_e32 v27, 0, v27
	v_pk_mul_f32 v[28:29], v[28:29], v[28:29]
	v_pk_mul_f32 v[30:31], v[24:25], v[24:25]
	v_pk_mul_f32 v[34:35], v[26:27], v[26:27]
	v_pk_fma_f32 v[16:17], v[16:17], v[182:183], v[128:129] op_sel_hi:[1,0,1]
	v_cvt_pk_bf16_f32 v24, v28, v29
	v_cvt_pk_bf16_f32 v25, v30, v31
	v_cvt_pk_bf16_f32 v26, v32, v33
	v_cvt_pk_bf16_f32 v27, v34, v35
	v_pk_fma_f32 v[22:23], v[22:23], v[182:183], v[134:135] op_sel_hi:[1,0,1]
	v_pk_fma_f32 v[20:21], v[20:21], v[182:183], v[132:133] op_sel_hi:[1,0,1]
	v_pk_fma_f32 v[18:19], v[18:19], v[182:183], v[130:131] op_sel_hi:[1,0,1]
	v_max_f32_e32 v16, 0, v16
	v_max_f32_e32 v17, 0, v17
	global_store_dwordx4 v[88:89], v[24:27], off offset:256
	v_max_f32_e32 v20, 0, v20
	v_max_f32_e32 v21, 0, v21
	v_pk_mul_f32 v[24:25], v[16:17], v[16:17]
	v_max_f32_e32 v16, 0, v22
	v_max_f32_e32 v18, 0, v18
	v_max_f32_e32 v17, 0, v23
	v_max_f32_e32 v19, 0, v19
	v_pk_mul_f32 v[20:21], v[20:21], v[20:21]
	v_pk_mul_f32 v[22:23], v[16:17], v[16:17]
	v_pk_mul_f32 v[26:27], v[18:19], v[18:19]
	v_pk_fma_f32 v[8:9], v[8:9], v[180:181], v[128:129] op_sel_hi:[1,0,1]
	v_cvt_pk_bf16_f32 v16, v20, v21
	v_cvt_pk_bf16_f32 v17, v22, v23
	v_cvt_pk_bf16_f32 v18, v24, v25
	v_cvt_pk_bf16_f32 v19, v26, v27
	v_pk_fma_f32 v[14:15], v[14:15], v[180:181], v[134:135] op_sel_hi:[1,0,1]
	v_pk_fma_f32 v[12:13], v[12:13], v[180:181], v[132:133] op_sel_hi:[1,0,1]
	v_pk_fma_f32 v[10:11], v[10:11], v[180:181], v[130:131] op_sel_hi:[1,0,1]
	v_max_f32_e32 v8, 0, v8
	v_max_f32_e32 v9, 0, v9
	global_store_dwordx4 v[80:81], v[16:19], off offset:256
	v_max_f32_e32 v12, 0, v12
	v_max_f32_e32 v13, 0, v13
	v_pk_mul_f32 v[16:17], v[8:9], v[8:9]
	v_max_f32_e32 v8, 0, v14
	v_max_f32_e32 v10, 0, v10
	v_max_f32_e32 v9, 0, v15
	v_max_f32_e32 v11, 0, v11
	v_pk_mul_f32 v[12:13], v[12:13], v[12:13]
	v_pk_mul_f32 v[14:15], v[8:9], v[8:9]
	v_pk_mul_f32 v[18:19], v[10:11], v[10:11]
	v_pk_fma_f32 v[0:1], v[0:1], v[178:179], v[128:129] op_sel_hi:[1,0,1]
	v_cvt_pk_bf16_f32 v8, v12, v13
	v_cvt_pk_bf16_f32 v9, v14, v15
	v_cvt_pk_bf16_f32 v10, v16, v17
	v_cvt_pk_bf16_f32 v11, v18, v19
	v_pk_fma_f32 v[6:7], v[6:7], v[178:179], v[134:135] op_sel_hi:[1,0,1]
	v_pk_fma_f32 v[4:5], v[4:5], v[178:179], v[132:133] op_sel_hi:[1,0,1]
	v_pk_fma_f32 v[2:3], v[2:3], v[178:179], v[130:131] op_sel_hi:[1,0,1]
	v_max_f32_e32 v0, 0, v0
	v_max_f32_e32 v1, 0, v1
	global_store_dwordx4 v[72:73], v[8:11], off offset:256
	v_max_f32_e32 v4, 0, v4
	v_max_f32_e32 v5, 0, v5
	v_pk_mul_f32 v[8:9], v[0:1], v[0:1]
	v_max_f32_e32 v0, 0, v6
	v_max_f32_e32 v2, 0, v2
	v_max_f32_e32 v1, 0, v7
	v_max_f32_e32 v3, 0, v3
	v_pk_mul_f32 v[4:5], v[4:5], v[4:5]
	v_pk_mul_f32 v[6:7], v[0:1], v[0:1]
	v_pk_mul_f32 v[10:11], v[2:3], v[2:3]
	v_cvt_pk_bf16_f32 v0, v4, v5
	v_cvt_pk_bf16_f32 v1, v6, v7
	v_cvt_pk_bf16_f32 v2, v8, v9
	v_cvt_pk_bf16_f32 v3, v10, v11
	s_mov_b64 s[4:5], -1
	global_store_dwordx4 v[56:57], v[0:3], off offset:256
	s_cbranch_vccnz .LBB0_1104
	s_andn2_b64 vcc, exec, s[10:11]
	s_cbranch_vccnz .LBB0_1103
	s_barrier
	s_branch .LBB0_1103

; DI unsigned cvtpk(float lo, float hi) { f32x2 v = {lo, hi}; bf16x2_t b = __builtin_convertvector(v, bf16x2_t); return __builtin_bit_cast(unsigned, b); }
;     DI void operator()(const f32x4 (&acc)[2][2][4][2], const pg8::Unit& u, int wr, int wc, int fr, int fq) const {
;         const int lrow0 = u.pm * 256 + wr * 64 + fr, grow0 = row_base + u.pm * 256, col0 = u.pn * 256 + wc * 32 + 8 * fq;
;         bf16* Ou = O + (size_t)(u.pm * 256) * ldc + u.pn * 256;
;         const int mrow = grow0 < NCTX ? 8 : (grow0 - NCTX) >> 12;
;         float rstd[2][4];
; #pragma unroll
;         for (int ai = 0; ai < 2; ++ai)
; #pragma unroll
;             for (int m = 0; m < 4; ++m) rstd[ai][m] = rsqrtf(rss[row_base + lrow0 + ai * 128 + m * 16] * (1.f / DM) + EPS);
;         const float* bp = bias + mrow * 4096 + col0;
;         f32x4 bb[2][2];
; #pragma unroll
;         for (int bj = 0; bj < 2; ++bj) { bb[bj][0] = *(const f32x4*)(bp + bj * 128); bb[bj][1] = *(const f32x4*)(bp + bj * 128 + 4); }
;         asm volatile("" ::: "memory");
; #pragma unroll
;         for (int bj = 0; bj < 2; ++bj) { const f32x4 b0 = bb[bj][0], b1 = bb[bj][1];
; #pragma unroll
;             for (int ai = 0; ai < 2; ++ai)
; #pragma unroll
;                 for (int m = 0; m < 4; ++m) {
;                     f32x4 v0 = acc[ai][bj][m][0] * rstd[ai][m] + b0, v1 = acc[ai][bj][m][1] * rstd[ai][m] + b1;
;                     if (ACT == 1) {
; #pragma unroll
;                         for (int e = 0; e < 4; ++e) { float a = fmaxf(v0[e], 0.f), b = fmaxf(v1[e], 0.f); v0[e] = a * a; v1[e] = b * b; } }
;                     u32x4 w; w.x = cvtpk(v0[0], v0[1]); w.y = cvtpk(v0[2], v0[3]); w.z = cvtpk(v1[0], v1[1]); w.w = cvtpk(v1[2], v1[3]);
;                     *(u32x4*)(Ou + (wr * 64 + fr + ai * 128 + m * 16) * ldc + wc * 32 + 8 * fq + bj * 128) = w; } }
.LBB0_1278:
	s_lshl_b32 s6, s63, 8
	v_add_u32_e32 v128, s6, v185
	v_ashrrev_i32_e32 v129, 31, v128
	v_lshl_add_u64 v[128:129], v[128:129], 2, s[60:61]
	global_load_dword v200, v[128:129], off
	global_load_dword v201, v[128:129], off offset:64
	global_load_dword v202, v[128:129], off offset:128
	global_load_dword v203, v[128:129], off offset:192
	global_load_dword v204, v[128:129], off offset:512
	global_load_dword v205, v[128:129], off offset:576
	global_load_dword v206, v[128:129], off offset:640
	global_load_dword v207, v[128:129], off offset:704
	s_lshl_b32 s4, s31, 8
	s_ashr_i32 s5, s4, 31
	s_mul_i32 s7, s63, 0xc0000
	s_mul_hi_i32 s8, s6, 0xc00
	s_add_u32 s9, s46, s7
	s_addc_u32 s8, s47, s8
	s_and_b32 s7, s6, 0xfffff000
	s_cmp_lt_u32 s6, 0x7ffff800
	s_cselect_b32 s6, s7, 0x8000
	s_ashr_i32 s7, s6, 31
	s_lshl_b64 s[6:7], s[6:7], 2
	s_add_u32 s6, s48, s6
	s_addc_u32 s7, s49, s7
	v_readlane_b32 s66, v254, 12
	s_waitcnt vmcnt(7)
	v_fmamk_f32 v200, v200, 0x3a800000, v189
	v_cmp_gt_f32_e32 vcc, s59, v200
	v_mul_f32_e32 v131, 0x4b800000, v200
	s_nop 0
	v_cndmask_b32_e32 v200, v200, v131, vcc
	v_rsq_f32_e32 v200, v200
	s_nop 0
	v_mul_f32_e32 v131, 0x45800000, v200
	v_cndmask_b32_e32 v178, v200, v131, vcc
	s_waitcnt vmcnt(6)
	v_fmamk_f32 v201, v201, 0x3a800000, v189
	v_cmp_gt_f32_e32 vcc, s59, v201
	v_mul_f32_e32 v131, 0x4b800000, v201
	s_nop 0
	v_cndmask_b32_e32 v201, v201, v131, vcc
	v_rsq_f32_e32 v201, v201
	s_nop 0
	v_mul_f32_e32 v131, 0x45800000, v201
	v_cndmask_b32_e32 v180, v201, v131, vcc
	s_waitcnt vmcnt(5)
	v_fmamk_f32 v202, v202, 0x3a800000, v189
	v_cmp_gt_f32_e32 vcc, s59, v202
	v_mul_f32_e32 v131, 0x4b800000, v202
	s_nop 0
	v_cndmask_b32_e32 v202, v202, v131, vcc
	v_rsq_f32_e32 v202, v202
	s_nop 0
	v_mul_f32_e32 v131, 0x45800000, v202
	v_cndmask_b32_e32 v182, v202, v131, vcc
	s_waitcnt vmcnt(4)
	v_fmamk_f32 v203, v203, 0x3a800000, v189
	v_cmp_gt_f32_e32 vcc, s59, v203
	v_mul_f32_e32 v131, 0x4b800000, v203
	s_nop 0
	v_cndmask_b32_e32 v203, v203, v131, vcc
	v_rsq_f32_e32 v203, v203
	s_nop 0
	v_mul_f32_e32 v131, 0x45800000, v203
	v_cndmask_b32_e32 v184, v203, v131, vcc
	s_waitcnt vmcnt(3)
	v_fmamk_f32 v204, v204, 0x3a800000, v189
	v_cmp_gt_f32_e32 vcc, s59, v204
	v_mul_f32_e32 v131, 0x4b800000, v204
	s_nop 0
	v_cndmask_b32_e32 v204, v204, v131, vcc
	v_rsq_f32_e32 v204, v204
	s_nop 0
	v_mul_f32_e32 v131, 0x45800000, v204
	v_cndmask_b32_e32 v186, v204, v131, vcc
	s_waitcnt vmcnt(2)
	v_fmamk_f32 v205, v205, 0x3a800000, v189
	v_cmp_gt_f32_e32 vcc, s59, v205
	v_mul_f32_e32 v131, 0x4b800000, v205
	s_nop 0
	v_cndmask_b32_e32 v205, v205, v131, vcc
	v_rsq_f32_e32 v205, v205
	s_nop 0
	v_mul_f32_e32 v131, 0x45800000, v205
	v_cndmask_b32_e32 v188, v205, v131, vcc
	s_waitcnt vmcnt(1)
	v_fmamk_f32 v206, v206, 0x3a800000, v189
	v_cmp_gt_f32_e32 vcc, s59, v206
	v_mul_f32_e32 v131, 0x4b800000, v206
	s_waitcnt vmcnt(0)
	v_fmamk_f32 v207, v207, 0x3a800000, v189
	v_cndmask_b32_e32 v206, v206, v131, vcc
	v_rsq_f32_e32 v206, v206
	v_mul_f32_e32 v129, 0x4b800000, v207
	v_mul_f32_e32 v131, 0x45800000, v206
	v_cndmask_b32_e32 v190, v206, v131, vcc
	v_cmp_gt_f32_e32 vcc, s59, v207
	s_nop 1
	v_cndmask_b32_e32 v207, v207, v129, vcc
	v_rsq_f32_e32 v207, v207
	s_nop 0
	v_mul_f32_e32 v129, 0x45800000, v207
	v_cndmask_b32_e32 v192, v207, v129, vcc
	v_or_b32_e32 v128, s4, v183
	v_ashrrev_i32_e32 v129, 31, v128
	v_lshl_add_u64 v[132:133], v[128:129], 2, s[6:7]
	global_load_dwordx4 v[136:139], v[132:133], off offset:16
	global_load_dwordx4 v[140:143], v[132:133], off
	global_load_dwordx4 v[128:131], v[132:133], off offset:528
	s_nop 0
	global_load_dwordx4 v[132:135], v[132:133], off offset:512
	s_lshl_b64 s[4:5], s[4:5], 1
	s_add_u32 s4, s9, s4
	s_addc_u32 s5, s8, s5
	s_add_u32 s4, s4, s62
	s_addc_u32 s5, s5, 0
	v_lshl_add_u64 v[194:195], s[4:5], 0, v[152:153]
	s_mov_b64 s[4:5], -1
	s_andn2_b64 vcc, exec, s[36:37]
	s_waitcnt vmcnt(3)
	v_pk_fma_f32 v[196:197], v[122:123], v[178:179], v[138:139] op_sel_hi:[1,0,1]
	s_waitcnt vmcnt(2)
	v_pk_fma_f32 v[126:127], v[126:127], v[178:179], v[142:143] op_sel_hi:[1,0,1]
	v_pk_fma_f32 v[124:125], v[124:125], v[178:179], v[140:141] op_sel_hi:[1,0,1]
	v_pk_fma_f32 v[122:123], v[120:121], v[178:179], v[136:137] op_sel_hi:[1,0,1]
	v_cvt_pk_bf16_f32 v120, v124, v125
	v_cvt_pk_bf16_f32 v121, v126, v127
	v_cvt_pk_bf16_f32 v122, v122, v123
	v_cvt_pk_bf16_f32 v123, v196, v197
	v_lshl_add_u64 v[124:125], v[154:155], 1, v[194:195]
	global_store_dwordx4 v[124:125], v[120:123], off
	v_pk_fma_f32 v[118:119], v[118:119], v[180:181], v[142:143] op_sel_hi:[1,0,1]
	v_pk_fma_f32 v[116:117], v[116:117], v[180:181], v[140:141] op_sel_hi:[1,0,1]
	v_pk_fma_f32 v[120:121], v[114:115], v[180:181], v[138:139] op_sel_hi:[1,0,1]
	v_pk_fma_f32 v[114:115], v[112:113], v[180:181], v[136:137] op_sel_hi:[1,0,1]
	v_cvt_pk_bf16_f32 v112, v116, v117
	v_cvt_pk_bf16_f32 v113, v118, v119
	v_cvt_pk_bf16_f32 v114, v114, v115
	v_cvt_pk_bf16_f32 v115, v120, v121
	v_lshl_add_u64 v[116:117], v[156:157], 1, v[194:195]
	global_store_dwordx4 v[116:117], v[112:115], off
	v_pk_fma_f32 v[110:111], v[110:111], v[182:183], v[142:143] op_sel_hi:[1,0,1]
	v_pk_fma_f32 v[108:109], v[108:109], v[182:183], v[140:141] op_sel_hi:[1,0,1]
	v_pk_fma_f32 v[112:113], v[106:107], v[182:183], v[138:139] op_sel_hi:[1,0,1]
	v_pk_fma_f32 v[106:107], v[104:105], v[182:183], v[136:137] op_sel_hi:[1,0,1]
	v_cvt_pk_bf16_f32 v104, v108, v109
	v_cvt_pk_bf16_f32 v105, v110, v111
	v_cvt_pk_bf16_f32 v106, v106, v107
	v_cvt_pk_bf16_f32 v107, v112, v113
	v_lshl_add_u64 v[108:109], v[158:159], 1, v[194:195]
	global_store_dwordx4 v[108:109], v[104:107], off
	v_pk_fma_f32 v[102:103], v[102:103], v[184:185], v[142:143] op_sel_hi:[1,0,1]
; DI unsigned cvtpk(float lo, float hi) { f32x2 v = {lo, hi}; bf16x2_t b = __builtin_convertvector(v, bf16x2_t); return __builtin_bit_cast(unsigned, b); }
;     DI void operator()(const f32x4 (&acc)[2][2][4][2], const pg8::Unit& u, int wr, int wc, int fr, int fq) const {
;     ...
;         for (int bj = 0; bj < 2; ++bj) { const f32x4 b0 = bb[bj][0], b1 = bb[bj][1];
; #pragma unroll
;             for (int ai = 0; ai < 2; ++ai)
; #pragma unroll
;                 for (int m = 0; m < 4; ++m) {
;                     f32x4 v0 = acc[ai][bj][m][0] * rstd[ai][m] + b0, v1 = acc[ai][bj][m][1] * rstd[ai][m] + b1;
;                     if (ACT == 1) {
; #pragma unroll
;                         for (int e = 0; e < 4; ++e) { float a = fmaxf(v0[e], 0.f), b = fmaxf(v1[e], 0.f); v0[e] = a * a; v1[e] = b * b; } }
;                     u32x4 w; w.x = cvtpk(v0[0], v0[1]); w.y = cvtpk(v0[2], v0[3]); w.z = cvtpk(v1[0], v1[1]); w.w = cvtpk(v1[2], v1[3]);
;                     *(u32x4*)(Ou + (wr * 64 + fr + ai * 128 + m * 16) * ldc + wc * 32 + 8 * fq + bj * 128) = w; } }
	v_pk_fma_f32 v[100:101], v[100:101], v[184:185], v[140:141] op_sel_hi:[1,0,1]
	v_pk_fma_f32 v[104:105], v[98:99], v[184:185], v[138:139] op_sel_hi:[1,0,1]
	v_pk_fma_f32 v[98:99], v[96:97], v[184:185], v[136:137] op_sel_hi:[1,0,1]
	v_cvt_pk_bf16_f32 v96, v100, v101
	v_cvt_pk_bf16_f32 v97, v102, v103
	v_cvt_pk_bf16_f32 v98, v98, v99
	v_cvt_pk_bf16_f32 v99, v104, v105
	v_lshl_add_u64 v[100:101], v[160:161], 1, v[194:195]
	global_store_dwordx4 v[100:101], v[96:99], off
	v_pk_fma_f32 v[94:95], v[94:95], v[186:187], v[142:143] op_sel_hi:[1,0,1]
	v_pk_fma_f32 v[92:93], v[92:93], v[186:187], v[140:141] op_sel_hi:[1,0,1]
	v_pk_fma_f32 v[96:97], v[90:91], v[186:187], v[138:139] op_sel_hi:[1,0,1]
	v_pk_fma_f32 v[90:91], v[88:89], v[186:187], v[136:137] op_sel_hi:[1,0,1]
	v_cvt_pk_bf16_f32 v88, v92, v93
	v_cvt_pk_bf16_f32 v89, v94, v95
	v_cvt_pk_bf16_f32 v90, v90, v91
	v_cvt_pk_bf16_f32 v91, v96, v97
	v_lshl_add_u64 v[92:93], v[162:163], 1, v[194:195]
	global_store_dwordx4 v[92:93], v[88:91], off
	v_pk_fma_f32 v[86:87], v[86:87], v[188:189], v[142:143] op_sel_hi:[1,0,1]
	v_pk_fma_f32 v[84:85], v[84:85], v[188:189], v[140:141] op_sel_hi:[1,0,1]
	v_pk_fma_f32 v[88:89], v[82:83], v[188:189], v[138:139] op_sel_hi:[1,0,1]
	v_pk_fma_f32 v[82:83], v[80:81], v[188:189], v[136:137] op_sel_hi:[1,0,1]
	v_cvt_pk_bf16_f32 v80, v84, v85
	v_cvt_pk_bf16_f32 v81, v86, v87
	v_cvt_pk_bf16_f32 v82, v82, v83
	v_cvt_pk_bf16_f32 v83, v88, v89
	v_lshl_add_u64 v[84:85], v[164:165], 1, v[194:195]
	global_store_dwordx4 v[84:85], v[80:83], off
	v_pk_fma_f32 v[74:75], v[74:75], v[190:191], v[142:143] op_sel_hi:[1,0,1]
	v_pk_fma_f32 v[72:73], v[72:73], v[190:191], v[140:141] op_sel_hi:[1,0,1]
	v_pk_fma_f32 v[80:81], v[66:67], v[190:191], v[138:139] op_sel_hi:[1,0,1]
	v_pk_fma_f32 v[66:67], v[64:65], v[190:191], v[136:137] op_sel_hi:[1,0,1]
	v_cvt_pk_bf16_f32 v64, v72, v73
	v_cvt_pk_bf16_f32 v65, v74, v75
	v_cvt_pk_bf16_f32 v66, v66, v67
	v_cvt_pk_bf16_f32 v67, v80, v81
	v_lshl_add_u64 v[72:73], v[166:167], 1, v[194:195]
	global_store_dwordx4 v[72:73], v[64:67], off
	v_pk_fma_f32 v[54:55], v[54:55], v[192:193], v[142:143] op_sel_hi:[1,0,1]
	v_pk_fma_f32 v[52:53], v[52:53], v[192:193], v[140:141] op_sel_hi:[1,0,1]
	v_pk_fma_f32 v[64:65], v[50:51], v[192:193], v[138:139] op_sel_hi:[1,0,1]
	v_pk_fma_f32 v[50:51], v[48:49], v[192:193], v[136:137] op_sel_hi:[1,0,1]
	v_cvt_pk_bf16_f32 v48, v52, v53
	v_cvt_pk_bf16_f32 v49, v54, v55
	v_cvt_pk_bf16_f32 v50, v50, v51
	v_cvt_pk_bf16_f32 v51, v64, v65
	v_lshl_add_u64 v[52:53], v[168:169], 1, v[194:195]
	global_store_dwordx4 v[52:53], v[48:51], off
	s_waitcnt vmcnt(9)
	v_pk_fma_f32 v[54:55], v[70:71], v[178:179], v[130:131] op_sel_hi:[1,0,1]
	v_pk_fma_f32 v[64:65], v[68:69], v[178:179], v[128:129] op_sel_hi:[1,0,1]
	s_waitcnt vmcnt(8)
	v_pk_fma_f32 v[50:51], v[78:79], v[178:179], v[134:135] op_sel_hi:[1,0,1]
	v_pk_fma_f32 v[48:49], v[76:77], v[178:179], v[132:133] op_sel_hi:[1,0,1]
	v_pk_fma_f32 v[56:57], v[56:57], v[180:181], v[128:129] op_sel_hi:[1,0,1]
	v_cvt_pk_bf16_f32 v48, v48, v49
	v_cvt_pk_bf16_f32 v49, v50, v51
	v_cvt_pk_bf16_f32 v50, v64, v65
	v_cvt_pk_bf16_f32 v51, v54, v55
	global_store_dwordx4 v[124:125], v[48:51], off offset:256
	v_pk_fma_f32 v[54:55], v[58:59], v[180:181], v[130:131] op_sel_hi:[1,0,1]
	v_pk_fma_f32 v[46:47], v[46:47], v[182:183], v[134:135] op_sel_hi:[1,0,1]
	v_pk_fma_f32 v[50:51], v[62:63], v[180:181], v[134:135] op_sel_hi:[1,0,1]
	v_pk_fma_f32 v[48:49], v[60:61], v[180:181], v[132:133] op_sel_hi:[1,0,1]
	v_pk_fma_f32 v[44:45], v[44:45], v[182:183], v[132:133] op_sel_hi:[1,0,1]
	v_cvt_pk_bf16_f32 v48, v48, v49
	v_cvt_pk_bf16_f32 v49, v50, v51
	v_cvt_pk_bf16_f32 v50, v56, v57
	v_cvt_pk_bf16_f32 v51, v54, v55
	global_store_dwordx4 v[116:117], v[48:51], off offset:256
	v_pk_fma_f32 v[38:39], v[38:39], v[184:185], v[134:135] op_sel_hi:[1,0,1]
	v_pk_fma_f32 v[36:37], v[36:37], v[184:185], v[132:133] op_sel_hi:[1,0,1]
	v_pk_fma_f32 v[48:49], v[42:43], v[182:183], v[130:131] op_sel_hi:[1,0,1]
	v_pk_fma_f32 v[42:43], v[40:41], v[182:183], v[128:129] op_sel_hi:[1,0,1]
	v_cvt_pk_bf16_f32 v40, v44, v45
	v_cvt_pk_bf16_f32 v41, v46, v47
	v_cvt_pk_bf16_f32 v42, v42, v43
	v_cvt_pk_bf16_f32 v43, v48, v49
	global_store_dwordx4 v[108:109], v[40:43], off offset:256
	v_pk_fma_f32 v[30:31], v[30:31], v[186:187], v[134:135] op_sel_hi:[1,0,1]
	v_pk_fma_f32 v[28:29], v[28:29], v[186:187], v[132:133] op_sel_hi:[1,0,1]
	v_pk_fma_f32 v[40:41], v[34:35], v[184:185], v[130:131] op_sel_hi:[1,0,1]
	v_pk_fma_f32 v[34:35], v[32:33], v[184:185], v[128:129] op_sel_hi:[1,0,1]
	v_cvt_pk_bf16_f32 v32, v36, v37
	v_cvt_pk_bf16_f32 v33, v38, v39
	v_cvt_pk_bf16_f32 v34, v34, v35
	v_cvt_pk_bf16_f32 v35, v40, v41
	global_store_dwordx4 v[100:101], v[32:35], off offset:256
	v_pk_fma_f32 v[22:23], v[22:23], v[188:189], v[134:135] op_sel_hi:[1,0,1]
	v_pk_fma_f32 v[20:21], v[20:21], v[188:189], v[132:133] op_sel_hi:[1,0,1]
	v_pk_fma_f32 v[32:33], v[26:27], v[186:187], v[130:131] op_sel_hi:[1,0,1]
	v_pk_fma_f32 v[26:27], v[24:25], v[186:187], v[128:129] op_sel_hi:[1,0,1]
	v_cvt_pk_bf16_f32 v24, v28, v29
	v_cvt_pk_bf16_f32 v25, v30, v31
	v_cvt_pk_bf16_f32 v26, v26, v27
	v_cvt_pk_bf16_f32 v27, v32, v33
	global_store_dwordx4 v[92:93], v[24:27], off offset:256
	v_pk_fma_f32 v[14:15], v[14:15], v[190:191], v[134:135] op_sel_hi:[1,0,1]
	v_pk_fma_f32 v[12:13], v[12:13], v[190:191], v[132:133] op_sel_hi:[1,0,1]
	v_pk_fma_f32 v[24:25], v[18:19], v[188:189], v[130:131] op_sel_hi:[1,0,1]
	v_pk_fma_f32 v[18:19], v[16:17], v[188:189], v[128:129] op_sel_hi:[1,0,1]
	v_cvt_pk_bf16_f32 v16, v20, v21
	v_cvt_pk_bf16_f32 v17, v22, v23
	v_cvt_pk_bf16_f32 v18, v18, v19
	v_cvt_pk_bf16_f32 v19, v24, v25
	global_store_dwordx4 v[84:85], v[16:19], off offset:256
	v_pk_fma_f32 v[6:7], v[6:7], v[192:193], v[134:135] op_sel_hi:[1,0,1]
	v_pk_fma_f32 v[4:5], v[4:5], v[192:193], v[132:133] op_sel_hi:[1,0,1]
	v_pk_fma_f32 v[16:17], v[10:11], v[190:191], v[130:131] op_sel_hi:[1,0,1]
	v_pk_fma_f32 v[10:11], v[8:9], v[190:191], v[128:129] op_sel_hi:[1,0,1]
	v_cvt_pk_bf16_f32 v8, v12, v13
	v_cvt_pk_bf16_f32 v9, v14, v15
	v_cvt_pk_bf16_f32 v10, v10, v11
	v_cvt_pk_bf16_f32 v11, v16, v17
	global_store_dwordx4 v[72:73], v[8:11], off offset:256
	s_nop 1
	v_pk_fma_f32 v[8:9], v[2:3], v[192:193], v[130:131] op_sel_hi:[1,0,1]
	v_pk_fma_f32 v[2:3], v[0:1], v[192:193], v[128:129] op_sel_hi:[1,0,1]
	v_cvt_pk_bf16_f32 v0, v4, v5
	v_cvt_pk_bf16_f32 v1, v6, v7
	v_cvt_pk_bf16_f32 v2, v2, v3
	v_cvt_pk_bf16_f32 v3, v8, v9
	global_store_dwordx4 v[52:53], v[0:3], off offset:256
	s_cbranch_vccnz .LBB0_1271
	s_andn2_b64 vcc, exec, s[10:11]
	s_cbranch_vccnz .LBB0_1270
	s_barrier
	s_branch .LBB0_1270

; DI unsigned cvtpk(float lo, float hi) { f32x2 v = {lo, hi}; bf16x2_t b = __builtin_convertvector(v, bf16x2_t); return __builtin_bit_cast(unsigned, b); }
;     DI void operator()(const f32x4 (&acc)[2][2][4][2], const pg8::Unit& u, int wr, int wc, int fr, int fq) const {
;         const int lrow0 = u.pm * 256 + wr * 64 + fr, grow0 = row_base + u.pm * 256, col0 = u.pn * 256 + wc * 32 + 8 * fq;
;         bf16* Ou = O + (size_t)(u.pm * 256) * ldc + u.pn * 256;
;         const int mrow = grow0 < NCTX ? 8 : (grow0 - NCTX) >> 12;
;         float rstd[2][4];
; #pragma unroll
;         for (int ai = 0; ai < 2; ++ai)
; #pragma unroll
;             for (int m = 0; m < 4; ++m) rstd[ai][m] = rsqrtf(rss[row_base + lrow0 + ai * 128 + m * 16] * (1.f / DM) + EPS);
;         const float* bp = bias + mrow * 4096 + col0;
;         f32x4 bb[2][2];
; #pragma unroll
;         for (int bj = 0; bj < 2; ++bj) { bb[bj][0] = *(const f32x4*)(bp + bj * 128); bb[bj][1] = *(const f32x4*)(bp + bj * 128 + 4); }
;         asm volatile("" ::: "memory");
; #pragma unroll
;         for (int bj = 0; bj < 2; ++bj) { const f32x4 b0 = bb[bj][0], b1 = bb[bj][1];
; #pragma unroll
;             for (int ai = 0; ai < 2; ++ai)
; #pragma unroll
;                 for (int m = 0; m < 4; ++m) {
;                     f32x4 v0 = acc[ai][bj][m][0] * rstd[ai][m] + b0, v1 = acc[ai][bj][m][1] * rstd[ai][m] + b1;
;                     if (ACT == 1) {
; #pragma unroll
;                         for (int e = 0; e < 4; ++e) { float a = fmaxf(v0[e], 0.f), b = fmaxf(v1[e], 0.f); v0[e] = a * a; v1[e] = b * b; } }
;                     u32x4 w; w.x = cvtpk(v0[0], v0[1]); w.y = cvtpk(v0[2], v0[3]); w.z = cvtpk(v1[0], v1[1]); w.w = cvtpk(v1[2], v1[3]);
;                     *(u32x4*)(Ou + (wr * 64 + fr + ai * 128 + m * 16) * ldc + wc * 32 + 8 * fq + bj * 128) = w; } }
.LBB0_1447:
	s_lshl_b32 s6, s44, 8
	v_add_u32_e32 v128, s6, v179
	v_ashrrev_i32_e32 v129, 31, v128
	v_lshl_add_u64 v[128:129], v[128:129], 2, s[60:61]
	global_load_dword v200, v[128:129], off
	global_load_dword v201, v[128:129], off offset:64
	global_load_dword v202, v[128:129], off offset:128
	global_load_dword v203, v[128:129], off offset:192
	global_load_dword v204, v[128:129], off offset:512
	global_load_dword v205, v[128:129], off offset:576
	global_load_dword v206, v[128:129], off offset:640
	global_load_dword v207, v[128:129], off offset:704
	s_lshl_b32 s4, s31, 8
	s_ashr_i32 s5, s4, 31
	s_mul_i32 s7, s44, 0xc0000
	s_mul_hi_i32 s6, s6, 0xc00
	s_add_u32 s7, s24, s7
	s_addc_u32 s6, s25, s6
	s_waitcnt vmcnt(7)
	v_fmamk_f32 v200, v200, 0x3a800000, v189
	v_cmp_gt_f32_e32 vcc, s48, v200
	v_mul_f32_e32 v131, 0x4b800000, v200
	s_nop 0
	v_cndmask_b32_e32 v200, v200, v131, vcc
	v_rsq_f32_e32 v200, v200
	s_nop 0
	v_mul_f32_e32 v131, 0x45800000, v200
	v_cndmask_b32_e32 v174, v200, v131, vcc
	s_waitcnt vmcnt(6)
	v_fmamk_f32 v201, v201, 0x3a800000, v189
	v_cmp_gt_f32_e32 vcc, s48, v201
	v_mul_f32_e32 v131, 0x4b800000, v201
	s_nop 0
	v_cndmask_b32_e32 v201, v201, v131, vcc
	v_rsq_f32_e32 v201, v201
	s_nop 0
	v_mul_f32_e32 v131, 0x45800000, v201
	v_cndmask_b32_e32 v176, v201, v131, vcc
	s_waitcnt vmcnt(5)
	v_fmamk_f32 v202, v202, 0x3a800000, v189
	v_cmp_gt_f32_e32 vcc, s48, v202
	v_mul_f32_e32 v131, 0x4b800000, v202
	s_nop 0
	v_cndmask_b32_e32 v202, v202, v131, vcc
	v_rsq_f32_e32 v202, v202
	s_nop 0
	v_mul_f32_e32 v131, 0x45800000, v202
	v_cndmask_b32_e32 v178, v202, v131, vcc
	s_waitcnt vmcnt(4)
	v_fmamk_f32 v203, v203, 0x3a800000, v189
	v_cmp_gt_f32_e32 vcc, s48, v203
	v_mul_f32_e32 v131, 0x4b800000, v203
	s_nop 0
	v_cndmask_b32_e32 v203, v203, v131, vcc
	v_rsq_f32_e32 v203, v203
	s_nop 0
	v_mul_f32_e32 v131, 0x45800000, v203
	v_cndmask_b32_e32 v180, v203, v131, vcc
	s_waitcnt vmcnt(3)
	v_fmamk_f32 v204, v204, 0x3a800000, v189
	v_cmp_gt_f32_e32 vcc, s48, v204
	v_mul_f32_e32 v131, 0x4b800000, v204
	s_nop 0
	v_cndmask_b32_e32 v204, v204, v131, vcc
	v_rsq_f32_e32 v204, v204
	s_nop 0
	v_mul_f32_e32 v131, 0x45800000, v204
	v_cndmask_b32_e32 v182, v204, v131, vcc
	s_waitcnt vmcnt(2)
	v_fmamk_f32 v205, v205, 0x3a800000, v189
	v_cmp_gt_f32_e32 vcc, s48, v205
	v_mul_f32_e32 v131, 0x4b800000, v205
	s_nop 0
	v_cndmask_b32_e32 v205, v205, v131, vcc
	v_rsq_f32_e32 v205, v205
	s_nop 0
	v_mul_f32_e32 v131, 0x45800000, v205
	v_cndmask_b32_e32 v184, v205, v131, vcc
	s_waitcnt vmcnt(1)
	v_fmamk_f32 v206, v206, 0x3a800000, v189
	v_cmp_gt_f32_e32 vcc, s48, v206
	v_mul_f32_e32 v131, 0x4b800000, v206
	s_waitcnt vmcnt(0)
	v_fmamk_f32 v207, v207, 0x3a800000, v189
	v_cndmask_b32_e32 v206, v206, v131, vcc
	v_rsq_f32_e32 v206, v206
	v_mul_f32_e32 v129, 0x4b800000, v207
	v_mul_f32_e32 v131, 0x45800000, v206
	v_cndmask_b32_e32 v186, v206, v131, vcc
	v_cmp_gt_f32_e32 vcc, s48, v207
	s_nop 1
	v_cndmask_b32_e32 v207, v207, v129, vcc
	v_rsq_f32_e32 v207, v207
	s_nop 0
	v_mul_f32_e32 v129, 0x45800000, v207
	v_cndmask_b32_e32 v188, v207, v129, vcc
	v_or_b32_e32 v128, s4, v183
	v_ashrrev_i32_e32 v129, 31, v128
	v_lshl_add_u64 v[132:133], v[128:129], 2, s[18:19]
	global_load_dwordx4 v[136:139], v[132:133], off offset:16
	global_load_dwordx4 v[140:143], v[132:133], off
	global_load_dwordx4 v[128:131], v[132:133], off offset:528
	s_nop 0
	global_load_dwordx4 v[132:135], v[132:133], off offset:512
	s_lshl_b64 s[4:5], s[4:5], 1
	s_add_u32 s4, s7, s4
	s_addc_u32 s5, s6, s5
	s_add_u32 s4, s4, s49
	s_addc_u32 s5, s5, 0
	v_lshl_add_u64 v[190:191], s[4:5], 0, v[152:153]
	s_mov_b64 s[4:5], -1
	s_andn2_b64 vcc, exec, s[38:39]
	s_waitcnt vmcnt(3)
	v_pk_fma_f32 v[194:195], v[122:123], v[174:175], v[138:139] op_sel_hi:[1,0,1]
	s_waitcnt vmcnt(2)
	v_pk_fma_f32 v[126:127], v[126:127], v[174:175], v[142:143] op_sel_hi:[1,0,1]
	v_pk_fma_f32 v[124:125], v[124:125], v[174:175], v[140:141] op_sel_hi:[1,0,1]
	v_pk_fma_f32 v[122:123], v[120:121], v[174:175], v[136:137] op_sel_hi:[1,0,1]
	v_cvt_pk_bf16_f32 v120, v124, v125
	v_cvt_pk_bf16_f32 v121, v126, v127
	v_cvt_pk_bf16_f32 v122, v122, v123
	v_cvt_pk_bf16_f32 v123, v194, v195
	v_lshl_add_u64 v[124:125], v[154:155], 1, v[190:191]
	global_store_dwordx4 v[124:125], v[120:123], off
	v_pk_fma_f32 v[118:119], v[118:119], v[176:177], v[142:143] op_sel_hi:[1,0,1]
	v_pk_fma_f32 v[116:117], v[116:117], v[176:177], v[140:141] op_sel_hi:[1,0,1]
	v_pk_fma_f32 v[120:121], v[114:115], v[176:177], v[138:139] op_sel_hi:[1,0,1]
	v_pk_fma_f32 v[114:115], v[112:113], v[176:177], v[136:137] op_sel_hi:[1,0,1]
	v_cvt_pk_bf16_f32 v112, v116, v117
	v_cvt_pk_bf16_f32 v113, v118, v119
	v_cvt_pk_bf16_f32 v114, v114, v115
	v_cvt_pk_bf16_f32 v115, v120, v121
	v_lshl_add_u64 v[116:117], v[156:157], 1, v[190:191]
	global_store_dwordx4 v[116:117], v[112:115], off
	v_pk_fma_f32 v[110:111], v[110:111], v[178:179], v[142:143] op_sel_hi:[1,0,1]
	v_pk_fma_f32 v[108:109], v[108:109], v[178:179], v[140:141] op_sel_hi:[1,0,1]
	v_pk_fma_f32 v[112:113], v[106:107], v[178:179], v[138:139] op_sel_hi:[1,0,1]
	v_pk_fma_f32 v[106:107], v[104:105], v[178:179], v[136:137] op_sel_hi:[1,0,1]
	v_cvt_pk_bf16_f32 v104, v108, v109
	v_cvt_pk_bf16_f32 v105, v110, v111
	v_cvt_pk_bf16_f32 v106, v106, v107
	v_cvt_pk_bf16_f32 v107, v112, v113
	v_lshl_add_u64 v[108:109], v[158:159], 1, v[190:191]
	global_store_dwordx4 v[108:109], v[104:107], off
	v_pk_fma_f32 v[102:103], v[102:103], v[180:181], v[142:143] op_sel_hi:[1,0,1]
	v_pk_fma_f32 v[100:101], v[100:101], v[180:181], v[140:141] op_sel_hi:[1,0,1]
	v_pk_fma_f32 v[104:105], v[98:99], v[180:181], v[138:139] op_sel_hi:[1,0,1]
; DI unsigned cvtpk(float lo, float hi) { f32x2 v = {lo, hi}; bf16x2_t b = __builtin_convertvector(v, bf16x2_t); return __builtin_bit_cast(unsigned, b); }
;     DI void operator()(const f32x4 (&acc)[2][2][4][2], const pg8::Unit& u, int wr, int wc, int fr, int fq) const {
;     ...
;         for (int bj = 0; bj < 2; ++bj) { const f32x4 b0 = bb[bj][0], b1 = bb[bj][1];
; #pragma unroll
;             for (int ai = 0; ai < 2; ++ai)
; #pragma unroll
;                 for (int m = 0; m < 4; ++m) {
;                     f32x4 v0 = acc[ai][bj][m][0] * rstd[ai][m] + b0, v1 = acc[ai][bj][m][1] * rstd[ai][m] + b1;
;                     if (ACT == 1) {
; #pragma unroll
;                         for (int e = 0; e < 4; ++e) { float a = fmaxf(v0[e], 0.f), b = fmaxf(v1[e], 0.f); v0[e] = a * a; v1[e] = b * b; } }
;                     u32x4 w; w.x = cvtpk(v0[0], v0[1]); w.y = cvtpk(v0[2], v0[3]); w.z = cvtpk(v1[0], v1[1]); w.w = cvtpk(v1[2], v1[3]);
;                     *(u32x4*)(Ou + (wr * 64 + fr + ai * 128 + m * 16) * ldc + wc * 32 + 8 * fq + bj * 128) = w; } }
	v_pk_fma_f32 v[98:99], v[96:97], v[180:181], v[136:137] op_sel_hi:[1,0,1]
	v_cvt_pk_bf16_f32 v96, v100, v101
	v_cvt_pk_bf16_f32 v97, v102, v103
	v_cvt_pk_bf16_f32 v98, v98, v99
	v_cvt_pk_bf16_f32 v99, v104, v105
	v_lshl_add_u64 v[100:101], v[160:161], 1, v[190:191]
	global_store_dwordx4 v[100:101], v[96:99], off
	v_pk_fma_f32 v[94:95], v[94:95], v[182:183], v[142:143] op_sel_hi:[1,0,1]
	v_pk_fma_f32 v[92:93], v[92:93], v[182:183], v[140:141] op_sel_hi:[1,0,1]
	v_pk_fma_f32 v[96:97], v[90:91], v[182:183], v[138:139] op_sel_hi:[1,0,1]
	v_pk_fma_f32 v[90:91], v[88:89], v[182:183], v[136:137] op_sel_hi:[1,0,1]
	v_cvt_pk_bf16_f32 v88, v92, v93
	v_cvt_pk_bf16_f32 v89, v94, v95
	v_cvt_pk_bf16_f32 v90, v90, v91
	v_cvt_pk_bf16_f32 v91, v96, v97
	v_lshl_add_u64 v[92:93], v[162:163], 1, v[190:191]
	global_store_dwordx4 v[92:93], v[88:91], off
	v_pk_fma_f32 v[86:87], v[86:87], v[184:185], v[142:143] op_sel_hi:[1,0,1]
	v_pk_fma_f32 v[84:85], v[84:85], v[184:185], v[140:141] op_sel_hi:[1,0,1]
	v_pk_fma_f32 v[88:89], v[82:83], v[184:185], v[138:139] op_sel_hi:[1,0,1]
	v_pk_fma_f32 v[82:83], v[80:81], v[184:185], v[136:137] op_sel_hi:[1,0,1]
	v_cvt_pk_bf16_f32 v80, v84, v85
	v_cvt_pk_bf16_f32 v81, v86, v87
	v_cvt_pk_bf16_f32 v82, v82, v83
	v_cvt_pk_bf16_f32 v83, v88, v89
	v_lshl_add_u64 v[84:85], v[164:165], 1, v[190:191]
	global_store_dwordx4 v[84:85], v[80:83], off
	v_pk_fma_f32 v[74:75], v[74:75], v[186:187], v[142:143] op_sel_hi:[1,0,1]
	v_pk_fma_f32 v[72:73], v[72:73], v[186:187], v[140:141] op_sel_hi:[1,0,1]
	v_pk_fma_f32 v[80:81], v[66:67], v[186:187], v[138:139] op_sel_hi:[1,0,1]
	v_pk_fma_f32 v[66:67], v[64:65], v[186:187], v[136:137] op_sel_hi:[1,0,1]
	v_cvt_pk_bf16_f32 v64, v72, v73
	v_cvt_pk_bf16_f32 v65, v74, v75
	v_cvt_pk_bf16_f32 v66, v66, v67
	v_cvt_pk_bf16_f32 v67, v80, v81
	v_lshl_add_u64 v[72:73], v[166:167], 1, v[190:191]
	global_store_dwordx4 v[72:73], v[64:67], off
	v_pk_fma_f32 v[54:55], v[54:55], v[188:189], v[142:143] op_sel_hi:[1,0,1]
	v_pk_fma_f32 v[52:53], v[52:53], v[188:189], v[140:141] op_sel_hi:[1,0,1]
	v_pk_fma_f32 v[64:65], v[50:51], v[188:189], v[138:139] op_sel_hi:[1,0,1]
	v_pk_fma_f32 v[50:51], v[48:49], v[188:189], v[136:137] op_sel_hi:[1,0,1]
	v_cvt_pk_bf16_f32 v48, v52, v53
	v_cvt_pk_bf16_f32 v49, v54, v55
	v_cvt_pk_bf16_f32 v50, v50, v51
	v_cvt_pk_bf16_f32 v51, v64, v65
	v_lshl_add_u64 v[52:53], v[168:169], 1, v[190:191]
	global_store_dwordx4 v[52:53], v[48:51], off
	s_waitcnt vmcnt(9)
	v_pk_fma_f32 v[54:55], v[70:71], v[174:175], v[130:131] op_sel_hi:[1,0,1]
	v_pk_fma_f32 v[64:65], v[68:69], v[174:175], v[128:129] op_sel_hi:[1,0,1]
	s_waitcnt vmcnt(8)
	v_pk_fma_f32 v[50:51], v[78:79], v[174:175], v[134:135] op_sel_hi:[1,0,1]
	v_pk_fma_f32 v[48:49], v[76:77], v[174:175], v[132:133] op_sel_hi:[1,0,1]
	v_pk_fma_f32 v[56:57], v[56:57], v[176:177], v[128:129] op_sel_hi:[1,0,1]
	v_cvt_pk_bf16_f32 v48, v48, v49
	v_cvt_pk_bf16_f32 v49, v50, v51
	v_cvt_pk_bf16_f32 v50, v64, v65
	v_cvt_pk_bf16_f32 v51, v54, v55
	global_store_dwordx4 v[124:125], v[48:51], off offset:256
	v_pk_fma_f32 v[54:55], v[58:59], v[176:177], v[130:131] op_sel_hi:[1,0,1]
	v_pk_fma_f32 v[46:47], v[46:47], v[178:179], v[134:135] op_sel_hi:[1,0,1]
	v_pk_fma_f32 v[50:51], v[62:63], v[176:177], v[134:135] op_sel_hi:[1,0,1]
	v_pk_fma_f32 v[48:49], v[60:61], v[176:177], v[132:133] op_sel_hi:[1,0,1]
	v_pk_fma_f32 v[44:45], v[44:45], v[178:179], v[132:133] op_sel_hi:[1,0,1]
	v_cvt_pk_bf16_f32 v48, v48, v49
	v_cvt_pk_bf16_f32 v49, v50, v51
	v_cvt_pk_bf16_f32 v50, v56, v57
	v_cvt_pk_bf16_f32 v51, v54, v55
	global_store_dwordx4 v[116:117], v[48:51], off offset:256
	v_pk_fma_f32 v[38:39], v[38:39], v[180:181], v[134:135] op_sel_hi:[1,0,1]
	v_pk_fma_f32 v[36:37], v[36:37], v[180:181], v[132:133] op_sel_hi:[1,0,1]
	v_pk_fma_f32 v[48:49], v[42:43], v[178:179], v[130:131] op_sel_hi:[1,0,1]
	v_pk_fma_f32 v[42:43], v[40:41], v[178:179], v[128:129] op_sel_hi:[1,0,1]
	v_cvt_pk_bf16_f32 v40, v44, v45
	v_cvt_pk_bf16_f32 v41, v46, v47
	v_cvt_pk_bf16_f32 v42, v42, v43
	v_cvt_pk_bf16_f32 v43, v48, v49
	global_store_dwordx4 v[108:109], v[40:43], off offset:256
	v_pk_fma_f32 v[30:31], v[30:31], v[182:183], v[134:135] op_sel_hi:[1,0,1]
	v_pk_fma_f32 v[28:29], v[28:29], v[182:183], v[132:133] op_sel_hi:[1,0,1]
	v_pk_fma_f32 v[40:41], v[34:35], v[180:181], v[130:131] op_sel_hi:[1,0,1]
	v_pk_fma_f32 v[34:35], v[32:33], v[180:181], v[128:129] op_sel_hi:[1,0,1]
	v_cvt_pk_bf16_f32 v32, v36, v37
	v_cvt_pk_bf16_f32 v33, v38, v39
	v_cvt_pk_bf16_f32 v34, v34, v35
	v_cvt_pk_bf16_f32 v35, v40, v41
	global_store_dwordx4 v[100:101], v[32:35], off offset:256
	v_pk_fma_f32 v[22:23], v[22:23], v[184:185], v[134:135] op_sel_hi:[1,0,1]
	v_pk_fma_f32 v[20:21], v[20:21], v[184:185], v[132:133] op_sel_hi:[1,0,1]
	v_pk_fma_f32 v[32:33], v[26:27], v[182:183], v[130:131] op_sel_hi:[1,0,1]
	v_pk_fma_f32 v[26:27], v[24:25], v[182:183], v[128:129] op_sel_hi:[1,0,1]
	v_cvt_pk_bf16_f32 v24, v28, v29
	v_cvt_pk_bf16_f32 v25, v30, v31
	v_cvt_pk_bf16_f32 v26, v26, v27
	v_cvt_pk_bf16_f32 v27, v32, v33
	global_store_dwordx4 v[92:93], v[24:27], off offset:256
	v_pk_fma_f32 v[14:15], v[14:15], v[186:187], v[134:135] op_sel_hi:[1,0,1]
	v_pk_fma_f32 v[12:13], v[12:13], v[186:187], v[132:133] op_sel_hi:[1,0,1]
	v_pk_fma_f32 v[24:25], v[18:19], v[184:185], v[130:131] op_sel_hi:[1,0,1]
	v_pk_fma_f32 v[18:19], v[16:17], v[184:185], v[128:129] op_sel_hi:[1,0,1]
	v_cvt_pk_bf16_f32 v16, v20, v21
	v_cvt_pk_bf16_f32 v17, v22, v23
	v_cvt_pk_bf16_f32 v18, v18, v19
	v_cvt_pk_bf16_f32 v19, v24, v25
	global_store_dwordx4 v[84:85], v[16:19], off offset:256
	v_pk_fma_f32 v[6:7], v[6:7], v[188:189], v[134:135] op_sel_hi:[1,0,1]
	v_pk_fma_f32 v[4:5], v[4:5], v[188:189], v[132:133] op_sel_hi:[1,0,1]
	v_pk_fma_f32 v[16:17], v[10:11], v[186:187], v[130:131] op_sel_hi:[1,0,1]
	v_pk_fma_f32 v[10:11], v[8:9], v[186:187], v[128:129] op_sel_hi:[1,0,1]
	v_cvt_pk_bf16_f32 v8, v12, v13
	v_cvt_pk_bf16_f32 v9, v14, v15
	v_cvt_pk_bf16_f32 v10, v10, v11
	v_cvt_pk_bf16_f32 v11, v16, v17
	global_store_dwordx4 v[72:73], v[8:11], off offset:256
	s_nop 1
	v_pk_fma_f32 v[8:9], v[2:3], v[188:189], v[130:131] op_sel_hi:[1,0,1]
	v_pk_fma_f32 v[2:3], v[0:1], v[188:189], v[128:129] op_sel_hi:[1,0,1]
	v_cvt_pk_bf16_f32 v0, v4, v5
	v_cvt_pk_bf16_f32 v1, v6, v7
	v_cvt_pk_bf16_f32 v2, v2, v3
	v_cvt_pk_bf16_f32 v3, v8, v9
	global_store_dwordx4 v[52:53], v[0:3], off offset:256
	s_cbranch_vccnz .LBB0_1440
	s_andn2_b64 vcc, exec, s[0:1]
	s_cbranch_vccnz .LBB0_1439
	s_barrier
	s_branch .LBB0_1439

; DI unsigned cvtpk(float lo, float hi) { f32x2 v = {lo, hi}; bf16x2_t b = __builtin_convertvector(v, bf16x2_t); return __builtin_bit_cast(unsigned, b); }
;     DI void operator()(const f32x4 (&acc)[2][2][4][2], const pg8::Unit& u, int wr, int wc, int fr, int fq) const {
;         const int lrow0 = u.pm * 256 + wr * 64 + fr, grow0 = row_base + u.pm * 256, col0 = u.pn * 256 + wc * 32 + 8 * fq;
;         bf16* Ou = O + (size_t)(u.pm * 256) * ldc + u.pn * 256;
;         const int mrow = grow0 < NCTX ? 8 : (grow0 - NCTX) >> 12;
;         float rstd[2][4];
; #pragma unroll
;         for (int ai = 0; ai < 2; ++ai)
; #pragma unroll
;             for (int m = 0; m < 4; ++m) rstd[ai][m] = rsqrtf(rss[row_base + lrow0 + ai * 128 + m * 16] * (1.f / DM) + EPS);
;         const float* bp = bias + mrow * 4096 + col0;
;         f32x4 bb[2][2];
; #pragma unroll
;         for (int bj = 0; bj < 2; ++bj) { bb[bj][0] = *(const f32x4*)(bp + bj * 128); bb[bj][1] = *(const f32x4*)(bp + bj * 128 + 4); }
;     ...
; #pragma unroll
;         for (int bj = 0; bj < 2; ++bj) { const f32x4 b0 = bb[bj][0], b1 = bb[bj][1];
; #pragma unroll
;             for (int ai = 0; ai < 2; ++ai)
; #pragma unroll
;                 for (int m = 0; m < 4; ++m) {
;                     f32x4 v0 = acc[ai][bj][m][0] * rstd[ai][m] + b0, v1 = acc[ai][bj][m][1] * rstd[ai][m] + b1;
;                     if (ACT == 1) {
; #pragma unroll
;                         for (int e = 0; e < 4; ++e) { float a = fmaxf(v0[e], 0.f), b = fmaxf(v1[e], 0.f); v0[e] = a * a; v1[e] = b * b; } }
;                     u32x4 w; w.x = cvtpk(v0[0], v0[1]); w.y = cvtpk(v0[2], v0[3]); w.z = cvtpk(v1[0], v1[1]); w.w = cvtpk(v1[2], v1[3]);
;                     *(u32x4*)(Ou + (wr * 64 + fr + ai * 128 + m * 16) * ldc + wc * 32 + 8 * fq + bj * 128) = w; } }
.LBB0_1709:
	s_lshl_b32 s6, s38, 8
	v_add_u32_e32 v128, s6, v183
	v_ashrrev_i32_e32 v129, 31, v128
	v_lshl_add_u64 v[128:129], v[128:129], 2, s[0:1]
	global_load_dword v200, v[128:129], off
	global_load_dword v201, v[128:129], off offset:64
	global_load_dword v202, v[128:129], off offset:128
	global_load_dword v203, v[128:129], off offset:192
	global_load_dword v204, v[128:129], off offset:512
	global_load_dword v205, v[128:129], off offset:576
	global_load_dword v206, v[128:129], off offset:640
	global_load_dword v207, v[128:129], off offset:704
	s_lshl_b32 s4, s31, 8
	s_ashr_i32 s7, s6, 31
	s_ashr_i32 s5, s4, 31
	s_lshl_b64 s[8:9], s[6:7], 13
	v_readlane_b32 s52, v254, 36
	v_readlane_b32 s53, v254, 37
	s_add_u32 s8, s52, s8
	s_addc_u32 s9, s53, s9
	s_and_b32 s7, s6, 0xfffff000
	s_cmp_lt_u32 s6, 0x7ffff800
	s_cselect_b32 s6, s7, 0x8000
	s_ashr_i32 s7, s6, 31
	s_lshl_b64 s[6:7], s[6:7], 2
	s_add_u32 s6, s44, s6
	s_addc_u32 s7, s45, s7
	s_waitcnt vmcnt(7)
	v_fmamk_f32 v200, v200, 0x3a800000, v187
	v_cmp_gt_f32_e32 vcc, s49, v200
	v_mul_f32_e32 v131, 0x4b800000, v200
	s_nop 0
	v_cndmask_b32_e32 v200, v200, v131, vcc
	v_rsq_f32_e32 v200, v200
	s_nop 0
	v_mul_f32_e32 v131, 0x45800000, v200
	v_cndmask_b32_e32 v192, v200, v131, vcc
	s_waitcnt vmcnt(6)
	v_fmamk_f32 v201, v201, 0x3a800000, v187
	v_cmp_gt_f32_e32 vcc, s49, v201
	v_mul_f32_e32 v131, 0x4b800000, v201
	s_nop 0
	v_cndmask_b32_e32 v201, v201, v131, vcc
	v_rsq_f32_e32 v201, v201
	s_nop 0
	v_mul_f32_e32 v131, 0x45800000, v201
	v_cndmask_b32_e32 v190, v201, v131, vcc
	s_waitcnt vmcnt(5)
	v_fmamk_f32 v202, v202, 0x3a800000, v187
	v_cmp_gt_f32_e32 vcc, s49, v202
	v_mul_f32_e32 v131, 0x4b800000, v202
	s_nop 0
	v_cndmask_b32_e32 v202, v202, v131, vcc
	v_rsq_f32_e32 v202, v202
	s_nop 0
	v_mul_f32_e32 v131, 0x45800000, v202
	v_cndmask_b32_e32 v188, v202, v131, vcc
	s_waitcnt vmcnt(4)
	v_fmamk_f32 v203, v203, 0x3a800000, v187
	v_cmp_gt_f32_e32 vcc, s49, v203
	v_mul_f32_e32 v131, 0x4b800000, v203
	s_nop 0
	v_cndmask_b32_e32 v203, v203, v131, vcc
	v_rsq_f32_e32 v203, v203
	s_nop 0
	v_mul_f32_e32 v131, 0x45800000, v203
	v_cndmask_b32_e32 v186, v203, v131, vcc
	s_waitcnt vmcnt(3)
	v_fmamk_f32 v204, v204, 0x3a800000, v187
	v_cmp_gt_f32_e32 vcc, s49, v204
	v_mul_f32_e32 v131, 0x4b800000, v204
	s_nop 0
	v_cndmask_b32_e32 v204, v204, v131, vcc
	v_rsq_f32_e32 v204, v204
	s_nop 0
	v_mul_f32_e32 v131, 0x45800000, v204
	v_cndmask_b32_e32 v184, v204, v131, vcc
	s_waitcnt vmcnt(2)
	v_fmamk_f32 v205, v205, 0x3a800000, v187
	v_cmp_gt_f32_e32 vcc, s49, v205
	v_mul_f32_e32 v131, 0x4b800000, v205
	s_nop 0
	v_cndmask_b32_e32 v205, v205, v131, vcc
	v_rsq_f32_e32 v205, v205
	s_nop 0
	v_mul_f32_e32 v131, 0x45800000, v205
	v_cndmask_b32_e32 v182, v205, v131, vcc
	s_waitcnt vmcnt(1)
	v_fmamk_f32 v206, v206, 0x3a800000, v187
	v_cmp_gt_f32_e32 vcc, s49, v206
	v_mul_f32_e32 v131, 0x4b800000, v206
	s_waitcnt vmcnt(0)
	v_fmamk_f32 v207, v207, 0x3a800000, v187
	v_cndmask_b32_e32 v206, v206, v131, vcc
	v_rsq_f32_e32 v206, v206
	v_mul_f32_e32 v129, 0x4b800000, v207
	v_mul_f32_e32 v131, 0x45800000, v206
	v_cndmask_b32_e32 v180, v206, v131, vcc
	v_cmp_gt_f32_e32 vcc, s49, v207
	s_nop 1
	v_cndmask_b32_e32 v207, v207, v129, vcc
	v_rsq_f32_e32 v207, v207
	s_nop 0
	v_mul_f32_e32 v129, 0x45800000, v207
	v_cndmask_b32_e32 v178, v207, v129, vcc
	v_or_b32_e32 v128, s4, v181
	v_ashrrev_i32_e32 v129, 31, v128
	v_lshl_add_u64 v[132:133], v[128:129], 2, s[6:7]
	global_load_dwordx4 v[136:139], v[132:133], off offset:16
	global_load_dwordx4 v[140:143], v[132:133], off
	global_load_dwordx4 v[128:131], v[132:133], off offset:528
	s_nop 0
	global_load_dwordx4 v[132:135], v[132:133], off offset:512
	s_lshl_b64 s[4:5], s[4:5], 1
	s_add_u32 s4, s8, s4
	s_addc_u32 s5, s9, s5
	s_add_u32 s4, s4, s50
	s_addc_u32 s5, s5, 0
	v_lshl_add_u64 v[194:195], s[4:5], 0, v[152:153]
	s_mov_b64 s[4:5], 0x100
	s_andn2_b64 vcc, exec, s[34:35]
	s_waitcnt vmcnt(3)
	v_pk_fma_f32 v[122:123], v[122:123], v[192:193], v[138:139] op_sel_hi:[1,0,1]
	s_waitcnt vmcnt(2)
	v_pk_fma_f32 v[126:127], v[126:127], v[192:193], v[142:143] op_sel_hi:[1,0,1]
	v_pk_fma_f32 v[124:125], v[124:125], v[192:193], v[140:141] op_sel_hi:[1,0,1]
	v_pk_fma_f32 v[120:121], v[120:121], v[192:193], v[136:137] op_sel_hi:[1,0,1]
	v_max_f32_e32 v124, 0, v124
	v_max_f32_e32 v120, 0, v120
	v_max_f32_e32 v125, 0, v125
	v_max_f32_e32 v121, 0, v121
	v_max_f32_e32 v126, 0, v126
	v_max_f32_e32 v122, 0, v122
	v_max_f32_e32 v127, 0, v127
	v_max_f32_e32 v123, 0, v123
	v_pk_mul_f32 v[124:125], v[124:125], v[124:125]
	v_pk_mul_f32 v[120:121], v[120:121], v[120:121]
	v_pk_mul_f32 v[126:127], v[126:127], v[126:127]
	v_pk_mul_f32 v[196:197], v[122:123], v[122:123]
	v_pk_fma_f32 v[112:113], v[112:113], v[190:191], v[136:137] op_sel_hi:[1,0,1]
	v_cvt_pk_bf16_f32 v122, v124, v125
	v_cvt_pk_bf16_f32 v123, v126, v127
	v_cvt_pk_bf16_f32 v124, v120, v121
	v_cvt_pk_bf16_f32 v125, v196, v197
	v_lshl_add_u64 v[120:121], v[154:155], 1, v[194:195]
	v_pk_fma_f32 v[118:119], v[118:119], v[190:191], v[142:143] op_sel_hi:[1,0,1]
	v_pk_fma_f32 v[116:117], v[116:117], v[190:191], v[140:141] op_sel_hi:[1,0,1]
	v_pk_fma_f32 v[114:115], v[114:115], v[190:191], v[138:139] op_sel_hi:[1,0,1]
	v_max_f32_e32 v112, 0, v112
	v_max_f32_e32 v113, 0, v113
	global_store_dwordx4 v[120:121], v[122:125], off
	v_max_f32_e32 v116, 0, v116
	v_max_f32_e32 v117, 0, v117
	v_pk_mul_f32 v[122:123], v[112:113], v[112:113]
	v_max_f32_e32 v112, 0, v118
	v_max_f32_e32 v114, 0, v114
	v_max_f32_e32 v113, 0, v119
	v_max_f32_e32 v115, 0, v115
	v_pk_mul_f32 v[116:117], v[116:117], v[116:117]
	v_pk_mul_f32 v[118:119], v[112:113], v[112:113]
	v_pk_mul_f32 v[124:125], v[114:115], v[114:115]
; DI unsigned cvtpk(float lo, float hi) { f32x2 v = {lo, hi}; bf16x2_t b = __builtin_convertvector(v, bf16x2_t); return __builtin_bit_cast(unsigned, b); }
;     DI void operator()(const f32x4 (&acc)[2][2][4][2], const pg8::Unit& u, int wr, int wc, int fr, int fq) const {
;     ...
; #pragma unroll
;         for (int bj = 0; bj < 2; ++bj) { const f32x4 b0 = bb[bj][0], b1 = bb[bj][1];
; #pragma unroll
;             for (int ai = 0; ai < 2; ++ai)
; #pragma unroll
;                 for (int m = 0; m < 4; ++m) {
;                     f32x4 v0 = acc[ai][bj][m][0] * rstd[ai][m] + b0, v1 = acc[ai][bj][m][1] * rstd[ai][m] + b1;
;                     if (ACT == 1) {
; #pragma unroll
;                         for (int e = 0; e < 4; ++e) { float a = fmaxf(v0[e], 0.f), b = fmaxf(v1[e], 0.f); v0[e] = a * a; v1[e] = b * b; } }
;                     u32x4 w; w.x = cvtpk(v0[0], v0[1]); w.y = cvtpk(v0[2], v0[3]); w.z = cvtpk(v1[0], v1[1]); w.w = cvtpk(v1[2], v1[3]);
;                     *(u32x4*)(Ou + (wr * 64 + fr + ai * 128 + m * 16) * ldc + wc * 32 + 8 * fq + bj * 128) = w; } }
	v_pk_fma_f32 v[104:105], v[104:105], v[188:189], v[136:137] op_sel_hi:[1,0,1]
	v_cvt_pk_bf16_f32 v112, v116, v117
	v_cvt_pk_bf16_f32 v113, v118, v119
	v_cvt_pk_bf16_f32 v114, v122, v123
	v_cvt_pk_bf16_f32 v115, v124, v125
	v_lshl_add_u64 v[116:117], v[194:195], 0, v[170:171]
	v_pk_fma_f32 v[110:111], v[110:111], v[188:189], v[142:143] op_sel_hi:[1,0,1]
	v_pk_fma_f32 v[108:109], v[108:109], v[188:189], v[140:141] op_sel_hi:[1,0,1]
	v_pk_fma_f32 v[106:107], v[106:107], v[188:189], v[138:139] op_sel_hi:[1,0,1]
	v_max_f32_e32 v104, 0, v104
	v_max_f32_e32 v105, 0, v105
	global_store_dwordx4 v[116:117], v[112:115], off
	v_max_f32_e32 v108, 0, v108
	v_max_f32_e32 v109, 0, v109
	v_pk_mul_f32 v[112:113], v[104:105], v[104:105]
	v_max_f32_e32 v104, 0, v110
	v_max_f32_e32 v106, 0, v106
	v_max_f32_e32 v105, 0, v111
	v_max_f32_e32 v107, 0, v107
	v_pk_mul_f32 v[108:109], v[108:109], v[108:109]
	v_pk_mul_f32 v[110:111], v[104:105], v[104:105]
	v_pk_mul_f32 v[114:115], v[106:107], v[106:107]
	v_pk_fma_f32 v[96:97], v[96:97], v[186:187], v[136:137] op_sel_hi:[1,0,1]
	v_cvt_pk_bf16_f32 v104, v108, v109
	v_cvt_pk_bf16_f32 v105, v110, v111
	v_cvt_pk_bf16_f32 v106, v112, v113
	v_cvt_pk_bf16_f32 v107, v114, v115
	v_lshl_add_u64 v[108:109], v[194:195], 0, v[172:173]
	v_pk_fma_f32 v[102:103], v[102:103], v[186:187], v[142:143] op_sel_hi:[1,0,1]
	v_pk_fma_f32 v[100:101], v[100:101], v[186:187], v[140:141] op_sel_hi:[1,0,1]
	v_pk_fma_f32 v[98:99], v[98:99], v[186:187], v[138:139] op_sel_hi:[1,0,1]
	v_max_f32_e32 v96, 0, v96
	v_max_f32_e32 v97, 0, v97
	global_store_dwordx4 v[108:109], v[104:107], off
	v_max_f32_e32 v100, 0, v100
	v_max_f32_e32 v101, 0, v101
	v_pk_mul_f32 v[104:105], v[96:97], v[96:97]
	v_max_f32_e32 v96, 0, v102
	v_max_f32_e32 v98, 0, v98
	v_max_f32_e32 v97, 0, v103
	v_max_f32_e32 v99, 0, v99
	v_pk_mul_f32 v[100:101], v[100:101], v[100:101]
	v_pk_mul_f32 v[102:103], v[96:97], v[96:97]
	v_pk_mul_f32 v[106:107], v[98:99], v[98:99]
	v_pk_fma_f32 v[94:95], v[94:95], v[184:185], v[142:143] op_sel_hi:[1,0,1]
	v_pk_fma_f32 v[92:93], v[92:93], v[184:185], v[140:141] op_sel_hi:[1,0,1]
	v_pk_fma_f32 v[90:91], v[90:91], v[184:185], v[138:139] op_sel_hi:[1,0,1]
	v_pk_fma_f32 v[88:89], v[88:89], v[184:185], v[136:137] op_sel_hi:[1,0,1]
	v_cvt_pk_bf16_f32 v96, v100, v101
	v_cvt_pk_bf16_f32 v97, v102, v103
	v_cvt_pk_bf16_f32 v98, v104, v105
	v_cvt_pk_bf16_f32 v99, v106, v107
	v_lshl_add_u64 v[100:101], v[194:195], 0, v[174:175]
	v_max_f32_e32 v92, 0, v92
	v_max_f32_e32 v88, 0, v88
	v_max_f32_e32 v93, 0, v93
	v_max_f32_e32 v89, 0, v89
	v_max_f32_e32 v94, 0, v94
	v_max_f32_e32 v90, 0, v90
	v_max_f32_e32 v95, 0, v95
	v_max_f32_e32 v91, 0, v91
	global_store_dwordx4 v[100:101], v[96:99], off
	v_pk_mul_f32 v[92:93], v[92:93], v[92:93]
	v_pk_mul_f32 v[88:89], v[88:89], v[88:89]
	v_pk_mul_f32 v[94:95], v[94:95], v[94:95]
	v_pk_mul_f32 v[96:97], v[90:91], v[90:91]
	v_pk_fma_f32 v[86:87], v[86:87], v[182:183], v[142:143] op_sel_hi:[1,0,1]
	v_pk_fma_f32 v[84:85], v[84:85], v[182:183], v[140:141] op_sel_hi:[1,0,1]
	v_pk_fma_f32 v[82:83], v[82:83], v[182:183], v[138:139] op_sel_hi:[1,0,1]
	v_pk_fma_f32 v[80:81], v[80:81], v[182:183], v[136:137] op_sel_hi:[1,0,1]
	v_cvt_pk_bf16_f32 v90, v92, v93
	v_cvt_pk_bf16_f32 v91, v94, v95
	v_cvt_pk_bf16_f32 v92, v88, v89
	v_cvt_pk_bf16_f32 v93, v96, v97
	v_lshl_add_u64 v[88:89], v[156:157], 1, v[194:195]
	v_max_f32_e32 v84, 0, v84
	v_max_f32_e32 v80, 0, v80
	v_max_f32_e32 v85, 0, v85
	v_max_f32_e32 v81, 0, v81
	v_max_f32_e32 v86, 0, v86
	v_max_f32_e32 v82, 0, v82
	v_max_f32_e32 v87, 0, v87
	v_max_f32_e32 v83, 0, v83
	global_store_dwordx4 v[88:89], v[90:93], off
	v_pk_mul_f32 v[84:85], v[84:85], v[84:85]
	v_pk_mul_f32 v[80:81], v[80:81], v[80:81]
	v_pk_mul_f32 v[86:87], v[86:87], v[86:87]
	v_pk_mul_f32 v[90:91], v[82:83], v[82:83]
	v_pk_fma_f32 v[78:79], v[78:79], v[180:181], v[142:143] op_sel_hi:[1,0,1]
	v_pk_fma_f32 v[76:77], v[76:77], v[180:181], v[140:141] op_sel_hi:[1,0,1]
	v_pk_fma_f32 v[74:75], v[74:75], v[180:181], v[138:139] op_sel_hi:[1,0,1]
	v_pk_fma_f32 v[72:73], v[72:73], v[180:181], v[136:137] op_sel_hi:[1,0,1]
	v_cvt_pk_bf16_f32 v82, v84, v85
	v_cvt_pk_bf16_f32 v83, v86, v87
	v_cvt_pk_bf16_f32 v84, v80, v81
	v_cvt_pk_bf16_f32 v85, v90, v91
	v_lshl_add_u64 v[80:81], v[158:159], 1, v[194:195]
	v_max_f32_e32 v76, 0, v76
	v_max_f32_e32 v72, 0, v72
	v_max_f32_e32 v77, 0, v77
	v_max_f32_e32 v73, 0, v73
	v_max_f32_e32 v78, 0, v78
	v_max_f32_e32 v74, 0, v74
	v_max_f32_e32 v79, 0, v79
	v_max_f32_e32 v75, 0, v75
	global_store_dwordx4 v[80:81], v[82:85], off
	v_pk_mul_f32 v[76:77], v[76:77], v[76:77]
	v_pk_mul_f32 v[72:73], v[72:73], v[72:73]
	v_pk_mul_f32 v[78:79], v[78:79], v[78:79]
	v_pk_mul_f32 v[82:83], v[74:75], v[74:75]
	v_pk_fma_f32 v[62:63], v[62:63], v[178:179], v[142:143] op_sel_hi:[1,0,1]
	v_pk_fma_f32 v[60:61], v[60:61], v[178:179], v[140:141] op_sel_hi:[1,0,1]
	v_pk_fma_f32 v[58:59], v[58:59], v[178:179], v[138:139] op_sel_hi:[1,0,1]
	v_pk_fma_f32 v[56:57], v[56:57], v[178:179], v[136:137] op_sel_hi:[1,0,1]
	v_cvt_pk_bf16_f32 v74, v76, v77
	v_cvt_pk_bf16_f32 v75, v78, v79
	v_cvt_pk_bf16_f32 v76, v72, v73
	v_cvt_pk_bf16_f32 v77, v82, v83
	v_lshl_add_u64 v[72:73], v[160:161], 1, v[194:195]
	v_max_f32_e32 v60, 0, v60
	v_max_f32_e32 v56, 0, v56
	v_max_f32_e32 v61, 0, v61
	v_max_f32_e32 v57, 0, v57
	v_max_f32_e32 v62, 0, v62
	v_max_f32_e32 v58, 0, v58
	v_max_f32_e32 v63, 0, v63
	v_max_f32_e32 v59, 0, v59
	global_store_dwordx4 v[72:73], v[74:77], off
	v_pk_mul_f32 v[60:61], v[60:61], v[60:61]
	v_pk_mul_f32 v[56:57], v[56:57], v[56:57]
	v_pk_mul_f32 v[62:63], v[62:63], v[62:63]
	v_pk_mul_f32 v[74:75], v[58:59], v[58:59]
	v_cvt_pk_bf16_f32 v58, v60, v61
	v_cvt_pk_bf16_f32 v59, v62, v63
	v_cvt_pk_bf16_f32 v60, v56, v57
	v_cvt_pk_bf16_f32 v61, v74, v75
	v_lshl_add_u64 v[56:57], v[162:163], 1, v[194:195]
	global_store_dwordx4 v[56:57], v[58:61], off
	s_waitcnt vmcnt(9)
; DI unsigned cvtpk(float lo, float hi) { f32x2 v = {lo, hi}; bf16x2_t b = __builtin_convertvector(v, bf16x2_t); return __builtin_bit_cast(unsigned, b); }
;     DI void operator()(const f32x4 (&acc)[2][2][4][2], const pg8::Unit& u, int wr, int wc, int fr, int fq) const {
;     ...
; #pragma unroll
;         for (int bj = 0; bj < 2; ++bj) { const f32x4 b0 = bb[bj][0], b1 = bb[bj][1];
; #pragma unroll
;             for (int ai = 0; ai < 2; ++ai)
; #pragma unroll
;                 for (int m = 0; m < 4; ++m) {
;                     f32x4 v0 = acc[ai][bj][m][0] * rstd[ai][m] + b0, v1 = acc[ai][bj][m][1] * rstd[ai][m] + b1;
;                     if (ACT == 1) {
; #pragma unroll
;                         for (int e = 0; e < 4; ++e) { float a = fmaxf(v0[e], 0.f), b = fmaxf(v1[e], 0.f); v0[e] = a * a; v1[e] = b * b; } }
;                     u32x4 w; w.x = cvtpk(v0[0], v0[1]); w.y = cvtpk(v0[2], v0[3]); w.z = cvtpk(v1[0], v1[1]); w.w = cvtpk(v1[2], v1[3]);
;                     *(u32x4*)(Ou + (wr * 64 + fr + ai * 128 + m * 16) * ldc + wc * 32 + 8 * fq + bj * 128) = w; } }
	v_pk_fma_f32 v[66:67], v[66:67], v[192:193], v[130:131] op_sel_hi:[1,0,1]
	v_pk_fma_f32 v[64:65], v[64:65], v[192:193], v[128:129] op_sel_hi:[1,0,1]
	s_waitcnt vmcnt(8)
	v_pk_fma_f32 v[58:59], v[70:71], v[192:193], v[134:135] op_sel_hi:[1,0,1]
	v_pk_fma_f32 v[60:61], v[68:69], v[192:193], v[132:133] op_sel_hi:[1,0,1]
	v_max_f32_e32 v64, 0, v64
	v_max_f32_e32 v60, 0, v60
	v_max_f32_e32 v61, 0, v61
	v_max_f32_e32 v65, 0, v65
	v_max_f32_e32 v58, 0, v58
	v_max_f32_e32 v66, 0, v66
	v_max_f32_e32 v59, 0, v59
	v_max_f32_e32 v67, 0, v67
	v_pk_mul_f32 v[60:61], v[60:61], v[60:61]
	v_pk_mul_f32 v[64:65], v[64:65], v[64:65]
	v_pk_mul_f32 v[68:69], v[58:59], v[58:59]
	v_pk_mul_f32 v[66:67], v[66:67], v[66:67]
	v_pk_fma_f32 v[48:49], v[48:49], v[190:191], v[128:129] op_sel_hi:[1,0,1]
	v_cvt_pk_bf16_f32 v58, v60, v61
	v_cvt_pk_bf16_f32 v59, v68, v69
	v_cvt_pk_bf16_f32 v60, v64, v65
	v_cvt_pk_bf16_f32 v61, v66, v67
	v_pk_fma_f32 v[54:55], v[54:55], v[190:191], v[134:135] op_sel_hi:[1,0,1]
	v_pk_fma_f32 v[52:53], v[52:53], v[190:191], v[132:133] op_sel_hi:[1,0,1]
	v_pk_fma_f32 v[50:51], v[50:51], v[190:191], v[130:131] op_sel_hi:[1,0,1]
	v_max_f32_e32 v48, 0, v48
	v_max_f32_e32 v49, 0, v49
	global_store_dwordx4 v[120:121], v[58:61], off offset:256
	v_max_f32_e32 v52, 0, v52
	v_max_f32_e32 v53, 0, v53
	v_pk_mul_f32 v[58:59], v[48:49], v[48:49]
	v_max_f32_e32 v48, 0, v54
	v_max_f32_e32 v50, 0, v50
	v_max_f32_e32 v49, 0, v55
	v_max_f32_e32 v51, 0, v51
	v_lshl_add_u64 v[62:63], v[194:195], 0, s[4:5]
	v_pk_mul_f32 v[52:53], v[52:53], v[52:53]
	v_pk_mul_f32 v[54:55], v[48:49], v[48:49]
	v_pk_mul_f32 v[60:61], v[50:51], v[50:51]
	v_pk_fma_f32 v[40:41], v[40:41], v[188:189], v[128:129] op_sel_hi:[1,0,1]
	v_cvt_pk_bf16_f32 v48, v52, v53
	v_cvt_pk_bf16_f32 v49, v54, v55
	v_cvt_pk_bf16_f32 v50, v58, v59
	v_cvt_pk_bf16_f32 v51, v60, v61
	v_lshl_add_u64 v[52:53], v[62:63], 0, v[170:171]
	v_pk_fma_f32 v[46:47], v[46:47], v[188:189], v[134:135] op_sel_hi:[1,0,1]
	v_pk_fma_f32 v[44:45], v[44:45], v[188:189], v[132:133] op_sel_hi:[1,0,1]
	v_pk_fma_f32 v[42:43], v[42:43], v[188:189], v[130:131] op_sel_hi:[1,0,1]
	v_max_f32_e32 v40, 0, v40
	v_max_f32_e32 v41, 0, v41
	global_store_dwordx4 v[52:53], v[48:51], off
	v_max_f32_e32 v44, 0, v44
	v_max_f32_e32 v45, 0, v45
	v_pk_mul_f32 v[48:49], v[40:41], v[40:41]
	v_max_f32_e32 v40, 0, v46
	v_max_f32_e32 v42, 0, v42
	v_max_f32_e32 v41, 0, v47
	v_max_f32_e32 v43, 0, v43
	v_pk_mul_f32 v[44:45], v[44:45], v[44:45]
	v_pk_mul_f32 v[46:47], v[40:41], v[40:41]
	v_pk_mul_f32 v[50:51], v[42:43], v[42:43]
	v_pk_fma_f32 v[32:33], v[32:33], v[186:187], v[128:129] op_sel_hi:[1,0,1]
	v_cvt_pk_bf16_f32 v40, v44, v45
	v_cvt_pk_bf16_f32 v41, v46, v47
	v_cvt_pk_bf16_f32 v42, v48, v49
	v_cvt_pk_bf16_f32 v43, v50, v51
	v_lshl_add_u64 v[44:45], v[62:63], 0, v[172:173]
	v_pk_fma_f32 v[38:39], v[38:39], v[186:187], v[134:135] op_sel_hi:[1,0,1]
	v_pk_fma_f32 v[36:37], v[36:37], v[186:187], v[132:133] op_sel_hi:[1,0,1]
	v_pk_fma_f32 v[34:35], v[34:35], v[186:187], v[130:131] op_sel_hi:[1,0,1]
	v_max_f32_e32 v32, 0, v32
	v_max_f32_e32 v33, 0, v33
	global_store_dwordx4 v[44:45], v[40:43], off
	v_max_f32_e32 v36, 0, v36
	v_max_f32_e32 v37, 0, v37
	v_pk_mul_f32 v[40:41], v[32:33], v[32:33]
	v_max_f32_e32 v32, 0, v38
	v_max_f32_e32 v34, 0, v34
	v_max_f32_e32 v33, 0, v39
	v_max_f32_e32 v35, 0, v35
	v_pk_mul_f32 v[36:37], v[36:37], v[36:37]
	v_pk_mul_f32 v[38:39], v[32:33], v[32:33]
	v_pk_mul_f32 v[42:43], v[34:35], v[34:35]
	v_pk_fma_f32 v[24:25], v[24:25], v[184:185], v[128:129] op_sel_hi:[1,0,1]
	v_cvt_pk_bf16_f32 v32, v36, v37
	v_cvt_pk_bf16_f32 v33, v38, v39
	v_cvt_pk_bf16_f32 v34, v40, v41
; #define PG8_BAR __builtin_amdgcn_s_barrier()
; DI unsigned cvtpk(float lo, float hi) { f32x2 v = {lo, hi}; bf16x2_t b = __builtin_convertvector(v, bf16x2_t); return __builtin_bit_cast(unsigned, b); }
; template <class Epi, class Sched, bool ALIGN_EPI = false, bool SP2 = false>
; __device__ __forceinline__ void gemm_phase(PG8_LAS unsigned char* lds, const Gemm g, const Sched& S, const Epi& E, const int tid_in) {
;     ...
;         if (!has_next) break;
; #pragma unroll
;         for (int a = 0; a < 2; ++a)
; #pragma unroll
;             for (int b = 0; b < 2; ++b)
; #pragma unroll
;                 for (int m = 0; m < 4; ++m)
; #pragma unroll
;                     for (int n = 0; n < 2; ++n) acc[a][b][m][n] = (f32x4){0.f, 0.f, 0.f, 0.f};
;         cur = nxt; cA = nA; cB = nB; ++ui;
;         if constexpr (ALIGN_EPI) { if (wr == 1) PG8_BAR; }
;     DI void operator()(const f32x4 (&acc)[2][2][4][2], const pg8::Unit& u, int wr, int wc, int fr, int fq) const {
;     ...
; #pragma unroll
;         for (int bj = 0; bj < 2; ++bj) { const f32x4 b0 = bb[bj][0], b1 = bb[bj][1];
; #pragma unroll
;             for (int ai = 0; ai < 2; ++ai)
; #pragma unroll
;                 for (int m = 0; m < 4; ++m) {
;                     f32x4 v0 = acc[ai][bj][m][0] * rstd[ai][m] + b0, v1 = acc[ai][bj][m][1] * rstd[ai][m] + b1;
;                     if (ACT == 1) {
; #pragma unroll
;                         for (int e = 0; e < 4; ++e) { float a = fmaxf(v0[e], 0.f), b = fmaxf(v1[e], 0.f); v0[e] = a * a; v1[e] = b * b; } }
;                     u32x4 w; w.x = cvtpk(v0[0], v0[1]); w.y = cvtpk(v0[2], v0[3]); w.z = cvtpk(v1[0], v1[1]); w.w = cvtpk(v1[2], v1[3]);
;                     *(u32x4*)(Ou + (wr * 64 + fr + ai * 128 + m * 16) * ldc + wc * 32 + 8 * fq + bj * 128) = w; } }
	v_cvt_pk_bf16_f32 v35, v42, v43
	v_lshl_add_u64 v[36:37], v[62:63], 0, v[174:175]
	v_pk_fma_f32 v[30:31], v[30:31], v[184:185], v[134:135] op_sel_hi:[1,0,1]
	v_pk_fma_f32 v[28:29], v[28:29], v[184:185], v[132:133] op_sel_hi:[1,0,1]
	v_pk_fma_f32 v[26:27], v[26:27], v[184:185], v[130:131] op_sel_hi:[1,0,1]
	v_max_f32_e32 v24, 0, v24
	v_max_f32_e32 v25, 0, v25
	global_store_dwordx4 v[36:37], v[32:35], off
	v_max_f32_e32 v28, 0, v28
	v_max_f32_e32 v29, 0, v29
	v_pk_mul_f32 v[32:33], v[24:25], v[24:25]
	v_max_f32_e32 v24, 0, v30
	v_max_f32_e32 v26, 0, v26
	v_max_f32_e32 v25, 0, v31
	v_max_f32_e32 v27, 0, v27
	v_pk_mul_f32 v[28:29], v[28:29], v[28:29]
	v_pk_mul_f32 v[30:31], v[24:25], v[24:25]
	v_pk_mul_f32 v[34:35], v[26:27], v[26:27]
	v_pk_fma_f32 v[16:17], v[16:17], v[182:183], v[128:129] op_sel_hi:[1,0,1]
	v_cvt_pk_bf16_f32 v24, v28, v29
	v_cvt_pk_bf16_f32 v25, v30, v31
	v_cvt_pk_bf16_f32 v26, v32, v33
	v_cvt_pk_bf16_f32 v27, v34, v35
	v_pk_fma_f32 v[22:23], v[22:23], v[182:183], v[134:135] op_sel_hi:[1,0,1]
	v_pk_fma_f32 v[20:21], v[20:21], v[182:183], v[132:133] op_sel_hi:[1,0,1]
	v_pk_fma_f32 v[18:19], v[18:19], v[182:183], v[130:131] op_sel_hi:[1,0,1]
	v_max_f32_e32 v16, 0, v16
	v_max_f32_e32 v17, 0, v17
	global_store_dwordx4 v[88:89], v[24:27], off offset:256
	v_max_f32_e32 v20, 0, v20
	v_max_f32_e32 v21, 0, v21
	v_pk_mul_f32 v[24:25], v[16:17], v[16:17]
	v_max_f32_e32 v16, 0, v22
	v_max_f32_e32 v18, 0, v18
	v_max_f32_e32 v17, 0, v23
	v_max_f32_e32 v19, 0, v19
	v_pk_mul_f32 v[20:21], v[20:21], v[20:21]
	v_pk_mul_f32 v[22:23], v[16:17], v[16:17]
	v_pk_mul_f32 v[26:27], v[18:19], v[18:19]
	v_pk_fma_f32 v[8:9], v[8:9], v[180:181], v[128:129] op_sel_hi:[1,0,1]
	v_cvt_pk_bf16_f32 v16, v20, v21
	v_cvt_pk_bf16_f32 v17, v22, v23
	v_cvt_pk_bf16_f32 v18, v24, v25
	v_cvt_pk_bf16_f32 v19, v26, v27
	v_pk_fma_f32 v[14:15], v[14:15], v[180:181], v[134:135] op_sel_hi:[1,0,1]
	v_pk_fma_f32 v[12:13], v[12:13], v[180:181], v[132:133] op_sel_hi:[1,0,1]
	v_pk_fma_f32 v[10:11], v[10:11], v[180:181], v[130:131] op_sel_hi:[1,0,1]
	v_max_f32_e32 v8, 0, v8
	v_max_f32_e32 v9, 0, v9
	global_store_dwordx4 v[80:81], v[16:19], off offset:256
	v_max_f32_e32 v12, 0, v12
	v_max_f32_e32 v13, 0, v13
	v_pk_mul_f32 v[16:17], v[8:9], v[8:9]
	v_max_f32_e32 v8, 0, v14
	v_max_f32_e32 v10, 0, v10
	v_max_f32_e32 v9, 0, v15
	v_max_f32_e32 v11, 0, v11
	v_pk_mul_f32 v[12:13], v[12:13], v[12:13]
	v_pk_mul_f32 v[14:15], v[8:9], v[8:9]
	v_pk_mul_f32 v[18:19], v[10:11], v[10:11]
	v_pk_fma_f32 v[0:1], v[0:1], v[178:179], v[128:129] op_sel_hi:[1,0,1]
	v_cvt_pk_bf16_f32 v8, v12, v13
	v_cvt_pk_bf16_f32 v9, v14, v15
	v_cvt_pk_bf16_f32 v10, v16, v17
	v_cvt_pk_bf16_f32 v11, v18, v19
	v_pk_fma_f32 v[6:7], v[6:7], v[178:179], v[134:135] op_sel_hi:[1,0,1]
	v_pk_fma_f32 v[4:5], v[4:5], v[178:179], v[132:133] op_sel_hi:[1,0,1]
	v_pk_fma_f32 v[2:3], v[2:3], v[178:179], v[130:131] op_sel_hi:[1,0,1]
	v_max_f32_e32 v0, 0, v0
	v_max_f32_e32 v1, 0, v1
	global_store_dwordx4 v[72:73], v[8:11], off offset:256
	v_max_f32_e32 v4, 0, v4
	v_max_f32_e32 v5, 0, v5
	v_pk_mul_f32 v[8:9], v[0:1], v[0:1]
	v_max_f32_e32 v0, 0, v6
	v_max_f32_e32 v2, 0, v2
	v_max_f32_e32 v1, 0, v7
	v_max_f32_e32 v3, 0, v3
	v_pk_mul_f32 v[4:5], v[4:5], v[4:5]
	v_pk_mul_f32 v[6:7], v[0:1], v[0:1]
	v_pk_mul_f32 v[10:11], v[2:3], v[2:3]
	v_cvt_pk_bf16_f32 v0, v4, v5
	v_cvt_pk_bf16_f32 v1, v6, v7
	v_cvt_pk_bf16_f32 v2, v8, v9
	v_cvt_pk_bf16_f32 v3, v10, v11
	s_mov_b64 s[4:5], -1
	global_store_dwordx4 v[56:57], v[0:3], off offset:256
	s_cbranch_vccnz .LBB0_1702
	s_andn2_b64 vcc, exec, s[10:11]
	s_cbranch_vccnz .LBB0_1701
	s_barrier
	s_branch .LBB0_1701
